# remove waits: workspace pointer kept in two spare lanes of the SGPR-spill VGPR (v_readlane) instead of 20 LDS pointer-table re-reads + waits on the mixer items' address chains
# speedup vs baseline: 1.0027x; 1.0027x over previous
; #define PG8_LAS __attribute__((address_space(3)))
;     __device__ __forceinline__ unsigned long long ld(int i) const { const unsigned long long v = *(const volatile __attribute__((address_space(3))) unsigned long long*)(unsigned)(PTAB_OFF + 8 * i);
;         const unsigned lo = __builtin_amdgcn_readfirstlane((unsigned)v), hi = __builtin_amdgcn_readfirstlane((unsigned)(v >> 32)); return ((unsigned long long)hi << 32) | lo; }
;     __device__ __forceinline__ const float* in(int i) const { return (const float*)(const __attribute__((address_space(1))) float*)ld(i); }
; __global__ void __launch_bounds__(512, 2) fwd_kernel(KP kparg) {
;     ...
;     unsigned char* ws = kp.ws();
;     PG8_LAS unsigned char* ldsg = (PG8_LAS unsigned char*)lds;
;     bf16* H = (bf16*)(ws + WS_H); bf16* Pm = (bf16*)(ws + WS_P); bf16* MIX = (bf16*)(ws + WS_MIX); bf16* ACT = (bf16*)(ws + WS_ACT);
;     float* CTXB = (float*)(ws + WS_CTX);
;     const int G = gridDim.x, c = blockIdx.x;
;     (void)xcd_barrier_post((unsigned*)ws + 1024, (volatile LAS unsigned*)(lds + CTRL_OFF) + 8);
;     ...
;     prologue<0>(kp, lds, tid, lane, wave); __syncthreads();
;     ...
;     GRIDBAR();
; #pragma unroll 1
;     for (int l = 0; l < 2; ++l) {
;         const float* mod = (const float*)(ws + WS_MOD) + (size_t)l * 5 * 6144;
;         const float* xin = l ? kp.out() : kp.in(I_X); const float* cin = l ? CTXB : kp.in(I_CTX);
;         FRESH();
;     ...
;         if (l == 0) { prologue<1>(kp, lds, tid, lane, wave); }
;     ...
;         for (int rep = 0; rep < REP_NORM; ++rep)
;         norm_pass(xin, cin, H, kp.in(I_N1G) + l * D, mod, 0, 1024, MALL, lane, wave, l ? (const float*)(ws + WS_PART) : nullptr, CTXB);
;         GRIDBAR();
;         { pg8::Gemm g{H, (const bf16*)(ws + WS_WIN) + (size_t)l * INP * D, MALL, INP, D}; pg8::StaticOrder S; S.init(MALL, INP, G, c);
;           pg8::EpiBf16S E{Pm, INP};
;     ...
;           for (int rep = 0; rep < REP_GEMM; ++rep)
;           pg8::gemm_phase<pg8::EpiBf16S, pg8::StaticOrder, true, true>(ldsg, g, S, E);
;     ...
;         }
;         GRIDBAR();
;         FRESH();
;         v4u gz0 = {0u, 0u, 0u, 0u}, gz1 = gz0, gw0 = gz0, gw1 = gz0; { const int i0 = (G == 256) ? XITEM(c) : c; if (i0 < 1056) gla_prefetch(gz0, gz1, gw0, gw1, kp, l, i0, lane, wave); }
;         for (int it = c; it < 1056 + 528 + 255; it += G) { const int item = (G == 256) ? XITEM(it) : it; if (item >= 1056 + 528) break;
.LBB0_77:
	s_or_b64 exec, exec, s[0:1]
	s_add_u32 s90, s46, 0x3400000
	s_addc_u32 s91, s33, 0
	s_add_u32 s92, s46, 0x7800000
	s_addc_u32 s93, s33, 0
	s_add_u32 s81, s46, 0x10e00000
	s_addc_u32 s85, s33, 0
	s_add_u32 s14, s46, 0x12c00000
	s_addc_u32 s15, s33, 0
	s_add_u32 s94, s46, 0x3000000
	s_addc_u32 s95, s33, 0
	s_add_u32 s0, s46, 0x100000
	v_writelane_b32 v253, s0, 3
	s_addc_u32 s0, s33, 0
	v_writelane_b32 v253, s0, 4
	s_lshl_b32 s0, s73, 3
	s_lshl_b32 s52, s84, 3
	s_add_u32 s50, s46, 0x1e400000
	s_addc_u32 s51, s33, 0
	v_writelane_b32 v253, s0, 5
	s_add_u32 s0, s46, 0x200000
	v_writelane_b32 v253, s0, 6
	s_addc_u32 s0, s33, 0
	s_cmpk_lt_i32 s73, 0x4a4
	v_writelane_b32 v253, s0, 7
	s_cselect_b64 s[0:1], -1, 0
	v_writelane_b32 v253, s0, 8
	s_ashr_i32 s86, s73, 31
	s_ashr_i32 s2, s73, 3
	v_writelane_b32 v253, s1, 9
	s_lshr_b32 s0, s86, 29
	s_add_i32 s0, s73, s0
	s_ashr_i32 s13, s0, 3
	s_and_b32 s0, s0, -8
	s_sub_i32 s16, s73, s0
	s_mul_i32 s0, s16, 0x94
	s_lshl_b32 s1, s73, 5
	s_add_i32 s6, s0, 4
	s_and_b32 s0, s73, 0xffffff00
	v_writelane_b32 v253, s1, 10
	s_and_b32 s1, s1, 0xe0
	s_add_i32 s0, s2, s0
	s_add_i32 s54, s1, s2
	s_ashr_i32 s89, s84, 31
	s_add_i32 s3, s0, s1
	s_sub_i32 s2, s54, 32
	s_cmp_lt_i32 s73, 16
	s_cselect_b32 s4, s73, -1
	s_cmpk_eq_i32 s84, 0x100
	s_cselect_b64 s[56:57], -1, 0
	s_and_b64 s[0:1], s[56:57], exec
	s_cselect_b32 s1, s3, s73
	s_cselect_b32 s0, s2, s4
	s_cmpk_lt_i32 s1, 0x420
	s_cselect_b64 s[2:3], -1, 0
	v_writelane_b32 v253, s2, 11
	s_mov_b32 s79, 0
	v_writelane_b32 v254, s16, 0
	v_writelane_b32 v253, s3, 12
	v_writelane_b32 v253, s1, 13
	s_lshl_b32 s1, s1, 1
	s_cmpk_lt_i32 s73, 0x72f
	v_writelane_b32 v253, s1, 14
	s_cselect_b64 s[2:3], -1, 0
	v_writelane_b32 v253, s2, 15
	s_add_i32 s1, s54, 0x100
	s_cmpk_lt_i32 s73, 0x200
	v_writelane_b32 v253, s3, 16
	v_writelane_b32 v253, s1, 17
	s_cselect_b64 s[2:3], -1, 0
	v_writelane_b32 v253, s2, 18
	s_cmp_lt_u32 s0, 16
	v_mov_b32_e32 v35, 0
	v_writelane_b32 v253, s3, 19
	s_cselect_b64 s[2:3], -1, 0
	v_writelane_b32 v253, s2, 20
	s_lshl_b32 s1, s0, 6
	v_mov_b32_e32 v217, 0x264b0
	v_writelane_b32 v253, s3, 21
	s_and_b32 s2, s1, 0x300
	s_and_b32 s1, s1, 0x380
	s_bitset1_b32 s1, 15
	v_writelane_b32 v253, s1, 22
	s_and_b32 s1, s0, 1
	s_lshl_b32 s0, s1, 6
	s_or_b32 s3, s2, 0x8000
	s_or_b32 s2, s2, 0x8080
	v_writelane_b32 v253, s3, 23
	s_add_u32 s3, s46, 0xb00000
	s_addc_u32 s4, s33, 0
	s_lshl_b32 s7, s16, 6
	s_cmp_lt_i32 s73, 64
	v_writelane_b32 v253, s2, 24
	s_cselect_b64 s[8:9], -1, 0
	s_and_b32 s18, s73, 3
	v_writelane_b32 v253, s8, 25
	s_lshl_b32 s2, s18, 9
	v_mov_b32_e32 v204, 0x264b8
	ds_read_b64 v[160:161], v204
	s_waitcnt lgkmcnt(0)
	v_readfirstlane_b32 s100, v160
	v_readfirstlane_b32 s101, v161
	s_nop 3
	v_writelane_b32 v255, s100, 62
	v_writelane_b32 v255, s101, 63
	v_writelane_b32 v253, s9, 26
	s_add_u32 s8, s46, s2
	s_addc_u32 s9, s33, 0
	s_add_u32 s10, s3, s2
	v_writelane_b32 v253, s3, 27
	s_addc_u32 s11, s4, 0
	s_ashr_i32 s2, s73, 4
	s_bfe_u32 s12, s73, 0x20002
	s_lshl_b32 s3, s18, 22
	v_writelane_b32 v253, s4, 28
	s_add_u32 s4, s50, s3
	s_addc_u32 s5, s51, 0
	v_writelane_b32 v253, s4, 29
	s_ashr_i32 s3, s2, 31
	v_mov_b32_e32 v205, 0x358637bd
	v_writelane_b32 v253, s5, 30
	s_lshl_b64 s[4:5], s[2:3], 19
	s_lshl_b32 s3, s12, 19
	s_add_u32 s60, s10, s3
	s_addc_u32 s61, s11, 0
	s_add_u32 s10, s60, 0x40000
	s_addc_u32 s11, s61, 0
	s_add_u32 s3, s8, s4
	s_addc_u32 s4, s9, s5
	s_add_u32 s62, s3, 0x14e00000
	s_addc_u32 s63, s4, 0
	s_add_u32 s64, s3, 0x14e40000
	s_addc_u32 s65, s4, 0
	v_writelane_b32 v253, s10, 31
	s_add_u32 s4, s60, 0x40080
	s_addc_u32 s5, s61, 0
	v_writelane_b32 v253, s11, 32
	v_writelane_b32 v253, s4, 33
	s_lshl_b32 s3, s12, 8
	s_mul_i32 s12, s12, 0x160000
	v_writelane_b32 v253, s5, 34
	s_lshl_b32 s4, s2, 8
	v_writelane_b32 v253, s3, 35
	s_or_b32 s3, s4, 16
	v_writelane_b32 v253, s3, 36
	s_or_b32 s5, s4, 32
	v_writelane_b32 v253, s5, 37
	s_or_b32 s5, s4, 48
	v_writelane_b32 v253, s5, 38
	s_or_b32 s5, s4, 0x80
	v_writelane_b32 v253, s5, 39
	s_or_b32 s5, s4, 0x90
	v_writelane_b32 v253, s5, 40
	s_or_b32 s5, s4, 0xa0
	v_writelane_b32 v253, s5, 41
	v_writelane_b32 v253, s4, 42
	s_or_b32 s4, s4, 0xb0
	v_writelane_b32 v253, s4, 43
	s_add_u32 s4, s46, 0xf00000
	v_writelane_b32 v253, s4, 44
	s_addc_u32 s4, s33, 0
	v_writelane_b32 v253, s4, 45
	s_add_u32 s5, s46, 0x2500000
	s_mov_b32 s4, s18
	s_addc_u32 s8, s33, 0
	v_writelane_b32 v253, s4, 46
	s_cmp_eq_u32 s18, 2
	s_mul_hi_i32 s3, s2, 0x160000
	v_writelane_b32 v253, s5, 47
	s_movk_i32 s4, 0x600
	s_cselect_b32 s4, s4, 0x880
	v_writelane_b32 v253, s4, 48
	s_mul_i32 s2, s2, 0x160000
	v_mov_b32_e32 v206, 0x260
	v_writelane_b32 v253, s5, 49
	s_lshl_b32 s4, s73, 6
	s_and_b32 s4, s4, 0x80
	s_sub_i32 s4, 0x300, s4
	s_lshr_b32 s49, s4, 6
	v_writelane_b32 v253, s5, 50
	s_add_u32 s4, s5, s12
	v_writelane_b32 v253, s4, 51
	s_addc_u32 s4, s8, 0
	v_writelane_b32 v253, s8, 52
	s_add_u32 s8, s46, s2
	s_addc_u32 s9, s33, s3
	v_writelane_b32 v253, s4, 53
	s_add_u32 s2, s8, 0x1dc00000
	v_writelane_b32 v253, s2, 54
	s_addc_u32 s2, s9, 0
	s_add_i32 s55, s49, -2
	v_writelane_b32 v253, s2, 55
	s_cmp_lt_i32 s16, 4
	s_mul_i32 s2, s16, 0x95
	s_cselect_b32 s2, s2, s6
	s_add_i32 s2, s2, s13
	s_mul_hi_i32 s3, s2, 0x38e38e39
	s_lshr_b32 s4, s3, 31
	s_ashr_i32 s3, s3, 4
	s_add_i32 s3, s3, s4
	s_mul_i32 s4, s3, 0x48
	s_lshl_b32 s5, s3, 3
	s_sub_i32 s4, s2, s4
	s_sub_i32 s2, 0x84, s5
	s_min_u32 s6, s2, 8
	s_cmp_lt_i32 s16, 0
	s_mul_i32 s2, s16, 0x41
	s_cselect_b32 s2, s2, s7
	s_add_i32 s2, s2, s13
	s_ashr_i32 s3, s2, 31
	s_lshr_b32 s3, s3, 27
	s_add_i32 s3, s2, s3
	s_and_b32 s7, s3, 0xffe0
	s_sub_i32 s2, s2, s7
	s_bfe_i32 s7, s2, 0x80000
	s_bfe_u32 s7, s7, 0x3000c
	s_add_i32 s7, s2, s7
	s_and_b32 s10, s7, 0xf8
	s_sub_i32 s2, s2, s10
	s_ashr_i32 s3, s3, 5
	s_bfe_i32 s7, s7, 0x80000
	s_lshl_b32 s3, s3, 3
	s_sext_i32_i16 s7, s7
	s_sext_i32_i8 s2, s2
	v_writelane_b32 v253, s13, 56
	s_add_i32 s12, s3, s2
	s_ashr_i32 s2, s7, 3
	v_writelane_b32 v253, s2, 57
	s_lshr_b32 s2, s7, 3
	s_bfe_i64 s[2:3], s[2:3], 0x100000
	s_lshl_b64 s[2:3], s[2:3], 19
	s_ashr_i32 s13, s12, 31
	v_writelane_b32 v253, s2, 58
	v_cvt_f32_ubyte0_e32 v2, s6
	s_waitcnt lgkmcnt(0)
; #define FRESH() do { tid = threadIdx.x; asm volatile("" : "+v"(tid)); lane = tid & 63; wave = __builtin_amdgcn_readfirstlane(tid >> 6); } while (0)
; #define GRIDBAR() do { XcdBarrier b_; b_.bar = (unsigned*)kp.ws() + 1024; b_.x = xb_xcc_id(); b_.st = (volatile LAS unsigned*)(lds + CTRL_OFF) + 8; xcd_barrier(b_); } while (0)
; __global__ void __launch_bounds__(512, 2) fwd_kernel(KP kparg) {
;     ...
;         FRESH();
;         v4u gz0 = {0u, 0u, 0u, 0u}, gz1 = gz0, gw0 = gz0, gw1 = gz0; { const int i0 = (G == 256) ? XITEM(c) : c; if (i0 < 1056) gla_prefetch(gz0, gz1, gw0, gw1, kp, l, i0, lane, wave); }
;         for (int it = c; it < 1056 + 528 + 255; it += G) { const int item = (G == 256) ? XITEM(it) : it; if (item >= 1056 + 528) break;
;     ...
;             if (item < 1056) { const int nx = (G == 256) ? XITEM(it + G) : it + G; gla_pair<false>(kp, l, item, lds, tid, lane, wave, gz0, gz1, gw0, gw1, nx < 1056 ? nx : -1); __syncthreads(); }
;     ...
;             if (item >= 1056) prep_pool_item(kp, l, item - 1056, lds, tid, lane, wave);
;     ...
;             __syncthreads();
;         }
;         GRIDBAR();
;         FRESH();
;         gla_scan(kp, tid);
;         {
;     ...
;           for (int rep = 0; rep < REP_SWA; ++rep)
;           for (int it = c; it < 512; it += G) { const int item = (G == 256) ? XITEM(it) : it; swa_item(kp, l, item, lds, tid, lane, wave); __syncthreads(); }
;     ...
;         }
;         GRIDBAR();
;         FRESH();
;         { const int ngl = l ? 1024 : 1056;
;     ...
;           v4u gz0 = {0u, 0u, 0u, 0u}, gz1 = gz0, gw0 = gz0, gw1 = gz0; { const int i0 = (G == 256) ? XITEM(c) : c; if (i0 < ngl) gla_prefetch(gz0, gz1, gw0, gw1, kp, l, i0, lane, wave); }
;           for (int it = c; it < ngl + 255; it += G) { const int item = (G == 256) ? XITEM(it) : it; if (item >= ngl) break;
;               const int nx = (G == 256) ? XITEM(it + G) : it + G; gla_pair<true>(kp, l, item, lds, tid, lane, wave, gz0, gz1, gw0, gw1, nx < ngl ? nx : -1); __syncthreads(); }
	v_cvt_f32_i32_e32 v1, s4
	v_writelane_b32 v253, s3, 59
	s_lshl_b64 s[2:3], s[12:13], 19
	s_add_u32 s2, s81, s2
	s_addc_u32 s3, s85, s3
	s_add_u32 s10, s2, 0x40000
	v_writelane_b32 v253, s2, 60
	s_addc_u32 s11, s3, 0
	v_rcp_iflag_f32_e32 v3, v2
	v_writelane_b32 v253, s3, 61
	v_writelane_b32 v253, s10, 62
	s_lshr_b32 s2, s16, 31
	v_writelane_b32 v254, s2, 1
	v_writelane_b32 v253, s11, 63
	s_mov_b32 s10, s12
	v_writelane_b32 v254, s10, 2
	s_mul_i32 s3, s12, 0x160000
	s_mul_hi_i32 s2, s12, 0x160000
	v_writelane_b32 v254, s11, 3
	s_add_u32 s10, s14, s3
	v_writelane_b32 v254, s14, 4
	s_addc_u32 s11, s15, s2
	s_add_u32 s2, s10, 0xb0000
	v_writelane_b32 v254, s15, 5
	v_writelane_b32 v254, s10, 6
	s_addc_u32 s3, s11, 0
	v_mul_f32_e32 v3, v1, v3
	v_writelane_b32 v254, s11, 7
	v_writelane_b32 v254, s2, 8
	v_trunc_f32_e32 v3, v3
	v_fma_f32 v1, -v3, v2, v1
	v_writelane_b32 v254, s3, 9
	s_ashr_i32 s2, s4, 30
	s_or_b32 s7, s2, 1
	v_cmp_ge_f32_e64 s[2:3], |v1|, v2
	v_cvt_i32_f32_e32 v1, v3
	s_and_b64 s[2:3], s[2:3], exec
	s_cselect_b32 s2, s7, 0
	v_mbcnt_lo_u32_b32 v2, -1, 0
	v_readfirstlane_b32 s3, v1
	s_add_i32 s2, s3, s2
	s_mul_i32 s3, s2, s6
	s_sub_i32 s3, s4, s3
	s_sext_i32_i8 s3, s3
	s_add_i32 s6, s5, s3
	s_bfe_i64 s[4:5], s[2:3], 0x80000
	s_lshl_b64 s[4:5], s[4:5], 19
	v_writelane_b32 v254, s4, 10
	s_ashr_i32 s7, s6, 31
	s_sext_i32_i8 s2, s2
	v_writelane_b32 v254, s5, 11
	s_mov_b32 s4, s6
	v_writelane_b32 v254, s4, 12
	v_mov_b32_e32 v214, 1
	v_mov_b32_e32 v207, 0x26440
	v_writelane_b32 v254, s5, 13
	s_lshl_b64 s[4:5], s[6:7], 19
	s_add_u32 s4, s90, s4
	v_writelane_b32 v254, s2, 14
	s_mul_i32 s2, s1, 3
	s_mulk_i32 s1, 0xc0
	s_addc_u32 s5, s91, s5
	v_writelane_b32 v254, s1, 15
	s_add_u32 s6, s4, 0x40000
	v_writelane_b32 v254, s4, 16
	s_addc_u32 s7, s5, 0
	s_ashr_i32 s53, s52, 31
	v_writelane_b32 v254, s5, 17
	v_writelane_b32 v254, s6, 18
	s_lshl_b32 s59, s84, 5
	s_lshl_b64 s[66:67], s[52:53], 11
	v_writelane_b32 v254, s7, 19
	s_add_u32 s1, s8, 0x1dcb0080
	v_writelane_b32 v254, s1, 20
	s_addc_u32 s1, s9, 0
	v_writelane_b32 v254, s1, 21
	s_lshl_b32 s1, s2, 2
	v_writelane_b32 v254, s1, 22
	s_lshl_b32 s0, s0, 1
	v_writelane_b32 v254, s0, 23
	s_add_i32 s0, 0, 0x26020
	v_writelane_b32 v254, s0, 24
	s_add_i32 s0, 0, 0x26024
	v_writelane_b32 v254, s0, 25
	s_add_i32 s0, 0, 0x22000
	v_writelane_b32 v254, s0, 26
	s_mov_b32 s0, s79
	v_writelane_b32 v254, s0, 27
	v_mov_b32_e32 v252, 0x26448
	v_mov_b32_e32 v215, 0x26468
	v_writelane_b32 v254, s1, 28
	v_writelane_b32 v254, s73, 29
	v_writelane_b32 v254, s76, 30
	s_mov_b32 s0, s80
	v_mov_b32_e32 v70, v35
	v_writelane_b32 v254, s77, 31
	v_writelane_b32 v254, s84, 32
	v_writelane_b32 v254, s0, 33
	v_mov_b32_e32 v71, v35
	v_mov_b32_e32 v72, v35
	v_writelane_b32 v254, s1, 34
	v_writelane_b32 v254, s90, 35
	v_mov_b32_e32 v73, v35
	v_mbcnt_hi_u32_b32 v216, -1, v2
	v_writelane_b32 v254, s91, 36
	v_writelane_b32 v254, s92, 37
	v_mov_b32_e32 v222, 0x41b17218
	v_mov_b32_e32 v223, 0x3fb8aa3b
	v_writelane_b32 v254, s93, 38
	v_writelane_b32 v254, s81, 39
	v_writelane_b32 v254, s85, 40
	v_writelane_b32 v254, s94, 41
	v_mov_b32_e32 v224, 0xf149f2ca
	v_mov_b64_e32 v[0:1], 0x200
	v_writelane_b32 v254, s95, 42
	v_writelane_b32 v254, s52, 43
	s_mov_b32 s68, 0x8080
	s_movk_i32 s69, 0xc0
	v_writelane_b32 v254, s53, 44
	v_writelane_b32 v254, s86, 45
	v_writelane_b32 v254, s89, 46
	v_writelane_b32 v254, s54, 47
	v_writelane_b32 v254, s56, 48
	s_movk_i32 s96, 0x2000
	s_movk_i32 s87, 0x3000
	v_writelane_b32 v254, s57, 49
	v_writelane_b32 v254, s59, 50
	v_writelane_b32 v254, s66, 51
	s_mov_b32 s88, 0xf800000
	s_movk_i32 s33, 0x1200
	v_writelane_b32 v254, s67, 52
	v_writelane_b32 v254, s50, 53
	s_mov_b32 s58, 0xf149f2ca
	s_mov_b64 s[14:15], 0
	v_writelane_b32 v254, s51, 54
	v_writelane_b32 v254, s60, 55
	s_mov_b64 s[46:47], -1
	s_mov_b64 s[70:71], 0x80
	v_writelane_b32 v254, s61, 56
	v_writelane_b32 v254, s62, 57
	s_barrier
	s_nop 0
	v_writelane_b32 v254, s63, 58
	v_writelane_b32 v254, s64, 59
	s_nop 1
	v_writelane_b32 v254, s65, 60
	v_writelane_b32 v254, s49, 61
	v_writelane_b32 v254, s55, 62
	s_branch .LBB0_80

;     __device__ __forceinline__ const float* in(int i) const { return (const float*)(const __attribute__((address_space(1))) float*)ld(i); }
;     __device__ __forceinline__ unsigned char* ws() const { return (unsigned char*)(__attribute__((address_space(1))) unsigned char*)ld(23); }
; __device__ __forceinline__ void gla_prefetch(v4u& pz0, v4u& pz1, v4u& pw0, v4u& pw1, const KPD& kp, int l, int pair, int lane, int wave) {
;     const int half = wave >> 2, w4 = wave & 3, item = 2 * pair + half, h = item & 3, sc = item >> 2; int b, n, rowbase; chunk_coords(sc, b, n, rowbase);
;     const int dir = w4 >> 1, d0 = 24 * (w4 & 1);
;     const bf16* prow = (const bf16*)(kp.ws() + WS_P) + (size_t)(rowbase + lane) * INP;
;     pz0 = *(const v4u*)(prow + (dir ? C_ZB : C_ZF)); pz1 = *(const v4u*)(prow + (dir ? C_ZB : C_ZF) + 8);
;     const float* W = kp.in(I_GWDEC) + (size_t)((l * 2 + dir) * 16) * 192 + h * 48 + d0;
;     const float* bias = kp.in(I_GBDEC) + (l * 2 + dir) * 192 + h * 48 + d0;
;     unsigned w[6];
; #pragma unroll
;     for (int i = 0; i < 6; ++i) { const int e = lane + 64 * i; w[i] = __float_as_uint(W[(e / 24) * 192 + (e % 24)]); }
;     pw0 = (v4u){w[0], w[1], w[2], w[3]}; pw1 = (v4u){w[4], w[5], __float_as_uint(bias[lane < 24 ? lane : 0]), 0u};
.LBB0_251:
	s_lshl_b32 s0, s4, 6
	s_and_b32 s1, s3, 3
	s_add_i32 s3, s5, s0
	s_lshr_b32 s0, s12, 1
	ds_read_b64 v[6:7], v207
	s_and_b32 s4, s0, 1
	s_and_b32 s6, 64, s2
	s_cmp_eq_u32 s4, 0
	s_movk_i32 s0, 0x920
	v_readlane_b32 s10, v254, 27
	s_cselect_b32 s0, 0x900, s0
	s_lshl_b32 s5, s10, 1
	s_or_b32 s9, s4, s5
	s_mul_i32 s78, s9, 0xc00
	s_waitcnt lgkmcnt(0)
	v_readfirstlane_b32 s8, v6
	s_lshl_b64 s[4:5], s[78:79], 2
	v_readfirstlane_b32 s7, v7
	s_add_u32 s4, s8, s4
	s_addc_u32 s5, s7, s5
	s_mul_i32 s7, s1, 0xc0
	s_add_u32 s8, s4, s7
	v_readlane_b32 s1, v255, 63
	v_readlane_b32 s4, v255, 62
	v_or_b32_e32 v2, s3, v120
	v_mov_b32_e32 v5, s1
	v_mov_b32_e32 v4, s4
	s_addc_u32 s10, s5, 0
	v_mad_i64_i32 v[4:5], s[4:5], v2, s33, v[4:5]
	s_mov_b32 s1, s79
	v_lshl_add_u64 v[4:5], v[4:5], 0, s[0:1]
	s_mov_b64 s[0:1], 0x7800000
	v_lshl_add_u64 v[6:7], v[4:5], 0, s[0:1]
	s_mov_b32 s0, 0x7800000
	v_add_co_u32_e32 v4, vcc, s0, v4
	s_cmp_lg_u32 s6, 0
	s_nop 0
	v_addc_co_u32_e32 v5, vcc, 0, v5, vcc
	global_load_dwordx4 v[18:21], v[4:5], off
	global_load_dwordx4 v[22:25], v[6:7], off offset:16
	ds_read_b64 v[4:5], v252
	v_mul_lo_u16_e32 v2, 43, v120
	v_or_b32_e32 v6, 64, v120
	v_or_b32_e32 v7, 0x80, v120
	v_or_b32_e32 v8, 0xc0, v120
	s_cselect_b32 s3, 0x60, 0
	v_lshrrev_b16_e32 v2, 10, v2
	v_mul_lo_u16_e32 v6, 43, v6
	v_mul_lo_u16_e32 v7, 0xab, v7
	v_mul_lo_u16_e32 v8, 0xab, v8
	v_or_b32_e32 v9, 0x100, v120
	v_or_b32_e32 v10, 0x140, v120
	s_add_u32 s0, s8, s3
	v_mul_u32_u24_e32 v2, 0xa8, v2
	v_lshrrev_b16_e32 v6, 10, v6
	v_lshrrev_b16_e32 v7, 12, v7
	v_lshrrev_b16_e32 v8, 12, v8
	v_mul_u32_u24_e32 v9, 0xaab, v9
	s_movk_i32 s4, 0xa8
	v_mul_u32_u24_e32 v10, 0xaab, v10
	s_addc_u32 s1, s10, 0
	v_add_lshl_u32 v2, v2, v120, 2
	v_mul_u32_u24_e32 v6, 0xa8, v6
	v_mul_u32_u24_e32 v7, 0xa8, v7
	v_mul_u32_u24_e32 v8, 0xa8, v8
	v_mul_lo_u16_sdwa v9, v9, s4 dst_sel:DWORD dst_unused:UNUSED_PAD src0_sel:WORD_1 src1_sel:DWORD
	v_mul_lo_u16_sdwa v10, v10, s4 dst_sel:DWORD dst_unused:UNUSED_PAD src0_sel:WORD_1 src1_sel:DWORD
	s_mul_i32 s78, s9, 0xc0
	v_add_lshl_u32 v6, v6, v120, 2
	v_add_lshl_u32 v7, v7, v120, 2
	v_add_lshl_u32 v8, v8, v120, 2
	v_add_lshl_u32 v9, v120, v9, 2
	v_add_lshl_u32 v10, v120, v10, 2
	global_load_dword v26, v2, s[0:1]
	global_load_dword v27, v6, s[0:1] offset:256
	global_load_dword v28, v7, s[0:1] offset:512
	global_load_dword v29, v8, s[0:1] offset:768
	global_load_dword v30, v9, s[0:1] offset:1024
	global_load_dword v31, v10, s[0:1] offset:1280
	s_waitcnt lgkmcnt(0)
	v_readfirstlane_b32 s5, v4
	s_lshl_b64 s[0:1], s[78:79], 2
	v_readfirstlane_b32 s4, v5
	s_add_u32 s0, s5, s0
	s_addc_u32 s1, s4, s1
	s_add_u32 s0, s0, s7
	s_addc_u32 s1, s1, 0
	v_cmp_gt_u32_e32 vcc, 24, v120
	s_add_u32 s0, s0, s3
	s_addc_u32 s1, s1, 0
	v_cndmask_b32_e32 v2, 0, v120, vcc
	v_lshlrev_b32_e32 v2, 2, v2
	global_load_dword v32, v2, s[0:1]
	v_readlane_b32 s11, v254, 28
	s_branch .LBB0_253

; __device__ __forceinline__ float lo16(unsigned w) { return __uint_as_float(w << 16); }
; template <bool PHC>
; __device__ __forceinline__ void gla_pair(const KPD& kp, int l, int pair, unsigned char* lds, int tid, int lane, int wave, v4u& pz0, v4u& pz1, v4u& pw0, v4u& pw1, int next_pair) {
;     const int half = wave >> 2, w4 = wave & 3, t4 = tid & 255;
;     const int item = 2 * pair + half;
;     const int h = item & 3, sc = item >> 2; int b, n, rowbase; chunk_coords(sc, b, n, rowbase);
;     unsigned char* L = lds + half * 69632;
;     const bf16* P = (const bf16*)(kp.ws() + WS_P);
;     float* ST = (float*)(kp.ws() + WS_ST); float* DEC = (float*)(kp.ws() + WS_DEC);
;     const int dir = w4 >> 1, d0 = 24 * (w4 & 1);
;     const bf16* prow = P + (size_t)(rowbase + lane) * INP;
;     v4u vpre[3];
; #pragma unroll
;     for (int i = 0; i < 3; ++i) { const int idx = t4 + 256 * i; vpre[i] = *(const v4u*)(P + (size_t)(rowbase + idx / 12) * INP + C_GV + h * 96 + 8 * (idx % 12)); }
;     v2u spre[9];
;     if constexpr (PHC) { const bf16* SI = (const bf16*)(kp.ws() + WS_SI);
; #pragma unroll
;         for (int i = 0; i < 9; ++i) { const int idx = t4 + 256 * i; const int dd = idx / 1152, e = (idx % 1152) * 4;
;             spre[i] = *(const v2u*)(SI + ((size_t)((dd * 4 + b) * NCH + n) * 4 + h) * 4608 + e); }
;     }
;     float z[16];
;     { const v4u z0 = pz0, z1 = pz1;
;       z[0] = lo16(z0.x); z[1] = hi16(z0.x); z[2] = lo16(z0.y); z[3] = hi16(z0.y); z[4] = lo16(z0.z); z[5] = hi16(z0.z); z[6] = lo16(z0.w); z[7] = hi16(z0.w);
;       z[8] = lo16(z1.x); z[9] = hi16(z1.x); z[10] = lo16(z1.y); z[11] = hi16(z1.y); z[12] = lo16(z1.z); z[13] = hi16(z1.z); z[14] = lo16(z1.w); z[15] = hi16(z1.w); }
;     v4u qraw[3], kraw[3];
; #pragma unroll
;     for (int i = 0; i < 3; ++i) { qraw[i] = *((const v4u*)(prow + C_GQ + h * 48 + d0) + i); kraw[i] = *((const v4u*)(prow + C_GK + h * 48 + d0) + i); }
;     const int wvv[6] = {(int)pw0.x, (int)pw0.y, (int)pw0.z, (int)pw0.w, (int)pw1.x, (int)pw1.y};
;     const int bvv = (int)pw1.z;
;     float bc[24], tot[24];
; #pragma unroll
;     for (int c = 0; c < 24; ++c) {
;         float pre = __int_as_float(__builtin_amdgcn_readlane(bvv, c));
; #pragma unroll
;         for (int r = 0; r < 16; ++r) pre += z[r] * __int_as_float(__builtin_amdgcn_readlane(wvv[(24 * r + c) >> 6], (24 * r + c) & 63));
.LBB0_264:
	v_readfirstlane_b32 vcc_lo, v225
	s_lshl_b32 vcc_hi, s10, 2
	s_lshr_b32 vcc_lo, vcc_lo, 6
	s_and_b32 vcc_lo, vcc_lo, 3
	s_add_i32 vcc_lo, vcc_lo, vcc_hi
	s_mul_i32 vcc_lo, vcc_lo, 0x1800
	s_waitcnt lgkmcnt(0)
	v_readlane_b32 s100, v255, 62
	v_readlane_b32 s101, v255, 63
	v_mbcnt_lo_u32_b32 v250, -1, 0
	v_mbcnt_hi_u32_b32 v250, -1, v250
	s_add_u32 s100, s100, 0x3400000
	s_addc_u32 s101, s101, 0
	s_add_u32 s100, s100, vcc_lo
	s_addc_u32 s101, s101, 0
	v_lshlrev_b32_e32 v250, 2, v250
	v_add_u32_e32 v251, 0x1000, v250
	s_lshl_b32 s2, s12, 6
	s_and_b32 s46, s10, 3
	s_add_i32 s10, s11, s2
	v_add_u32_e32 v16, s10, v120
	s_waitcnt lgkmcnt(0)
	v_readlane_b32 s3, v255, 63
	v_readlane_b32 s2, v255, 62
	s_add_u32 s2, s2, 0x7800000
	s_addc_u32 s3, s3, 0
	v_mov_b64_e32 v[14:15], s[2:3]
	v_add_u32_e32 v6, s10, v37
	s_waitcnt lgkmcnt(0)
	v_readlane_b32 s47, v255, 63
	v_readlane_b32 s48, v255, 62
	v_add_u32_e32 v10, s10, v121
	v_mad_i64_i32 v[6:7], s[2:3], v6, s33, v[14:15]
	v_mad_i64_i32 v[10:11], s[2:3], v10, s33, v[14:15]
	s_waitcnt lgkmcnt(0)
	v_readlane_b32 s50, v255, 62
	v_add_u32_e32 v2, s10, v33
	v_readlane_b32 s49, v255, 63
	v_mad_i64_i32 v[2:3], s[2:3], v2, s33, v[14:15]
	v_mad_i64_i32 v[14:15], s[2:3], v16, s33, v[14:15]
	s_waitcnt vmcnt(0)
	v_mbcnt_lo_u32_b32 v211, -1, 0
	v_mbcnt_hi_u32_b32 v211, -1, v211
	v_lshrrev_b32_e32 v212, 5, v211
	v_and_b32_e32 v210, 31, v211
	v_mad_u32_u24 v210, v212, 24, v210
	v_add_u32_e32 v212, 0, v210
	v_and_b32_e32 v212, 63, v212
	v_lshlrev_b32_e32 v212, 2, v212
	ds_bpermute_b32 v197, v212, v26
	v_add_u32_e32 v212, 48, v210
	v_mov_b32_e32 v189, v212
	v_and_b32_e32 v212, 63, v212
	v_lshlrev_b32_e32 v212, 2, v212
	ds_bpermute_b32 v198, v212, v26
	ds_bpermute_b32 v177, v212, v27
	v_add_u32_e32 v212, 96, v210
	v_mov_b32_e32 v190, v212
	v_and_b32_e32 v212, 63, v212
	v_lshlrev_b32_e32 v212, 2, v212
	ds_bpermute_b32 v199, v212, v27
	ds_bpermute_b32 v178, v212, v28
	v_add_u32_e32 v212, 144, v210
	v_and_b32_e32 v212, 63, v212
	v_lshlrev_b32_e32 v212, 2, v212
	ds_bpermute_b32 v200, v212, v28
	v_add_u32_e32 v212, 192, v210
	v_and_b32_e32 v212, 63, v212
	v_lshlrev_b32_e32 v212, 2, v212
	ds_bpermute_b32 v201, v212, v29
	v_add_u32_e32 v212, 240, v210
	v_mov_b32_e32 v193, v212
	v_and_b32_e32 v212, 63, v212
	v_lshlrev_b32_e32 v212, 2, v212
	ds_bpermute_b32 v202, v212, v29
	ds_bpermute_b32 v181, v212, v30
	v_add_u32_e32 v212, 288, v210
	v_mov_b32_e32 v194, v212
	v_and_b32_e32 v212, 63, v212
	v_lshlrev_b32_e32 v212, 2, v212
	ds_bpermute_b32 v203, v212, v30
	ds_bpermute_b32 v186, v212, v31
	v_add_u32_e32 v212, 336, v210
	v_and_b32_e32 v212, 63, v212
	v_lshlrev_b32_e32 v212, 2, v212
	ds_bpermute_b32 v208, v212, v31
	s_waitcnt lgkmcnt(0)
	v_cmp_gt_u32_e32 vcc, 0x40, v189
	s_nop 1
	v_cndmask_b32_e32 v198, v177, v198, vcc
	v_cmp_gt_u32_e32 vcc, 0x80, v190
	s_nop 1
	v_cndmask_b32_e32 v199, v178, v199, vcc
	v_cmp_gt_u32_e32 vcc, 0x100, v193
	s_nop 1
	v_cndmask_b32_e32 v202, v181, v202, vcc
	v_cmp_gt_u32_e32 vcc, 0x140, v194
	s_nop 1
	v_cndmask_b32_e32 v203, v186, v203, vcc
	v_cmp_gt_u32_e32 vcc, 32, v211
	s_nop 1
	v_cndmask_b32_e32 v209, 0, v32, vcc
	v_mov_b32_e32 v196, 1.0
	v_lshlrev_b32_e32 v176, 16, v18
	v_and_b32_e32 v188, 0xffff0000, v18
	v_lshlrev_b32_e32 v177, 16, v19
	v_and_b32_e32 v189, 0xffff0000, v19
	v_lshlrev_b32_e32 v178, 16, v20
	v_and_b32_e32 v190, 0xffff0000, v20
	v_lshlrev_b32_e32 v179, 16, v21
	v_and_b32_e32 v191, 0xffff0000, v21
	v_lshlrev_b32_e32 v180, 16, v22
	v_and_b32_e32 v192, 0xffff0000, v22
	v_lshlrev_b32_e32 v181, 16, v23
	v_and_b32_e32 v193, 0xffff0000, v23
	v_lshlrev_b32_e32 v186, 16, v24
	v_and_b32_e32 v194, 0xffff0000, v24
	v_lshlrev_b32_e32 v187, 16, v25
	v_and_b32_e32 v195, 0xffff0000, v25
	v_permlane32_swap_b32_e32 v176, v188
	v_permlane32_swap_b32_e32 v177, v189
	v_permlane32_swap_b32_e32 v178, v190
	v_permlane32_swap_b32_e32 v179, v191
	v_permlane32_swap_b32_e32 v180, v192
	v_permlane32_swap_b32_e32 v181, v193
	v_permlane32_swap_b32_e32 v186, v194
	v_permlane32_swap_b32_e32 v187, v195
	v_mfma_f32_32x32x2_f32 v[160:175], v209, v196, 0
	v_mfma_f32_32x32x2_f32 v[226:241], v209, v196, 0
	v_mfma_f32_32x32x2_f32 v[160:175], v197, v176, v[160:175]
	v_mfma_f32_32x32x2_f32 v[226:241], v197, v188, v[226:241]
	v_mfma_f32_32x32x2_f32 v[160:175], v198, v177, v[160:175]
	v_mfma_f32_32x32x2_f32 v[226:241], v198, v189, v[226:241]
	v_mfma_f32_32x32x2_f32 v[160:175], v199, v178, v[160:175]
	v_mfma_f32_32x32x2_f32 v[226:241], v199, v190, v[226:241]
	v_mfma_f32_32x32x2_f32 v[160:175], v200, v179, v[160:175]
	v_mfma_f32_32x32x2_f32 v[226:241], v200, v191, v[226:241]
	v_mfma_f32_32x32x2_f32 v[160:175], v201, v180, v[160:175]
	v_mfma_f32_32x32x2_f32 v[226:241], v201, v192, v[226:241]
	v_mfma_f32_32x32x2_f32 v[160:175], v202, v181, v[160:175]
	v_mfma_f32_32x32x2_f32 v[226:241], v202, v193, v[226:241]
	v_mfma_f32_32x32x2_f32 v[160:175], v203, v186, v[160:175]
	v_mfma_f32_32x32x2_f32 v[226:241], v203, v194, v[226:241]
	v_mfma_f32_32x32x2_f32 v[160:175], v208, v187, v[160:175]
	v_mfma_f32_32x32x2_f32 v[226:241], v208, v195, v[226:241]
	s_nop 15
	s_nop 1
	v_permlane32_swap_b32_e32 v160, v226
	v_permlane32_swap_b32_e32 v161, v227
	v_permlane32_swap_b32_e32 v162, v228
	v_permlane32_swap_b32_e32 v163, v229
	v_permlane32_swap_b32_e32 v164, v230
	v_permlane32_swap_b32_e32 v165, v231
	v_permlane32_swap_b32_e32 v166, v232
	v_permlane32_swap_b32_e32 v167, v233
	v_permlane32_swap_b32_e32 v168, v234
	v_permlane32_swap_b32_e32 v169, v235
	v_permlane32_swap_b32_e32 v170, v236
	v_permlane32_swap_b32_e32 v171, v237
	v_lshlrev_b32_e32 v64, 16, v18
	v_and_b32_e32 v63, 0xffff0000, v18
	v_lshlrev_b32_e32 v50, 16, v25
;     __device__ __forceinline__ unsigned char* ws() const { return (unsigned char*)(__attribute__((address_space(1))) unsigned char*)ld(23); }
; __device__ __forceinline__ float lo16(unsigned w) { return __uint_as_float(w << 16); }
; __device__ __forceinline__ float hi16(unsigned w) { return __uint_as_float(w & 0xffff0000u); }
; template <bool PHC>
; __device__ __forceinline__ void gla_pair(const KPD& kp, int l, int pair, unsigned char* lds, int tid, int lane, int wave, v4u& pz0, v4u& pz1, v4u& pw0, v4u& pw1, int next_pair) {
;     ...
;     for (int i = 0; i < 3; ++i) { const int idx = t4 + 256 * i; vpre[i] = *(const v4u*)(P + (size_t)(rowbase + idx / 12) * INP + C_GV + h * 96 + 8 * (idx % 12)); }
;     v2u spre[9];
;     if constexpr (PHC) { const bf16* SI = (const bf16*)(kp.ws() + WS_SI);
; #pragma unroll
;         for (int i = 0; i < 9; ++i) { const int idx = t4 + 256 * i; const int dd = idx / 1152, e = (idx % 1152) * 4;
;             spre[i] = *(const v2u*)(SI + ((size_t)((dd * 4 + b) * NCH + n) * 4 + h) * 4608 + e); }
;     }
;     float z[16];
;     { const v4u z0 = pz0, z1 = pz1;
;       z[0] = lo16(z0.x); z[1] = hi16(z0.x); z[2] = lo16(z0.y); z[3] = hi16(z0.y); z[4] = lo16(z0.z); z[5] = hi16(z0.z); z[6] = lo16(z0.w); z[7] = hi16(z0.w);
;       z[8] = lo16(z1.x); z[9] = hi16(z1.x); z[10] = lo16(z1.y); z[11] = hi16(z1.y); z[12] = lo16(z1.z); z[13] = hi16(z1.z); z[14] = lo16(z1.w); z[15] = hi16(z1.w); }
;     v4u qraw[3], kraw[3];
; #pragma unroll
;     for (int i = 0; i < 3; ++i) { qraw[i] = *((const v4u*)(prow + C_GQ + h * 48 + d0) + i); kraw[i] = *((const v4u*)(prow + C_GK + h * 48 + d0) + i); }
;     const int wvv[6] = {(int)pw0.x, (int)pw0.y, (int)pw0.z, (int)pw0.w, (int)pw1.x, (int)pw1.y};
;     const int bvv = (int)pw1.z;
;     float bc[24], tot[24];
; #pragma unroll
;     for (int c = 0; c < 24; ++c) {
;         float pre = __int_as_float(__builtin_amdgcn_readlane(bvv, c));
; #pragma unroll
;         for (int r = 0; r < 16; ++r) pre += z[r] * __int_as_float(__builtin_amdgcn_readlane(wvv[(24 * r + c) >> 6], (24 * r + c) & 63));
;         const float la = (fminf(pre, 0.f) - __logf(1.f + __expf(-fabsf(pre)))) * (1.f / 16.f);
;         const float inc = wave_incl_scan(la);
;         const float total = __int_as_float(__builtin_amdgcn_readlane(__float_as_int(inc), 63));
;         bc[c] = dir ? (total - inc + la) : inc; tot[c] = total;
	v_and_b32_e32 v51, 0xffff0000, v25
	s_mov_b32 s72, 0xbfb8aa3b
	s_mul_i32 s78, s46, 0xc0
	s_mul_i32 s51, s46, 48
	v_lshl_add_u64 v[2:3], v[2:3], 0, s[78:79]
	v_lshl_add_u64 v[6:7], v[6:7], 0, s[78:79]
	v_lshl_add_u64 v[10:11], v[10:11], 0, s[78:79]
	s_lshl_b32 s78, s51, 1
	v_lshl_add_u64 v[14:15], v[14:15], 0, s[78:79]
	s_lshl_b32 s78, s40, 1
	v_mov_b32_e32 v38, v160
	v_min_f32_e32 v65, 0, v38
	v_mul_f32_e64 v38, |v38|, s72
	v_exp_f32_e32 v38, v38
	v_lshl_add_u64 v[46:47], v[14:15], 0, s[78:79]
	s_mov_b32 s78, 0x800000
	s_mov_b32 s87, 0x3f317217
	v_add_f32_e32 v38, 1.0, v38
	v_cmp_gt_f32_e32 vcc, s78, v38
	s_mov_b32 s97, 0x7f800000
	s_nop 0
	v_cndmask_b32_e64 v66, 0, 32, vcc
	v_ldexp_f32 v38, v38, v66
	v_log_f32_e32 v38, v38
	s_nop 0
	v_mul_f32_e32 v66, 0x3f317217, v38
	v_fma_f32 v66, v38, s87, -v66
	v_fmac_f32_e32 v66, 0x3377d1cf, v38
	v_fmac_f32_e32 v66, 0x3f317217, v38
	v_cmp_lt_f32_e64 s[10:11], |v38|, s97
	s_nop 1
	v_cndmask_b32_e64 v38, v38, v66, s[10:11]
	v_cndmask_b32_e32 v66, 0, v222, vcc
	v_sub_f32_e32 v38, v38, v66
	v_sub_f32_e32 v38, v65, v38
	v_mul_f32_e32 v65, 0x3d800000, v38
	v_mov_b32_e32 v66, v35
	s_nop 0
	v_mov_b32_dpp v65, v65 row_shr:1 row_mask:0xf bank_mask:0xf bound_ctrl:1
	v_fmac_f32_e32 v65, 0x3d800000, v38
	s_nop 1
	v_add_f32_dpp v65, v65, v65 row_shr:2 row_mask:0xf bank_mask:0xf bound_ctrl:1
	s_nop 1
	v_add_f32_dpp v65, v65, v65 row_shr:4 row_mask:0xf bank_mask:0xf bound_ctrl:1
	s_nop 1
	v_add_f32_dpp v65, v65, v65 row_shr:8 row_mask:0xf bank_mask:0xf bound_ctrl:1
	s_nop 1
	v_mov_b32_dpp v66, v65 row_bcast:15 row_mask:0xa bank_mask:0xf
	v_add_f32_e32 v65, v65, v66
	v_mov_b32_e32 v66, v35
	s_nop 0
	v_mov_b32_dpp v66, v65 row_bcast:31 row_mask:0xc bank_mask:0xf
	v_add_f32_e32 v65, v65, v66
	s_nop 0
	v_readlane_b32 s54, v65, 63
	s_nop 1
	v_sub_f32_e32 v66, s54, v65
	v_fmac_f32_e32 v66, 0x3d800000, v38
	v_cndmask_b32_e64 v65, v66, v65, s[0:1]
	global_store_dword v250, v65, s[100:101]
	v_mov_b32_e32 v38, v161
	v_min_f32_e32 v39, 0, v38
	v_mul_f32_e64 v38, |v38|, s72
	v_exp_f32_e32 v38, v38
	s_nop 0
	v_add_f32_e32 v38, 1.0, v38
	v_cmp_gt_f32_e32 vcc, s78, v38
	s_nop 1
	v_cndmask_b32_e64 v66, 0, 32, vcc
	v_ldexp_f32 v38, v38, v66
	v_log_f32_e32 v38, v38
	v_mov_b32_e32 v79, v35
	v_mul_f32_e32 v66, 0x3f317217, v38
	v_fma_f32 v66, v38, s87, -v66
	v_fmac_f32_e32 v66, 0x3377d1cf, v38
	v_fmac_f32_e32 v66, 0x3f317217, v38
	v_cmp_lt_f32_e64 s[10:11], |v38|, s97
	s_nop 1
	v_cndmask_b32_e64 v38, v38, v66, s[10:11]
	v_cndmask_b32_e32 v66, 0, v222, vcc
	v_sub_f32_e32 v38, v38, v66
	v_sub_f32_e32 v38, v39, v38
	v_mul_f32_e32 v39, 0x3d800000, v38
	v_mov_b32_e32 v66, v35
	s_nop 0
	v_mov_b32_dpp v39, v39 row_shr:1 row_mask:0xf bank_mask:0xf bound_ctrl:1
	v_fmac_f32_e32 v39, 0x3d800000, v38
	s_nop 1
	v_add_f32_dpp v39, v39, v39 row_shr:2 row_mask:0xf bank_mask:0xf bound_ctrl:1
	v_lshl_add_u64 v[2:3], v[2:3], 0, v[78:79]
	s_nop 0
	v_add_f32_dpp v39, v39, v39 row_shr:4 row_mask:0xf bank_mask:0xf bound_ctrl:1
	v_readlane_b32 s12, v31, 21
	s_nop 0
	v_add_f32_dpp v39, v39, v39 row_shr:8 row_mask:0xf bank_mask:0xf bound_ctrl:1
	v_readlane_b32 s13, v31, 45
	s_nop 0
	v_mov_b32_dpp v66, v39 row_bcast:15 row_mask:0xa bank_mask:0xf
	v_add_f32_e32 v39, v39, v66
	v_mov_b32_e32 v66, v35
	v_mov_b32_e32 v81, v35
	v_mov_b32_dpp v66, v39 row_bcast:31 row_mask:0xc bank_mask:0xf
	v_add_f32_e32 v39, v39, v66
	s_nop 0
	v_readlane_b32 s36, v39, 63
	v_lshl_add_u64 v[6:7], v[6:7], 0, v[80:81]
	s_nop 0
	v_sub_f32_e32 v66, s36, v39
	v_fmac_f32_e32 v66, 0x3d800000, v38
	v_cndmask_b32_e64 v66, v66, v39, s[0:1]
	global_store_dword v250, v66, s[100:101] offset:256
	v_mov_b32_e32 v83, v35
	v_mov_b32_e32 v38, v162
	v_min_f32_e32 v39, 0, v38
	v_mul_f32_e64 v38, |v38|, s72
	v_exp_f32_e32 v38, v38
	v_lshl_add_u64 v[10:11], v[10:11], 0, v[82:83]
	v_add_f32_e32 v38, 1.0, v38
	v_cmp_gt_f32_e32 vcc, s78, v38
	s_nop 1
	v_cndmask_b32_e64 v40, 0, 32, vcc
	v_ldexp_f32 v38, v38, v40
	v_log_f32_e32 v38, v38
	global_load_dwordx4 v[2:5], v[2:3], off offset:768
	v_mul_f32_e32 v40, 0x3f317217, v38
	v_fma_f32 v40, v38, s87, -v40
	v_fmac_f32_e32 v40, 0x3377d1cf, v38
	v_fmac_f32_e32 v40, 0x3f317217, v38
	v_cmp_lt_f32_e64 s[10:11], |v38|, s97
	s_nop 1
	v_cndmask_b32_e64 v38, v38, v40, s[10:11]
	v_cndmask_b32_e32 v40, 0, v222, vcc
	v_sub_f32_e32 v38, v38, v40
	v_sub_f32_e32 v38, v39, v38
	v_mul_f32_e32 v39, 0x3d800000, v38
	v_mov_b32_e32 v40, v35
	s_nop 0
	v_mov_b32_dpp v39, v39 row_shr:1 row_mask:0xf bank_mask:0xf bound_ctrl:1
	v_fmac_f32_e32 v39, 0x3d800000, v38
	s_nop 1
	v_add_f32_dpp v39, v39, v39 row_shr:2 row_mask:0xf bank_mask:0xf bound_ctrl:1
	global_load_dwordx4 v[6:9], v[6:7], off offset:768
	s_nop 0
	v_add_f32_dpp v39, v39, v39 row_shr:4 row_mask:0xf bank_mask:0xf bound_ctrl:1
	global_load_dwordx4 v[10:13], v[10:11], off offset:768
	s_nop 0
	v_add_f32_dpp v39, v39, v39 row_shr:8 row_mask:0xf bank_mask:0xf bound_ctrl:1
	global_load_dwordx4 v[14:17], v[46:47], off offset:416
	global_load_dwordx4 v[42:45], v[46:47], off offset:400
	global_load_dwordx4 v[46:49], v[46:47], off offset:384
	v_mov_b32_dpp v40, v39 row_bcast:15 row_mask:0xa bank_mask:0xf
	v_add_f32_e32 v39, v39, v40
	v_mov_b32_e32 v40, v35
	s_nop 0
	v_mov_b32_dpp v40, v39 row_bcast:31 row_mask:0xc bank_mask:0xf
	v_add_f32_e32 v39, v39, v40
	s_nop 0
	v_readlane_b32 s34, v39, 63
	s_nop 1
	v_sub_f32_e32 v40, s34, v39
	v_fmac_f32_e32 v40, 0x3d800000, v38
	v_cndmask_b32_e64 v67, v40, v39, s[0:1]
	global_store_dword v250, v67, s[100:101] offset:512
	v_mov_b32_e32 v38, v163
	v_min_f32_e32 v39, 0, v38
	v_mul_f32_e64 v38, |v38|, s72
	v_exp_f32_e32 v38, v38
	s_nop 0
	v_add_f32_e32 v38, 1.0, v38
	v_cmp_gt_f32_e32 vcc, s78, v38
	s_nop 1
	v_cndmask_b32_e64 v40, 0, 32, vcc
	v_ldexp_f32 v38, v38, v40
	v_log_f32_e32 v38, v38
	s_nop 0
	v_mul_f32_e32 v40, 0x3f317217, v38
	v_fma_f32 v40, v38, s87, -v40
	v_fmac_f32_e32 v40, 0x3377d1cf, v38
	v_fmac_f32_e32 v40, 0x3f317217, v38
	v_cmp_lt_f32_e64 s[10:11], |v38|, s97
	s_nop 1
	v_cndmask_b32_e64 v38, v38, v40, s[10:11]
	v_cndmask_b32_e32 v40, 0, v222, vcc
	v_sub_f32_e32 v38, v38, v40
	v_sub_f32_e32 v38, v39, v38
	v_mul_f32_e32 v39, 0x3d800000, v38
	v_mov_b32_e32 v40, v35
	s_nop 0
	v_mov_b32_dpp v39, v39 row_shr:1 row_mask:0xf bank_mask:0xf bound_ctrl:1
	v_fmac_f32_e32 v39, 0x3d800000, v38
	s_nop 1
	v_add_f32_dpp v39, v39, v39 row_shr:2 row_mask:0xf bank_mask:0xf bound_ctrl:1
	s_waitcnt vmcnt(0)
; template <bool PHC>
; __device__ __forceinline__ void gla_pair(const KPD& kp, int l, int pair, unsigned char* lds, int tid, int lane, int wave, v4u& pz0, v4u& pz1, v4u& pw0, v4u& pw1, int next_pair) {
;     ...
;     for (int c = 0; c < 24; ++c) {
;         float pre = __int_as_float(__builtin_amdgcn_readlane(bvv, c));
; #pragma unroll
;         for (int r = 0; r < 16; ++r) pre += z[r] * __int_as_float(__builtin_amdgcn_readlane(wvv[(24 * r + c) >> 6], (24 * r + c) & 63));
;         const float la = (fminf(pre, 0.f) - __logf(1.f + __expf(-fabsf(pre)))) * (1.f / 16.f);
;         const float inc = wave_incl_scan(la);
;         const float total = __int_as_float(__builtin_amdgcn_readlane(__float_as_int(inc), 63));
;         bc[c] = dir ? (total - inc + la) : inc; tot[c] = total;
	v_lshlrev_b32_e32 v41, 16, v47
	v_add_f32_dpp v39, v39, v39 row_shr:4 row_mask:0xf bank_mask:0xf bound_ctrl:1
	s_nop 1
	v_add_f32_dpp v39, v39, v39 row_shr:8 row_mask:0xf bank_mask:0xf bound_ctrl:1
	s_nop 1
	v_mov_b32_dpp v40, v39 row_bcast:15 row_mask:0xa bank_mask:0xf
	v_add_f32_e32 v39, v39, v40
	v_mov_b32_e32 v40, v35
	s_nop 0
	v_mov_b32_dpp v40, v39 row_bcast:31 row_mask:0xc bank_mask:0xf
	v_add_f32_e32 v39, v39, v40
	s_nop 0
	v_readlane_b32 s30, v39, 63
	s_nop 1
	v_sub_f32_e32 v40, s30, v39
	v_fmac_f32_e32 v40, 0x3d800000, v38
	v_cndmask_b32_e64 v68, v40, v39, s[0:1]
	global_store_dword v250, v68, s[100:101] offset:768
	v_mov_b32_e32 v38, v226
	v_min_f32_e32 v39, 0, v38
	v_mul_f32_e64 v38, |v38|, s72
	v_exp_f32_e32 v38, v38
	s_nop 0
	v_add_f32_e32 v38, 1.0, v38
	v_cmp_gt_f32_e32 vcc, s78, v38
	s_nop 1
	v_cndmask_b32_e64 v40, 0, 32, vcc
	v_ldexp_f32 v38, v38, v40
	v_log_f32_e32 v38, v38
	s_nop 0
	v_mul_f32_e32 v40, 0x3f317217, v38
	v_fma_f32 v40, v38, s87, -v40
	v_fmac_f32_e32 v40, 0x3377d1cf, v38
	v_fmac_f32_e32 v40, 0x3f317217, v38
	v_cmp_lt_f32_e64 s[10:11], |v38|, s97
	s_nop 1
	v_cndmask_b32_e64 v38, v38, v40, s[10:11]
	v_cndmask_b32_e32 v40, 0, v222, vcc
	v_sub_f32_e32 v38, v38, v40
	v_sub_f32_e32 v38, v39, v38
	v_mul_f32_e32 v39, 0x3d800000, v38
	v_mov_b32_e32 v40, v35
	s_nop 0
	v_mov_b32_dpp v39, v39 row_shr:1 row_mask:0xf bank_mask:0xf bound_ctrl:1
	v_fmac_f32_e32 v39, 0x3d800000, v38
	s_nop 1
	v_add_f32_dpp v39, v39, v39 row_shr:2 row_mask:0xf bank_mask:0xf bound_ctrl:1
	s_nop 1
	v_add_f32_dpp v39, v39, v39 row_shr:4 row_mask:0xf bank_mask:0xf bound_ctrl:1
	s_nop 1
	v_add_f32_dpp v39, v39, v39 row_shr:8 row_mask:0xf bank_mask:0xf bound_ctrl:1
	s_nop 1
	v_mov_b32_dpp v40, v39 row_bcast:15 row_mask:0xa bank_mask:0xf
	v_add_f32_e32 v39, v39, v40
	v_mov_b32_e32 v40, v35
	s_nop 0
	v_mov_b32_dpp v40, v39 row_bcast:31 row_mask:0xc bank_mask:0xf
	v_add_f32_e32 v39, v39, v40
	s_nop 0
	v_readlane_b32 s28, v39, 63
	s_nop 1
	v_sub_f32_e32 v40, s28, v39
	v_fmac_f32_e32 v40, 0x3d800000, v38
	v_cndmask_b32_e64 v69, v40, v39, s[0:1]
	global_store_dword v250, v69, s[100:101] offset:1024
	v_mov_b32_e32 v38, v227
	v_min_f32_e32 v39, 0, v38
	v_mul_f32_e64 v38, |v38|, s72
	v_exp_f32_e32 v38, v38
	s_nop 0
	v_add_f32_e32 v38, 1.0, v38
	v_cmp_gt_f32_e32 vcc, s78, v38
	s_nop 1
	v_cndmask_b32_e64 v40, 0, 32, vcc
	v_ldexp_f32 v38, v38, v40
	v_log_f32_e32 v38, v38
	s_nop 0
	v_mul_f32_e32 v40, 0x3f317217, v38
	v_fma_f32 v40, v38, s87, -v40
	v_fmac_f32_e32 v40, 0x3377d1cf, v38
	v_fmac_f32_e32 v40, 0x3f317217, v38
	v_cmp_lt_f32_e64 s[10:11], |v38|, s97
	s_nop 1
	v_cndmask_b32_e64 v38, v38, v40, s[10:11]
	v_cndmask_b32_e32 v40, 0, v222, vcc
	v_sub_f32_e32 v38, v38, v40
	v_sub_f32_e32 v38, v39, v38
	v_mul_f32_e32 v39, 0x3d800000, v38
	s_nop 1
	v_mov_b32_dpp v39, v39 row_shr:1 row_mask:0xf bank_mask:0xf bound_ctrl:1
	v_fmac_f32_e32 v39, 0x3d800000, v38
	s_nop 1
	v_add_f32_dpp v39, v39, v39 row_shr:2 row_mask:0xf bank_mask:0xf bound_ctrl:1
	v_mov_b32_e32 v40, v35
	s_nop 0
	v_add_f32_dpp v39, v39, v39 row_shr:4 row_mask:0xf bank_mask:0xf bound_ctrl:1
	s_nop 1
	v_add_f32_dpp v39, v39, v39 row_shr:8 row_mask:0xf bank_mask:0xf bound_ctrl:1
	s_nop 1
	v_mov_b32_dpp v40, v39 row_bcast:15 row_mask:0xa bank_mask:0xf
	v_add_f32_e32 v39, v39, v40
	v_mov_b32_e32 v40, v35
	s_nop 0
	v_mov_b32_dpp v40, v39 row_bcast:31 row_mask:0xc bank_mask:0xf
	v_add_f32_e32 v39, v39, v40
	s_nop 0
	v_readlane_b32 s29, v39, 63
	s_nop 1
	v_sub_f32_e32 v40, s29, v39
	v_fmac_f32_e32 v40, 0x3d800000, v38
	v_cndmask_b32_e64 v79, v40, v39, s[0:1]
	global_store_dword v250, v79, s[100:101] offset:1280
	v_mov_b32_e32 v38, v228
	v_min_f32_e32 v39, 0, v38
	v_mul_f32_e64 v38, |v38|, s72
	v_exp_f32_e32 v38, v38
	s_nop 0
	v_add_f32_e32 v38, 1.0, v38
	v_cmp_gt_f32_e32 vcc, s78, v38
	s_nop 1
	v_cndmask_b32_e64 v40, 0, 32, vcc
	v_ldexp_f32 v38, v38, v40
	v_log_f32_e32 v38, v38
	s_nop 0
	v_mul_f32_e32 v40, 0x3f317217, v38
	v_fma_f32 v40, v38, s87, -v40
	v_fmac_f32_e32 v40, 0x3377d1cf, v38
	v_fmac_f32_e32 v40, 0x3f317217, v38
	v_cmp_lt_f32_e64 s[10:11], |v38|, s97
	s_nop 1
	v_cndmask_b32_e64 v38, v38, v40, s[10:11]
	v_cndmask_b32_e32 v40, 0, v222, vcc
	v_sub_f32_e32 v38, v38, v40
	v_sub_f32_e32 v38, v39, v38
	v_mul_f32_e32 v39, 0x3d800000, v38
	v_mov_b32_e32 v40, v35
	s_nop 0
	v_mov_b32_dpp v39, v39 row_shr:1 row_mask:0xf bank_mask:0xf bound_ctrl:1
	v_fmac_f32_e32 v39, 0x3d800000, v38
	s_nop 1
	v_add_f32_dpp v39, v39, v39 row_shr:2 row_mask:0xf bank_mask:0xf bound_ctrl:1
	s_nop 1
	v_add_f32_dpp v39, v39, v39 row_shr:4 row_mask:0xf bank_mask:0xf bound_ctrl:1
	s_nop 1
	v_add_f32_dpp v39, v39, v39 row_shr:8 row_mask:0xf bank_mask:0xf bound_ctrl:1
	s_nop 1
	v_mov_b32_dpp v40, v39 row_bcast:15 row_mask:0xa bank_mask:0xf
	v_add_f32_e32 v39, v39, v40
	v_mov_b32_e32 v40, v35
	s_nop 0
	v_mov_b32_dpp v40, v39 row_bcast:31 row_mask:0xc bank_mask:0xf
	v_add_f32_e32 v39, v39, v40
	s_nop 0
	v_readlane_b32 s31, v39, 63
	s_nop 1
	v_sub_f32_e32 v40, s31, v39
	v_fmac_f32_e32 v40, 0x3d800000, v38
	v_cndmask_b32_e64 v81, v40, v39, s[0:1]
	global_store_dword v250, v81, s[100:101] offset:1536
	v_mov_b32_e32 v38, v229
	v_min_f32_e32 v39, 0, v38
	v_mul_f32_e64 v38, |v38|, s72
	v_exp_f32_e32 v38, v38
	s_nop 0
	v_add_f32_e32 v38, 1.0, v38
	v_cmp_gt_f32_e32 vcc, s78, v38
	s_nop 1
	v_cndmask_b32_e64 v40, 0, 32, vcc
	v_ldexp_f32 v38, v38, v40
	v_log_f32_e32 v38, v38
	s_nop 0
	v_mul_f32_e32 v40, 0x3f317217, v38
	v_fma_f32 v40, v38, s87, -v40
	v_fmac_f32_e32 v40, 0x3377d1cf, v38
	v_fmac_f32_e32 v40, 0x3f317217, v38
	v_cmp_lt_f32_e64 s[10:11], |v38|, s97
	s_nop 1
	v_cndmask_b32_e64 v38, v38, v40, s[10:11]
	v_cndmask_b32_e32 v40, 0, v222, vcc
; template <bool PHC>
; __device__ __forceinline__ void gla_pair(const KPD& kp, int l, int pair, unsigned char* lds, int tid, int lane, int wave, v4u& pz0, v4u& pz1, v4u& pw0, v4u& pw1, int next_pair) {
;     ...
;     for (int c = 0; c < 24; ++c) {
;         float pre = __int_as_float(__builtin_amdgcn_readlane(bvv, c));
; #pragma unroll
;         for (int r = 0; r < 16; ++r) pre += z[r] * __int_as_float(__builtin_amdgcn_readlane(wvv[(24 * r + c) >> 6], (24 * r + c) & 63));
;         const float la = (fminf(pre, 0.f) - __logf(1.f + __expf(-fabsf(pre)))) * (1.f / 16.f);
;         const float inc = wave_incl_scan(la);
;         const float total = __int_as_float(__builtin_amdgcn_readlane(__float_as_int(inc), 63));
;         bc[c] = dir ? (total - inc + la) : inc; tot[c] = total;
	v_sub_f32_e32 v38, v38, v40
	v_sub_f32_e32 v38, v39, v38
	v_mul_f32_e32 v39, 0x3d800000, v38
	v_mov_b32_e32 v40, v35
	s_nop 0
	v_mov_b32_dpp v39, v39 row_shr:1 row_mask:0xf bank_mask:0xf bound_ctrl:1
	v_fmac_f32_e32 v39, 0x3d800000, v38
	s_nop 1
	v_add_f32_dpp v39, v39, v39 row_shr:2 row_mask:0xf bank_mask:0xf bound_ctrl:1
	s_nop 1
	v_add_f32_dpp v39, v39, v39 row_shr:4 row_mask:0xf bank_mask:0xf bound_ctrl:1
	s_nop 1
	v_add_f32_dpp v39, v39, v39 row_shr:8 row_mask:0xf bank_mask:0xf bound_ctrl:1
	s_nop 1
	v_mov_b32_dpp v40, v39 row_bcast:15 row_mask:0xa bank_mask:0xf
	v_add_f32_e32 v39, v39, v40
	v_mov_b32_e32 v40, v35
	s_nop 0
	v_mov_b32_dpp v40, v39 row_bcast:31 row_mask:0xc bank_mask:0xf
	v_add_f32_e32 v39, v39, v40
	s_nop 0
	v_readlane_b32 s35, v39, 63
	s_nop 1
	v_sub_f32_e32 v40, s35, v39
	v_fmac_f32_e32 v40, 0x3d800000, v38
	v_cndmask_b32_e64 v83, v40, v39, s[0:1]
	global_store_dword v250, v83, s[100:101] offset:1792
	v_mov_b32_e32 v38, v164
	v_min_f32_e32 v39, 0, v38
	v_mul_f32_e64 v38, |v38|, s72
	v_exp_f32_e32 v38, v38
	s_nop 0
	v_add_f32_e32 v38, 1.0, v38
	v_cmp_gt_f32_e32 vcc, s78, v38
	s_nop 1
	v_cndmask_b32_e64 v40, 0, 32, vcc
	v_ldexp_f32 v38, v38, v40
	v_log_f32_e32 v38, v38
	s_nop 0
	v_mul_f32_e32 v40, 0x3f317217, v38
	v_fma_f32 v40, v38, s87, -v40
	v_fmac_f32_e32 v40, 0x3377d1cf, v38
	v_fmac_f32_e32 v40, 0x3f317217, v38
	v_cmp_lt_f32_e64 s[10:11], |v38|, s97
	s_nop 1
	v_cndmask_b32_e64 v38, v38, v40, s[10:11]
	v_cndmask_b32_e32 v40, 0, v222, vcc
	v_sub_f32_e32 v38, v38, v40
	v_sub_f32_e32 v38, v39, v38
	v_mul_f32_e32 v39, 0x3d800000, v38
	v_mov_b32_e32 v40, v35
	s_nop 0
	v_mov_b32_dpp v39, v39 row_shr:1 row_mask:0xf bank_mask:0xf bound_ctrl:1
	v_fmac_f32_e32 v39, 0x3d800000, v38
	s_nop 1
	v_add_f32_dpp v39, v39, v39 row_shr:2 row_mask:0xf bank_mask:0xf bound_ctrl:1
	s_nop 1
	v_add_f32_dpp v39, v39, v39 row_shr:4 row_mask:0xf bank_mask:0xf bound_ctrl:1
	s_nop 1
	v_add_f32_dpp v39, v39, v39 row_shr:8 row_mask:0xf bank_mask:0xf bound_ctrl:1
	s_nop 1
	v_mov_b32_dpp v40, v39 row_bcast:15 row_mask:0xa bank_mask:0xf
	v_add_f32_e32 v39, v39, v40
	v_mov_b32_e32 v40, v35
	s_nop 0
	v_mov_b32_dpp v40, v39 row_bcast:31 row_mask:0xc bank_mask:0xf
	v_add_f32_e32 v39, v39, v40
	s_nop 0
	v_readlane_b32 s37, v39, 63
	s_nop 1
	v_sub_f32_e32 v40, s37, v39
	v_fmac_f32_e32 v40, 0x3d800000, v38
	v_cndmask_b32_e64 v85, v40, v39, s[0:1]
	global_store_dword v250, v85, s[100:101] offset:2048
	v_mov_b32_e32 v38, v165
	v_min_f32_e32 v39, 0, v38
	v_mul_f32_e64 v38, |v38|, s72
	v_exp_f32_e32 v38, v38
	s_nop 0
	v_add_f32_e32 v38, 1.0, v38
	v_cmp_gt_f32_e32 vcc, s78, v38
	s_nop 1
	v_cndmask_b32_e64 v40, 0, 32, vcc
	v_ldexp_f32 v38, v38, v40
	v_log_f32_e32 v38, v38
	s_nop 0
	v_mul_f32_e32 v40, 0x3f317217, v38
	v_fma_f32 v40, v38, s87, -v40
	v_fmac_f32_e32 v40, 0x3377d1cf, v38
	v_fmac_f32_e32 v40, 0x3f317217, v38
	v_cmp_lt_f32_e64 s[10:11], |v38|, s97
	s_nop 1
	v_cndmask_b32_e64 v38, v38, v40, s[10:11]
	v_cndmask_b32_e32 v40, 0, v222, vcc
	v_sub_f32_e32 v38, v38, v40
	v_sub_f32_e32 v38, v39, v38
	v_mul_f32_e32 v39, 0x3d800000, v38
	v_mov_b32_e32 v40, v35
	s_nop 0
	v_mov_b32_dpp v39, v39 row_shr:1 row_mask:0xf bank_mask:0xf bound_ctrl:1
	v_fmac_f32_e32 v39, 0x3d800000, v38
	s_nop 1
	v_add_f32_dpp v39, v39, v39 row_shr:2 row_mask:0xf bank_mask:0xf bound_ctrl:1
	s_nop 1
	v_add_f32_dpp v39, v39, v39 row_shr:4 row_mask:0xf bank_mask:0xf bound_ctrl:1
	s_nop 1
	v_add_f32_dpp v39, v39, v39 row_shr:8 row_mask:0xf bank_mask:0xf bound_ctrl:1
	s_nop 1
	v_mov_b32_dpp v40, v39 row_bcast:15 row_mask:0xa bank_mask:0xf
	v_add_f32_e32 v39, v39, v40
	v_mov_b32_e32 v40, v35
	s_nop 0
	v_mov_b32_dpp v40, v39 row_bcast:31 row_mask:0xc bank_mask:0xf
	v_add_f32_e32 v39, v39, v40
	s_nop 0
	v_readlane_b32 s55, v39, 63
	s_nop 1
	v_sub_f32_e32 v40, s55, v39
	v_fmac_f32_e32 v40, 0x3d800000, v38
	v_cndmask_b32_e64 v87, v40, v39, s[0:1]
	global_store_dword v250, v87, s[100:101] offset:2304
	v_mov_b32_e32 v38, v166
	v_min_f32_e32 v39, 0, v38
	v_mul_f32_e64 v38, |v38|, s72
	v_exp_f32_e32 v38, v38
	s_nop 0
	v_add_f32_e32 v38, 1.0, v38
	v_cmp_gt_f32_e32 vcc, s78, v38
	s_nop 1
	v_cndmask_b32_e64 v40, 0, 32, vcc
	v_ldexp_f32 v38, v38, v40
	v_log_f32_e32 v38, v38
	s_nop 0
	v_mul_f32_e32 v40, 0x3f317217, v38
	v_fma_f32 v40, v38, s87, -v40
	v_fmac_f32_e32 v40, 0x3377d1cf, v38
	v_fmac_f32_e32 v40, 0x3f317217, v38
	v_cmp_lt_f32_e64 s[10:11], |v38|, s97
	s_nop 1
	v_cndmask_b32_e64 v38, v38, v40, s[10:11]
	v_cndmask_b32_e32 v40, 0, v222, vcc
	v_sub_f32_e32 v38, v38, v40
	v_sub_f32_e32 v38, v39, v38
	v_mul_f32_e32 v39, 0x3d800000, v38
	v_mov_b32_e32 v40, v35
	s_nop 0
	v_mov_b32_dpp v39, v39 row_shr:1 row_mask:0xf bank_mask:0xf bound_ctrl:1
	v_fmac_f32_e32 v39, 0x3d800000, v38
	s_nop 1
	v_add_f32_dpp v39, v39, v39 row_shr:2 row_mask:0xf bank_mask:0xf bound_ctrl:1
	s_nop 1
	v_add_f32_dpp v39, v39, v39 row_shr:4 row_mask:0xf bank_mask:0xf bound_ctrl:1
	s_nop 1
	v_add_f32_dpp v39, v39, v39 row_shr:8 row_mask:0xf bank_mask:0xf bound_ctrl:1
	s_nop 1
	v_mov_b32_dpp v40, v39 row_bcast:15 row_mask:0xa bank_mask:0xf
	v_add_f32_e32 v39, v39, v40
	v_mov_b32_e32 v40, v35
	s_nop 0
	v_mov_b32_dpp v40, v39 row_bcast:31 row_mask:0xc bank_mask:0xf
	v_add_f32_e32 v39, v39, v40
	s_nop 0
	v_readlane_b32 s56, v39, 63
	s_nop 1
	v_sub_f32_e32 v40, s56, v39
	v_fmac_f32_e32 v40, 0x3d800000, v38
	v_cndmask_b32_e64 v89, v40, v39, s[0:1]
	global_store_dword v250, v89, s[100:101] offset:2560
	v_mov_b32_e32 v38, v167
	v_min_f32_e32 v39, 0, v38
	v_mul_f32_e64 v38, |v38|, s72
	v_exp_f32_e32 v38, v38
	s_nop 0
	v_add_f32_e32 v38, 1.0, v38
	v_cmp_gt_f32_e32 vcc, s78, v38
	s_nop 1
	v_cndmask_b32_e64 v40, 0, 32, vcc
	v_ldexp_f32 v38, v38, v40
; template <bool PHC>
; __device__ __forceinline__ void gla_pair(const KPD& kp, int l, int pair, unsigned char* lds, int tid, int lane, int wave, v4u& pz0, v4u& pz1, v4u& pw0, v4u& pw1, int next_pair) {
;     ...
;     for (int c = 0; c < 24; ++c) {
;         float pre = __int_as_float(__builtin_amdgcn_readlane(bvv, c));
; #pragma unroll
;         for (int r = 0; r < 16; ++r) pre += z[r] * __int_as_float(__builtin_amdgcn_readlane(wvv[(24 * r + c) >> 6], (24 * r + c) & 63));
;         const float la = (fminf(pre, 0.f) - __logf(1.f + __expf(-fabsf(pre)))) * (1.f / 16.f);
;         const float inc = wave_incl_scan(la);
;         const float total = __int_as_float(__builtin_amdgcn_readlane(__float_as_int(inc), 63));
;         bc[c] = dir ? (total - inc + la) : inc; tot[c] = total;
	v_log_f32_e32 v38, v38
	s_nop 0
	v_mul_f32_e32 v40, 0x3f317217, v38
	v_fma_f32 v40, v38, s87, -v40
	v_fmac_f32_e32 v40, 0x3377d1cf, v38
	v_fmac_f32_e32 v40, 0x3f317217, v38
	v_cmp_lt_f32_e64 s[10:11], |v38|, s97
	s_nop 1
	v_cndmask_b32_e64 v38, v38, v40, s[10:11]
	v_cndmask_b32_e32 v40, 0, v222, vcc
	v_sub_f32_e32 v38, v38, v40
	v_sub_f32_e32 v38, v39, v38
	v_mul_f32_e32 v39, 0x3d800000, v38
	v_mov_b32_e32 v40, v35
	s_nop 0
	v_mov_b32_dpp v39, v39 row_shr:1 row_mask:0xf bank_mask:0xf bound_ctrl:1
	v_fmac_f32_e32 v39, 0x3d800000, v38
	s_nop 1
	v_add_f32_dpp v39, v39, v39 row_shr:2 row_mask:0xf bank_mask:0xf bound_ctrl:1
	s_nop 1
	v_add_f32_dpp v39, v39, v39 row_shr:4 row_mask:0xf bank_mask:0xf bound_ctrl:1
	s_nop 1
	v_add_f32_dpp v39, v39, v39 row_shr:8 row_mask:0xf bank_mask:0xf bound_ctrl:1
	s_nop 1
	v_mov_b32_dpp v40, v39 row_bcast:15 row_mask:0xa bank_mask:0xf
	v_add_f32_e32 v39, v39, v40
	v_mov_b32_e32 v40, v35
	s_nop 0
	v_mov_b32_dpp v40, v39 row_bcast:31 row_mask:0xc bank_mask:0xf
	v_add_f32_e32 v39, v39, v40
	s_nop 0
	v_readlane_b32 s57, v39, 63
	s_nop 1
	v_sub_f32_e32 v40, s57, v39
	v_fmac_f32_e32 v40, 0x3d800000, v38
	v_cndmask_b32_e64 v91, v40, v39, s[0:1]
	global_store_dword v250, v91, s[100:101] offset:2816
	v_mov_b32_e32 v38, v230
	v_min_f32_e32 v39, 0, v38
	v_mul_f32_e64 v38, |v38|, s72
	v_exp_f32_e32 v38, v38
	s_nop 0
	v_add_f32_e32 v38, 1.0, v38
	v_cmp_gt_f32_e32 vcc, s78, v38
	s_nop 1
	v_cndmask_b32_e64 v40, 0, 32, vcc
	v_ldexp_f32 v38, v38, v40
	v_log_f32_e32 v38, v38
	s_nop 0
	v_mul_f32_e32 v40, 0x3f317217, v38
	v_fma_f32 v40, v38, s87, -v40
	v_fmac_f32_e32 v40, 0x3377d1cf, v38
	v_fmac_f32_e32 v40, 0x3f317217, v38
	v_cmp_lt_f32_e64 s[10:11], |v38|, s97
	s_nop 1
	v_cndmask_b32_e64 v38, v38, v40, s[10:11]
	v_cndmask_b32_e32 v40, 0, v222, vcc
	v_sub_f32_e32 v38, v38, v40
	v_sub_f32_e32 v38, v39, v38
	v_mul_f32_e32 v39, 0x3d800000, v38
	v_mov_b32_e32 v40, v35
	s_nop 0
	v_mov_b32_dpp v39, v39 row_shr:1 row_mask:0xf bank_mask:0xf bound_ctrl:1
	v_fmac_f32_e32 v39, 0x3d800000, v38
	s_nop 1
	v_add_f32_dpp v39, v39, v39 row_shr:2 row_mask:0xf bank_mask:0xf bound_ctrl:1
	s_nop 1
	v_add_f32_dpp v39, v39, v39 row_shr:4 row_mask:0xf bank_mask:0xf bound_ctrl:1
	s_nop 1
	v_add_f32_dpp v39, v39, v39 row_shr:8 row_mask:0xf bank_mask:0xf bound_ctrl:1
	s_nop 1
	v_mov_b32_dpp v40, v39 row_bcast:15 row_mask:0xa bank_mask:0xf
	v_add_f32_e32 v39, v39, v40
	v_mov_b32_e32 v40, v35
	s_nop 0
	v_mov_b32_dpp v40, v39 row_bcast:31 row_mask:0xc bank_mask:0xf
	v_add_f32_e32 v39, v39, v40
	s_nop 0
	v_readlane_b32 s59, v39, 63
	s_nop 1
	v_sub_f32_e32 v40, s59, v39
	v_fmac_f32_e32 v40, 0x3d800000, v38
	v_cndmask_b32_e64 v93, v40, v39, s[0:1]
	global_store_dword v250, v93, s[100:101] offset:3072
	v_mov_b32_e32 v38, v231
	v_min_f32_e32 v39, 0, v38
	v_mul_f32_e64 v38, |v38|, s72
	v_exp_f32_e32 v38, v38
	s_nop 0
	v_add_f32_e32 v38, 1.0, v38
	v_cmp_gt_f32_e32 vcc, s78, v38
	s_nop 1
	v_cndmask_b32_e64 v40, 0, 32, vcc
	v_ldexp_f32 v38, v38, v40
	v_log_f32_e32 v38, v38
	s_nop 0
	v_mul_f32_e32 v40, 0x3f317217, v38
	v_fma_f32 v40, v38, s87, -v40
	v_fmac_f32_e32 v40, 0x3377d1cf, v38
	v_fmac_f32_e32 v40, 0x3f317217, v38
	v_cmp_lt_f32_e64 s[10:11], |v38|, s97
	s_nop 1
	v_cndmask_b32_e64 v38, v38, v40, s[10:11]
	v_cndmask_b32_e32 v40, 0, v222, vcc
	v_sub_f32_e32 v38, v38, v40
	v_sub_f32_e32 v38, v39, v38
	v_mul_f32_e32 v39, 0x3d800000, v38
	v_mov_b32_e32 v40, v35
	s_nop 0
	v_mov_b32_dpp v39, v39 row_shr:1 row_mask:0xf bank_mask:0xf bound_ctrl:1
	v_fmac_f32_e32 v39, 0x3d800000, v38
	s_nop 1
	v_add_f32_dpp v39, v39, v39 row_shr:2 row_mask:0xf bank_mask:0xf bound_ctrl:1
	s_nop 1
	v_add_f32_dpp v39, v39, v39 row_shr:4 row_mask:0xf bank_mask:0xf bound_ctrl:1
	s_nop 1
	v_add_f32_dpp v39, v39, v39 row_shr:8 row_mask:0xf bank_mask:0xf bound_ctrl:1
	s_nop 1
	v_mov_b32_dpp v40, v39 row_bcast:15 row_mask:0xa bank_mask:0xf
	v_add_f32_e32 v39, v39, v40
	v_mov_b32_e32 v40, v35
	s_nop 0
	v_mov_b32_dpp v40, v39 row_bcast:31 row_mask:0xc bank_mask:0xf
	v_add_f32_e32 v39, v39, v40
	s_nop 0
	v_readlane_b32 s60, v39, 63
	s_nop 1
	v_sub_f32_e32 v40, s60, v39
	v_fmac_f32_e32 v40, 0x3d800000, v38
	v_cndmask_b32_e64 v94, v40, v39, s[0:1]
	global_store_dword v250, v94, s[100:101] offset:3328
	v_mov_b32_e32 v38, v232
	v_min_f32_e32 v39, 0, v38
	v_mul_f32_e64 v38, |v38|, s72
	v_exp_f32_e32 v38, v38
	s_nop 0
	v_add_f32_e32 v38, 1.0, v38
	v_cmp_gt_f32_e32 vcc, s78, v38
	s_nop 1
	v_cndmask_b32_e64 v40, 0, 32, vcc
	v_ldexp_f32 v38, v38, v40
	v_log_f32_e32 v38, v38
	s_nop 0
	v_mul_f32_e32 v40, 0x3f317217, v38
	v_fma_f32 v40, v38, s87, -v40
	v_fmac_f32_e32 v40, 0x3377d1cf, v38
	v_fmac_f32_e32 v40, 0x3f317217, v38
	v_cmp_lt_f32_e64 s[10:11], |v38|, s97
	s_nop 1
	v_cndmask_b32_e64 v38, v38, v40, s[10:11]
	v_cndmask_b32_e32 v40, 0, v222, vcc
	v_sub_f32_e32 v38, v38, v40
	v_sub_f32_e32 v38, v39, v38
	v_mul_f32_e32 v39, 0x3d800000, v38
	v_mov_b32_e32 v40, v35
	s_nop 0
	v_mov_b32_dpp v39, v39 row_shr:1 row_mask:0xf bank_mask:0xf bound_ctrl:1
	v_fmac_f32_e32 v39, 0x3d800000, v38
	s_nop 1
	v_add_f32_dpp v39, v39, v39 row_shr:2 row_mask:0xf bank_mask:0xf bound_ctrl:1
	s_nop 1
	v_add_f32_dpp v39, v39, v39 row_shr:4 row_mask:0xf bank_mask:0xf bound_ctrl:1
	s_nop 1
	v_add_f32_dpp v39, v39, v39 row_shr:8 row_mask:0xf bank_mask:0xf bound_ctrl:1
	s_nop 1
	v_mov_b32_dpp v40, v39 row_bcast:15 row_mask:0xa bank_mask:0xf
	v_add_f32_e32 v39, v39, v40
	v_mov_b32_e32 v40, v35
	s_nop 0
	v_mov_b32_dpp v40, v39 row_bcast:31 row_mask:0xc bank_mask:0xf
	v_add_f32_e32 v39, v39, v40
	s_nop 0
	v_readlane_b32 s61, v39, 63
	s_nop 1
	v_sub_f32_e32 v40, s61, v39
	v_fmac_f32_e32 v40, 0x3d800000, v38
	v_cndmask_b32_e64 v95, v40, v39, s[0:1]
; template <bool PHC>
; __device__ __forceinline__ void gla_pair(const KPD& kp, int l, int pair, unsigned char* lds, int tid, int lane, int wave, v4u& pz0, v4u& pz1, v4u& pw0, v4u& pw1, int next_pair) {
;     ...
;     for (int c = 0; c < 24; ++c) {
;         float pre = __int_as_float(__builtin_amdgcn_readlane(bvv, c));
; #pragma unroll
;         for (int r = 0; r < 16; ++r) pre += z[r] * __int_as_float(__builtin_amdgcn_readlane(wvv[(24 * r + c) >> 6], (24 * r + c) & 63));
;         const float la = (fminf(pre, 0.f) - __logf(1.f + __expf(-fabsf(pre)))) * (1.f / 16.f);
;         const float inc = wave_incl_scan(la);
;         const float total = __int_as_float(__builtin_amdgcn_readlane(__float_as_int(inc), 63));
;         bc[c] = dir ? (total - inc + la) : inc; tot[c] = total;
	global_store_dword v250, v95, s[100:101] offset:3584
	v_mov_b32_e32 v38, v233
	v_min_f32_e32 v39, 0, v38
	v_mul_f32_e64 v38, |v38|, s72
	v_exp_f32_e32 v38, v38
	s_nop 0
	v_add_f32_e32 v38, 1.0, v38
	v_cmp_gt_f32_e32 vcc, s78, v38
	s_nop 1
	v_cndmask_b32_e64 v40, 0, 32, vcc
	v_ldexp_f32 v38, v38, v40
	v_log_f32_e32 v38, v38
	s_nop 0
	v_mul_f32_e32 v40, 0x3f317217, v38
	v_fma_f32 v40, v38, s87, -v40
	v_fmac_f32_e32 v40, 0x3377d1cf, v38
	v_fmac_f32_e32 v40, 0x3f317217, v38
	v_cmp_lt_f32_e64 s[10:11], |v38|, s97
	s_nop 1
	v_cndmask_b32_e64 v38, v38, v40, s[10:11]
	v_cndmask_b32_e32 v40, 0, v222, vcc
	v_sub_f32_e32 v38, v38, v40
	v_sub_f32_e32 v38, v39, v38
	v_mul_f32_e32 v39, 0x3d800000, v38
	v_mov_b32_e32 v40, v35
	s_nop 0
	v_mov_b32_dpp v39, v39 row_shr:1 row_mask:0xf bank_mask:0xf bound_ctrl:1
	v_fmac_f32_e32 v39, 0x3d800000, v38
	s_nop 1
	v_add_f32_dpp v39, v39, v39 row_shr:2 row_mask:0xf bank_mask:0xf bound_ctrl:1
	s_nop 1
	v_add_f32_dpp v39, v39, v39 row_shr:4 row_mask:0xf bank_mask:0xf bound_ctrl:1
	s_nop 1
	v_add_f32_dpp v39, v39, v39 row_shr:8 row_mask:0xf bank_mask:0xf bound_ctrl:1
	s_nop 1
	v_mov_b32_dpp v40, v39 row_bcast:15 row_mask:0xa bank_mask:0xf
	v_add_f32_e32 v39, v39, v40
	v_mov_b32_e32 v40, v35
	s_nop 0
	v_mov_b32_dpp v40, v39 row_bcast:31 row_mask:0xc bank_mask:0xf
	v_add_f32_e32 v39, v39, v40
	s_nop 0
	v_readlane_b32 s62, v39, 63
	s_nop 1
	v_sub_f32_e32 v40, s62, v39
	v_fmac_f32_e32 v40, 0x3d800000, v38
	v_cndmask_b32_e64 v96, v40, v39, s[0:1]
	global_store_dword v250, v96, s[100:101] offset:3840
	v_mov_b32_e32 v38, v168
	v_min_f32_e32 v39, 0, v38
	v_mul_f32_e64 v38, |v38|, s72
	v_exp_f32_e32 v38, v38
	s_nop 0
	v_add_f32_e32 v38, 1.0, v38
	v_cmp_gt_f32_e32 vcc, s78, v38
	s_nop 1
	v_cndmask_b32_e64 v40, 0, 32, vcc
	v_ldexp_f32 v38, v38, v40
	v_log_f32_e32 v38, v38
	s_nop 0
	v_mul_f32_e32 v40, 0x3f317217, v38
	v_fma_f32 v40, v38, s87, -v40
	v_fmac_f32_e32 v40, 0x3377d1cf, v38
	v_fmac_f32_e32 v40, 0x3f317217, v38
	v_cmp_lt_f32_e64 s[10:11], |v38|, s97
	s_nop 1
	v_cndmask_b32_e64 v38, v38, v40, s[10:11]
	v_cndmask_b32_e32 v40, 0, v222, vcc
	v_sub_f32_e32 v38, v38, v40
	v_sub_f32_e32 v38, v39, v38
	v_mul_f32_e32 v39, 0x3d800000, v38
	v_mov_b32_e32 v40, v35
	s_nop 0
	v_mov_b32_dpp v39, v39 row_shr:1 row_mask:0xf bank_mask:0xf bound_ctrl:1
	v_fmac_f32_e32 v39, 0x3d800000, v38
	s_nop 1
	v_add_f32_dpp v39, v39, v39 row_shr:2 row_mask:0xf bank_mask:0xf bound_ctrl:1
	s_nop 1
	v_add_f32_dpp v39, v39, v39 row_shr:4 row_mask:0xf bank_mask:0xf bound_ctrl:1
	s_nop 1
	v_add_f32_dpp v39, v39, v39 row_shr:8 row_mask:0xf bank_mask:0xf bound_ctrl:1
	s_nop 1
	v_mov_b32_dpp v40, v39 row_bcast:15 row_mask:0xa bank_mask:0xf
	v_add_f32_e32 v39, v39, v40
	v_mov_b32_e32 v40, v35
	s_nop 0
	v_mov_b32_dpp v40, v39 row_bcast:31 row_mask:0xc bank_mask:0xf
	v_add_f32_e32 v39, v39, v40
	s_nop 0
	v_readlane_b32 s63, v39, 63
	s_nop 1
	v_sub_f32_e32 v40, s63, v39
	v_fmac_f32_e32 v40, 0x3d800000, v38
	v_cndmask_b32_e64 v97, v40, v39, s[0:1]
	global_store_dword v251, v97, s[100:101]
	v_mov_b32_e32 v38, v169
	v_min_f32_e32 v39, 0, v38
	v_mul_f32_e64 v38, |v38|, s72
	v_exp_f32_e32 v38, v38
	s_nop 0
	v_add_f32_e32 v38, 1.0, v38
	v_cmp_gt_f32_e32 vcc, s78, v38
	s_nop 1
	v_cndmask_b32_e64 v40, 0, 32, vcc
	v_ldexp_f32 v38, v38, v40
	v_log_f32_e32 v38, v38
	s_nop 0
	v_mul_f32_e32 v40, 0x3f317217, v38
	v_fma_f32 v40, v38, s87, -v40
	v_fmac_f32_e32 v40, 0x3377d1cf, v38
	v_fmac_f32_e32 v40, 0x3f317217, v38
	v_cmp_lt_f32_e64 s[10:11], |v38|, s97
	s_nop 1
	v_cndmask_b32_e64 v38, v38, v40, s[10:11]
	v_cndmask_b32_e32 v40, 0, v222, vcc
	v_sub_f32_e32 v38, v38, v40
	v_sub_f32_e32 v38, v39, v38
	v_mul_f32_e32 v39, 0x3d800000, v38
	v_mov_b32_e32 v40, v35
	s_nop 0
	v_mov_b32_dpp v39, v39 row_shr:1 row_mask:0xf bank_mask:0xf bound_ctrl:1
	v_fmac_f32_e32 v39, 0x3d800000, v38
	s_nop 1
	v_add_f32_dpp v39, v39, v39 row_shr:2 row_mask:0xf bank_mask:0xf bound_ctrl:1
	s_nop 1
	v_add_f32_dpp v39, v39, v39 row_shr:4 row_mask:0xf bank_mask:0xf bound_ctrl:1
	s_nop 1
	v_add_f32_dpp v39, v39, v39 row_shr:8 row_mask:0xf bank_mask:0xf bound_ctrl:1
	s_nop 1
	v_mov_b32_dpp v40, v39 row_bcast:15 row_mask:0xa bank_mask:0xf
	v_add_f32_e32 v39, v39, v40
	v_mov_b32_e32 v40, v35
	s_nop 0
	v_mov_b32_dpp v40, v39 row_bcast:31 row_mask:0xc bank_mask:0xf
	v_add_f32_e32 v39, v39, v40
	s_nop 0
	v_readlane_b32 s64, v39, 63
	s_nop 1
	v_sub_f32_e32 v40, s64, v39
	v_fmac_f32_e32 v40, 0x3d800000, v38
	v_cndmask_b32_e64 v98, v40, v39, s[0:1]
	global_store_dword v251, v98, s[100:101] offset:256
	v_mov_b32_e32 v38, v170
	v_min_f32_e32 v39, 0, v38
	v_mul_f32_e64 v38, |v38|, s72
	v_exp_f32_e32 v38, v38
	s_nop 0
	v_add_f32_e32 v38, 1.0, v38
	v_cmp_gt_f32_e32 vcc, s78, v38
	s_nop 1
	v_cndmask_b32_e64 v40, 0, 32, vcc
	v_ldexp_f32 v38, v38, v40
	v_log_f32_e32 v38, v38
	s_nop 0
	v_mul_f32_e32 v40, 0x3f317217, v38
	v_fma_f32 v40, v38, s87, -v40
	v_fmac_f32_e32 v40, 0x3377d1cf, v38
	v_fmac_f32_e32 v40, 0x3f317217, v38
	v_cmp_lt_f32_e64 s[10:11], |v38|, s97
	s_nop 1
	v_cndmask_b32_e64 v38, v38, v40, s[10:11]
	v_cndmask_b32_e32 v40, 0, v222, vcc
	v_sub_f32_e32 v38, v38, v40
	v_sub_f32_e32 v38, v39, v38
	v_mul_f32_e32 v39, 0x3d800000, v38
	v_mov_b32_e32 v40, v35
	s_nop 0
	v_mov_b32_dpp v39, v39 row_shr:1 row_mask:0xf bank_mask:0xf bound_ctrl:1
	v_fmac_f32_e32 v39, 0x3d800000, v38
	s_nop 1
	v_add_f32_dpp v39, v39, v39 row_shr:2 row_mask:0xf bank_mask:0xf bound_ctrl:1
	s_nop 1
	v_add_f32_dpp v39, v39, v39 row_shr:4 row_mask:0xf bank_mask:0xf bound_ctrl:1
	s_nop 1
	v_add_f32_dpp v39, v39, v39 row_shr:8 row_mask:0xf bank_mask:0xf bound_ctrl:1
	s_nop 1
	v_mov_b32_dpp v40, v39 row_bcast:15 row_mask:0xa bank_mask:0xf
; __device__ __forceinline__ float wave_incl_scan(float v) {
;     v += __builtin_bit_cast(float, __builtin_amdgcn_update_dpp(0, __builtin_bit_cast(int, v), 0x111, 0xf, 0xf, true));
;     v += __builtin_bit_cast(float, __builtin_amdgcn_update_dpp(0, __builtin_bit_cast(int, v), 0x112, 0xf, 0xf, true));
;     v += __builtin_bit_cast(float, __builtin_amdgcn_update_dpp(0, __builtin_bit_cast(int, v), 0x114, 0xf, 0xf, true));
;     v += __builtin_bit_cast(float, __builtin_amdgcn_update_dpp(0, __builtin_bit_cast(int, v), 0x118, 0xf, 0xf, true));
;     v += __builtin_bit_cast(float, __builtin_amdgcn_update_dpp(0, __builtin_bit_cast(int, v), 0x142, 0xa, 0xf, false));
;     v += __builtin_bit_cast(float, __builtin_amdgcn_update_dpp(0, __builtin_bit_cast(int, v), 0x143, 0xc, 0xf, false));
;     return v;
; template <bool PHC>
; __device__ __forceinline__ void gla_pair(const KPD& kp, int l, int pair, unsigned char* lds, int tid, int lane, int wave, v4u& pz0, v4u& pz1, v4u& pw0, v4u& pw1, int next_pair) {
;     ...
;     for (int c = 0; c < 24; ++c) {
;         float pre = __int_as_float(__builtin_amdgcn_readlane(bvv, c));
; #pragma unroll
;         for (int r = 0; r < 16; ++r) pre += z[r] * __int_as_float(__builtin_amdgcn_readlane(wvv[(24 * r + c) >> 6], (24 * r + c) & 63));
;         const float la = (fminf(pre, 0.f) - __logf(1.f + __expf(-fabsf(pre)))) * (1.f / 16.f);
;         const float inc = wave_incl_scan(la);
;         const float total = __int_as_float(__builtin_amdgcn_readlane(__float_as_int(inc), 63));
;         bc[c] = dir ? (total - inc + la) : inc; tot[c] = total;
	v_add_f32_e32 v39, v39, v40
	v_mov_b32_e32 v40, v35
	s_nop 0
	v_mov_b32_dpp v40, v39 row_bcast:31 row_mask:0xc bank_mask:0xf
	v_add_f32_e32 v39, v39, v40
	s_nop 0
	v_readlane_b32 s65, v39, 63
	s_nop 1
	v_sub_f32_e32 v40, s65, v39
	v_fmac_f32_e32 v40, 0x3d800000, v38
	v_cndmask_b32_e64 v99, v40, v39, s[0:1]
	global_store_dword v251, v99, s[100:101] offset:512
	v_mov_b32_e32 v38, v171
	v_min_f32_e32 v39, 0, v38
	v_mul_f32_e64 v38, |v38|, s72
	v_exp_f32_e32 v38, v38
	s_nop 0
	v_add_f32_e32 v38, 1.0, v38
	v_cmp_gt_f32_e32 vcc, s78, v38
	s_nop 1
	v_cndmask_b32_e64 v40, 0, 32, vcc
	v_ldexp_f32 v38, v38, v40
	v_log_f32_e32 v38, v38
	s_nop 0
	v_mul_f32_e32 v40, 0x3f317217, v38
	v_fma_f32 v40, v38, s87, -v40
	v_fmac_f32_e32 v40, 0x3377d1cf, v38
	v_fmac_f32_e32 v40, 0x3f317217, v38
	v_cmp_lt_f32_e64 s[10:11], |v38|, s97
	s_nop 1
	v_cndmask_b32_e64 v38, v38, v40, s[10:11]
	v_cndmask_b32_e32 v40, 0, v222, vcc
	v_sub_f32_e32 v38, v38, v40
	v_sub_f32_e32 v38, v39, v38
	v_mul_f32_e32 v39, 0x3d800000, v38
	v_mov_b32_e32 v40, v35
	s_nop 0
	v_mov_b32_dpp v39, v39 row_shr:1 row_mask:0xf bank_mask:0xf bound_ctrl:1
	v_fmac_f32_e32 v39, 0x3d800000, v38
	s_nop 1
	v_add_f32_dpp v39, v39, v39 row_shr:2 row_mask:0xf bank_mask:0xf bound_ctrl:1
	s_nop 1
	v_add_f32_dpp v39, v39, v39 row_shr:4 row_mask:0xf bank_mask:0xf bound_ctrl:1
	s_nop 1
	v_add_f32_dpp v39, v39, v39 row_shr:8 row_mask:0xf bank_mask:0xf bound_ctrl:1
	s_nop 1
	v_mov_b32_dpp v40, v39 row_bcast:15 row_mask:0xa bank_mask:0xf
	v_add_f32_e32 v39, v39, v40
	v_mov_b32_e32 v40, v35
	s_nop 0
	v_mov_b32_dpp v40, v39 row_bcast:31 row_mask:0xc bank_mask:0xf
	v_add_f32_e32 v39, v39, v40
	s_nop 0
	v_readlane_b32 s66, v39, 63
	s_nop 1
	v_sub_f32_e32 v40, s66, v39
	v_fmac_f32_e32 v40, 0x3d800000, v38
	v_cndmask_b32_e64 v100, v40, v39, s[0:1]
	global_store_dword v251, v100, s[100:101] offset:768
	v_mov_b32_e32 v38, v234
	v_min_f32_e32 v39, 0, v38
	v_mul_f32_e64 v38, |v38|, s72
	v_exp_f32_e32 v38, v38
	s_nop 0
	v_add_f32_e32 v38, 1.0, v38
	v_cmp_gt_f32_e32 vcc, s78, v38
	s_nop 1
	v_cndmask_b32_e64 v40, 0, 32, vcc
	v_ldexp_f32 v38, v38, v40
	v_log_f32_e32 v38, v38
	s_nop 0
	v_mul_f32_e32 v40, 0x3f317217, v38
	v_fma_f32 v40, v38, s87, -v40
	v_fmac_f32_e32 v40, 0x3377d1cf, v38
	v_fmac_f32_e32 v40, 0x3f317217, v38
	v_cmp_lt_f32_e64 s[10:11], |v38|, s97
	s_nop 1
	v_cndmask_b32_e64 v38, v38, v40, s[10:11]
	v_cndmask_b32_e32 v40, 0, v222, vcc
	v_sub_f32_e32 v38, v38, v40
	v_sub_f32_e32 v38, v39, v38
	v_mul_f32_e32 v39, 0x3d800000, v38
	v_mov_b32_e32 v40, v35
	s_nop 0
	v_mov_b32_dpp v39, v39 row_shr:1 row_mask:0xf bank_mask:0xf bound_ctrl:1
	v_fmac_f32_e32 v39, 0x3d800000, v38
	s_nop 1
	v_add_f32_dpp v39, v39, v39 row_shr:2 row_mask:0xf bank_mask:0xf bound_ctrl:1
	s_nop 1
	v_add_f32_dpp v39, v39, v39 row_shr:4 row_mask:0xf bank_mask:0xf bound_ctrl:1
	s_nop 1
	v_add_f32_dpp v39, v39, v39 row_shr:8 row_mask:0xf bank_mask:0xf bound_ctrl:1
	s_nop 1
	v_mov_b32_dpp v40, v39 row_bcast:15 row_mask:0xa bank_mask:0xf
	v_add_f32_e32 v39, v39, v40
	v_mov_b32_e32 v40, v35
	s_nop 0
	v_mov_b32_dpp v40, v39 row_bcast:31 row_mask:0xc bank_mask:0xf
	v_add_f32_e32 v39, v39, v40
	s_nop 0
	v_readlane_b32 s67, v39, 63
	s_nop 1
	v_sub_f32_e32 v40, s67, v39
	v_fmac_f32_e32 v40, 0x3d800000, v38
	v_readlane_b32 s3, v31, 61
	v_cndmask_b32_e64 v101, v40, v39, s[0:1]
	global_store_dword v251, v101, s[100:101] offset:1024
	v_readlane_b32 s2, v31, 37
	s_nop 1
	v_pk_mul_f32 v[102:103], v[50:51], s[2:3]
	v_mov_b32_e32 v38, v235
	v_min_f32_e32 v39, 0, v38
	v_mul_f32_e64 v38, |v38|, s72
	v_exp_f32_e32 v38, v38
	s_nop 0
	v_add_f32_e32 v38, 1.0, v38
	v_cmp_gt_f32_e32 vcc, s78, v38
	s_nop 1
	v_cndmask_b32_e64 v40, 0, 32, vcc
	v_ldexp_f32 v38, v38, v40
	v_log_f32_e32 v38, v38
	s_nop 0
	v_mul_f32_e32 v40, 0x3f317217, v38
	v_fma_f32 v40, v38, s87, -v40
	v_fmac_f32_e32 v40, 0x3377d1cf, v38
	v_fmac_f32_e32 v40, 0x3f317217, v38
	v_cmp_lt_f32_e64 s[10:11], |v38|, s97
	s_nop 1
	v_cndmask_b32_e64 v38, v38, v40, s[10:11]
	v_cndmask_b32_e32 v40, 0, v222, vcc
	v_sub_f32_e32 v38, v38, v40
	v_sub_f32_e32 v38, v39, v38
	v_mul_f32_e32 v39, 0x3d800000, v38
	v_mov_b32_e32 v40, v35
	s_nop 0
	v_mov_b32_dpp v39, v39 row_shr:1 row_mask:0xf bank_mask:0xf bound_ctrl:1
	v_fmac_f32_e32 v39, 0x3d800000, v38
	s_nop 1
	v_add_f32_dpp v39, v39, v39 row_shr:2 row_mask:0xf bank_mask:0xf bound_ctrl:1
	s_nop 1
	v_add_f32_dpp v39, v39, v39 row_shr:4 row_mask:0xf bank_mask:0xf bound_ctrl:1
	s_nop 1
	v_add_f32_dpp v39, v39, v39 row_shr:8 row_mask:0xf bank_mask:0xf bound_ctrl:1
	s_nop 1
	v_mov_b32_dpp v40, v39 row_bcast:15 row_mask:0xa bank_mask:0xf
	v_add_f32_e32 v39, v39, v40
	v_mov_b32_e32 v40, v35
	s_nop 0
	v_mov_b32_dpp v40, v39 row_bcast:31 row_mask:0xc bank_mask:0xf
	v_add_f32_e32 v39, v39, v40
	s_nop 0
	v_readlane_b32 s68, v39, 63
	s_nop 1
	v_sub_f32_e32 v40, s68, v39
	v_fmac_f32_e32 v40, 0x3d800000, v38
	v_readlane_b32 s3, v31, 62
	v_cndmask_b32_e64 v102, v40, v39, s[0:1]
	global_store_dword v251, v102, s[100:101] offset:1280
	v_readlane_b32 s2, v31, 38
	s_nop 1
	v_pk_mul_f32 v[104:105], v[50:51], s[2:3]
	v_mov_b32_e32 v38, v236
	v_min_f32_e32 v39, 0, v38
	v_mul_f32_e64 v38, |v38|, s72
	v_exp_f32_e32 v38, v38
	s_nop 0
	v_add_f32_e32 v38, 1.0, v38
	v_cmp_gt_f32_e32 vcc, s78, v38
	s_nop 1
	v_cndmask_b32_e64 v40, 0, 32, vcc
	v_ldexp_f32 v38, v38, v40
	v_log_f32_e32 v38, v38
	s_nop 0
	v_mul_f32_e32 v40, 0x3f317217, v38
	v_fma_f32 v40, v38, s87, -v40
	v_fmac_f32_e32 v40, 0x3377d1cf, v38
	v_fmac_f32_e32 v40, 0x3f317217, v38
	v_cmp_lt_f32_e64 s[10:11], |v38|, s97
	s_nop 1
	v_cndmask_b32_e64 v38, v38, v40, s[10:11]
	v_cndmask_b32_e32 v40, 0, v222, vcc
	v_sub_f32_e32 v38, v38, v40
; __device__ __forceinline__ unsigned pk2(float lo, float hi) { return cvtpk(lo, hi); }
; __device__ __forceinline__ float lo16(unsigned w) { return __uint_as_float(w << 16); }
; __device__ __forceinline__ float hi16(unsigned w) { return __uint_as_float(w & 0xffff0000u); }
; template <bool PHC>
; __device__ __forceinline__ void gla_pair(const KPD& kp, int l, int pair, unsigned char* lds, int tid, int lane, int wave, v4u& pz0, v4u& pz1, v4u& pw0, v4u& pw1, int next_pair) {
;     ...
;     for (int c = 0; c < 24; ++c) {
;         float pre = __int_as_float(__builtin_amdgcn_readlane(bvv, c));
; #pragma unroll
;         for (int r = 0; r < 16; ++r) pre += z[r] * __int_as_float(__builtin_amdgcn_readlane(wvv[(24 * r + c) >> 6], (24 * r + c) & 63));
;         const float la = (fminf(pre, 0.f) - __logf(1.f + __expf(-fabsf(pre)))) * (1.f / 16.f);
;         const float inc = wave_incl_scan(la);
;         const float total = __int_as_float(__builtin_amdgcn_readlane(__float_as_int(inc), 63));
;         bc[c] = dir ? (total - inc + la) : inc; tot[c] = total;
;     }
;     float qv[24], kv[24];
; #pragma unroll
;     for (int i = 0; i < 3; ++i) {
;         qv[8 * i] = lo16(qraw[i].x); qv[8 * i + 1] = hi16(qraw[i].x); qv[8 * i + 2] = lo16(qraw[i].y); qv[8 * i + 3] = hi16(qraw[i].y);
;         qv[8 * i + 4] = lo16(qraw[i].z); qv[8 * i + 5] = hi16(qraw[i].z); qv[8 * i + 6] = lo16(qraw[i].w); qv[8 * i + 7] = hi16(qraw[i].w);
;         kv[8 * i] = lo16(kraw[i].x); kv[8 * i + 1] = hi16(kraw[i].x); kv[8 * i + 2] = lo16(kraw[i].y); kv[8 * i + 3] = hi16(kraw[i].y);
;         kv[8 * i + 4] = lo16(kraw[i].z); kv[8 * i + 5] = hi16(kraw[i].z); kv[8 * i + 6] = lo16(kraw[i].w); kv[8 * i + 7] = hi16(kraw[i].w); }
;     const size_t stbase = (size_t)((dir * 4 + b) * NCH + n);
;     if constexpr (!PHC) {
;         bf16* Vr = (bf16*)L;
;         bf16* KE = (bf16*)(L + 13312);
;         { unsigned kw[12];
; #pragma unroll
;           for (int i = 0; i < 12; ++i) kw[i] = pk2(kv[2 * i] * __expf(tot[2 * i] - bc[2 * i]), kv[2 * i + 1] * __expf(tot[2 * i + 1] - bc[2 * i + 1]));
;           v4u* ko = (v4u*)(KE + (dir * 64 + lane) * 56 + d0);
; #pragma unroll
;           for (int i = 0; i < 3; ++i) ko[i] = (v4u){kw[4 * i], kw[4 * i + 1], kw[4 * i + 2], kw[4 * i + 3]}; }
	v_sub_f32_e32 v38, v39, v38
	v_mul_f32_e32 v39, 0x3d800000, v38
	v_mov_b32_e32 v40, v35
	s_nop 0
	v_mov_b32_dpp v39, v39 row_shr:1 row_mask:0xf bank_mask:0xf bound_ctrl:1
	v_fmac_f32_e32 v39, 0x3d800000, v38
	s_nop 1
	v_add_f32_dpp v39, v39, v39 row_shr:2 row_mask:0xf bank_mask:0xf bound_ctrl:1
	s_nop 1
	v_add_f32_dpp v39, v39, v39 row_shr:4 row_mask:0xf bank_mask:0xf bound_ctrl:1
	s_nop 1
	v_add_f32_dpp v39, v39, v39 row_shr:8 row_mask:0xf bank_mask:0xf bound_ctrl:1
	s_nop 1
	v_mov_b32_dpp v40, v39 row_bcast:15 row_mask:0xa bank_mask:0xf
	v_add_f32_e32 v39, v39, v40
	v_mov_b32_e32 v40, v35
	s_nop 0
	v_mov_b32_dpp v40, v39 row_bcast:31 row_mask:0xc bank_mask:0xf
	v_add_f32_e32 v39, v39, v40
	s_nop 0
	v_readlane_b32 s69, v39, 63
	s_nop 1
	v_sub_f32_e32 v40, s69, v39
	v_fmac_f32_e32 v40, 0x3d800000, v38
	v_cndmask_b32_e64 v38, v40, v39, s[0:1]
	global_store_dword v251, v38, s[100:101] offset:1536
	v_sub_f32_e32 v38, s69, v38
	v_mul_f32_e32 v38, 0x3fb8aa3b, v38
	v_exp_f32_e32 v38, v38
	v_and_b32_e32 v62, 0xffff0000, v17
	v_lshlrev_b32_e32 v61, 16, v17
	v_sub_f32_e32 v17, s29, v79
	v_and_b32_e32 v60, 0xffff0000, v16
	v_mul_f32_e32 v17, 0x3fb8aa3b, v17
	v_lshlrev_b32_e32 v59, 16, v16
	v_sub_f32_e32 v16, s30, v68
	v_and_b32_e32 v58, 0xffff0000, v15
	v_mul_f32_e32 v16, 0x3fb8aa3b, v16
	v_lshlrev_b32_e32 v57, 16, v15
	v_sub_f32_e32 v15, s36, v66
	v_and_b32_e32 v56, 0xffff0000, v14
	v_mul_f32_e32 v15, 0x3fb8aa3b, v15
	v_lshlrev_b32_e32 v55, 16, v14
	v_sub_f32_e32 v14, s54, v65
	v_mul_f32_e32 v14, 0x3fb8aa3b, v14
	v_exp_f32_e32 v14, v14
	v_exp_f32_e32 v15, v15
	v_exp_f32_e32 v16, v16
	v_exp_f32_e32 v17, v17
	v_lshlrev_b32_e32 v52, 16, v43
	v_and_b32_e32 v43, 0xffff0000, v43
	v_lshlrev_b32_e32 v53, 16, v44
	v_and_b32_e32 v44, 0xffff0000, v44
	v_mov_b32_e32 v34, v237
	v_min_f32_e32 v39, 0, v34
	v_mul_f32_e64 v34, |v34|, s72
	v_exp_f32_e32 v34, v34
	v_lshlrev_b32_e32 v50, 16, v49
	v_and_b32_e32 v49, 0xffff0000, v49
	v_lshlrev_b32_e32 v51, 16, v42
	v_add_f32_e32 v34, 1.0, v34
	v_cmp_gt_f32_e32 vcc, s78, v34
	v_and_b32_e32 v42, 0xffff0000, v42
	v_lshlrev_b32_e32 v54, 16, v45
	v_cndmask_b32_e64 v40, 0, 32, vcc
	v_ldexp_f32 v34, v34, v40
	v_log_f32_e32 v34, v34
	v_and_b32_e32 v45, 0xffff0000, v45
	s_add_i32 s2, s52, s41
	s_mulk_i32 s2, 0x84
	v_mul_f32_e32 v40, 0x3f317217, v34
	v_fma_f32 v40, v34, s87, -v40
	v_fmac_f32_e32 v40, 0x3377d1cf, v34
	v_fmac_f32_e32 v40, 0x3f317217, v34
	v_cmp_lt_f32_e64 s[10:11], |v34|, s97
	s_add_i32 s2, s2, s53
	s_ashr_i32 s3, s2, 31
	v_cndmask_b32_e64 v34, v34, v40, s[10:11]
	v_cndmask_b32_e32 v40, 0, v222, vcc
	v_sub_f32_e32 v34, v34, v40
	v_sub_f32_e32 v34, v39, v34
	v_mul_f32_e32 v39, 0x3d800000, v34
	v_mov_b32_e32 v40, v35
	v_mul_f32_e32 v38, v38, v61
	v_mov_b32_dpp v39, v39 row_shr:1 row_mask:0xf bank_mask:0xf bound_ctrl:1
	v_fmac_f32_e32 v39, 0x3d800000, v34
	s_nop 1
	v_add_f32_dpp v39, v39, v39 row_shr:2 row_mask:0xf bank_mask:0xf bound_ctrl:1
	s_nop 1
	v_add_f32_dpp v39, v39, v39 row_shr:4 row_mask:0xf bank_mask:0xf bound_ctrl:1
	s_nop 1
	v_add_f32_dpp v39, v39, v39 row_shr:8 row_mask:0xf bank_mask:0xf bound_ctrl:1
	s_nop 1
	v_mov_b32_dpp v40, v39 row_bcast:15 row_mask:0xa bank_mask:0xf
	v_add_f32_e32 v39, v39, v40
	v_mov_b32_e32 v40, v35
	s_nop 0
	v_mov_b32_dpp v40, v39 row_bcast:31 row_mask:0xc bank_mask:0xf
	v_add_f32_e32 v39, v39, v40
	s_nop 0
	v_readlane_b32 s72, v39, 63
	s_nop 1
	v_sub_f32_e32 v40, s72, v39
	v_fmac_f32_e32 v40, 0x3d800000, v34
	v_cndmask_b32_e64 v34, v40, v39, s[0:1]
	global_store_dword v251, v34, s[100:101] offset:1792
	v_lshlrev_b32_e32 v39, 16, v46
	v_and_b32_e32 v40, 0xffff0000, v46
	v_mul_f32_e32 v14, v14, v39
	v_mul_f32_e32 v15, v15, v40
	v_cvt_pk_bf16_f32 v14, v14, v15
	v_sub_f32_e32 v15, s34, v67
	v_mul_f32_e32 v15, 0x3fb8aa3b, v15
	v_exp_f32_e32 v15, v15
	v_and_b32_e32 v46, 0xffff0000, v47
	v_mul_f32_e32 v16, v16, v46
	v_lshlrev_b32_e32 v47, 16, v48
	v_mul_f32_e32 v15, v15, v41
	v_cvt_pk_bf16_f32 v15, v15, v16
	v_sub_f32_e32 v16, s28, v69
	v_mul_f32_e32 v16, 0x3fb8aa3b, v16
	v_exp_f32_e32 v16, v16
	v_and_b32_e32 v48, 0xffff0000, v48
	v_mul_f32_e32 v17, v17, v48
	v_sub_f32_e32 v39, s35, v83
	v_mul_f32_e32 v16, v16, v47
	v_cvt_pk_bf16_f32 v16, v16, v17
	v_sub_f32_e32 v17, s31, v81
	v_mul_f32_e32 v17, 0x3fb8aa3b, v17
	v_mul_f32_e32 v39, 0x3fb8aa3b, v39
	v_exp_f32_e32 v17, v17
	v_exp_f32_e32 v39, v39
	v_sub_f32_e32 v40, s55, v87
	v_mul_f32_e32 v40, 0x3fb8aa3b, v40
	v_mul_f32_e32 v17, v17, v50
	v_mul_f32_e32 v39, v39, v49
	v_cvt_pk_bf16_f32 v17, v17, v39
	v_sub_f32_e32 v39, s37, v85
	v_mul_f32_e32 v39, 0x3fb8aa3b, v39
	v_exp_f32_e32 v39, v39
	v_exp_f32_e32 v40, v40
	v_sub_f32_e32 v34, s72, v34
	v_mul_f32_e32 v34, 0x3fb8aa3b, v34
	v_mul_f32_e32 v39, v39, v51
	v_mul_f32_e32 v40, v40, v42
	v_cvt_pk_bf16_f32 v42, v39, v40
	v_sub_f32_e32 v39, s56, v89
	v_sub_f32_e32 v40, s57, v91
	v_mul_f32_e32 v39, 0x3fb8aa3b, v39
	v_mul_f32_e32 v40, 0x3fb8aa3b, v40
	v_exp_f32_e32 v39, v39
	v_exp_f32_e32 v40, v40
	v_exp_f32_e32 v34, v34
	v_mul_f32_e32 v39, v39, v52
	v_mul_f32_e32 v40, v40, v43
	v_cvt_pk_bf16_f32 v43, v39, v40
	v_sub_f32_e32 v39, s59, v93
	v_sub_f32_e32 v40, s60, v94
	v_mul_f32_e32 v39, 0x3fb8aa3b, v39
	v_mul_f32_e32 v40, 0x3fb8aa3b, v40
	v_exp_f32_e32 v39, v39
	v_exp_f32_e32 v40, v40
	v_mul_f32_e32 v34, v34, v62
	v_cvt_pk_bf16_f32 v49, v38, v34
	v_mul_f32_e32 v39, v39, v53
	v_mul_f32_e32 v40, v40, v44
	v_cvt_pk_bf16_f32 v44, v39, v40
	v_sub_f32_e32 v39, s61, v95
	v_sub_f32_e32 v40, s62, v96
	v_mul_f32_e32 v39, 0x3fb8aa3b, v39
	v_mul_f32_e32 v40, 0x3fb8aa3b, v40
	v_exp_f32_e32 v39, v39
	v_exp_f32_e32 v40, v40
	v_mul_f32_e32 v39, v39, v54
	v_mul_f32_e32 v40, v40, v45
	v_cvt_pk_bf16_f32 v45, v39, v40
	v_sub_f32_e32 v39, s63, v97
	v_sub_f32_e32 v40, s64, v98
	v_mul_f32_e32 v39, 0x3fb8aa3b, v39
	v_mul_f32_e32 v40, 0x3fb8aa3b, v40
	v_exp_f32_e32 v39, v39
	v_exp_f32_e32 v40, v40
	v_mul_f32_e32 v39, v39, v55
	v_mul_f32_e32 v40, v40, v56
	v_cvt_pk_bf16_f32 v46, v39, v40
	v_sub_f32_e32 v39, s65, v99
	v_sub_f32_e32 v40, s66, v100
	v_mul_f32_e32 v39, 0x3fb8aa3b, v39
	v_mul_f32_e32 v40, 0x3fb8aa3b, v40
	v_exp_f32_e32 v39, v39
	v_exp_f32_e32 v40, v40
	v_mul_f32_e32 v39, v39, v57
	v_mul_f32_e32 v40, v40, v58
	v_cvt_pk_bf16_f32 v47, v39, v40
	v_sub_f32_e32 v39, s67, v101
	v_sub_f32_e32 v40, s68, v102
	v_mul_f32_e32 v39, 0x3fb8aa3b, v39
	v_mul_f32_e32 v40, 0x3fb8aa3b, v40
	v_exp_f32_e32 v39, v39
	v_exp_f32_e32 v40, v40
	v_mul_f32_e32 v39, v39, v59
	v_mul_f32_e32 v40, v40, v60
	v_cvt_pk_bf16_f32 v48, v39, v40
	ds_write_b128 v122, v[14:17] offset:13312
	ds_write_b128 v122, v[42:45] offset:13328
	ds_write_b128 v122, v[46:49] offset:13344
	s_and_saveexec_b64 s[10:11], s[4:5]
	s_cbranch_execz .LBB0_266
; template <bool PHC>
; __device__ __forceinline__ void gla_pair(const KPD& kp, int l, int pair, unsigned char* lds, int tid, int lane, int wave, v4u& pz0, v4u& pz1, v4u& pw0, v4u& pw1, int next_pair) {
;     ...
;         if (lane == 0) {
; #pragma unroll
;             for (int c = 0; c < 24; ++c) DEC[stbase * 192 + h * 48 + d0 + c] = __expf(tot[c]);
;         }
	s_mul_i32 s13, s2, 0x300
	s_mul_hi_i32 s12, s2, 0x300
	s_add_u32 s13, s50, s13
	s_addc_u32 s12, s49, s12
	s_lshl_b32 s49, s51, 2
	v_mul_f32_e32 v14, s54, v223
	v_mul_f32_e32 v15, s36, v223
	v_mul_f32_e32 v16, s34, v223
	v_mul_f32_e32 v17, s30, v223
	s_add_u32 s13, s13, s49
	v_exp_f32_e32 v14, v14
	v_exp_f32_e32 v15, v15
	v_exp_f32_e32 v16, v16
	v_exp_f32_e32 v17, v17
	s_addc_u32 s12, s12, 0
	s_lshl_b32 s49, s40, 2
	s_add_u32 s50, s13, s49
	s_addc_u32 s51, s12, 0
	v_mov_b32_e32 v34, 0x19b00000
	global_store_dwordx4 v34, v[14:17], s[50:51]
	s_add_u32 s12, s50, 0x19b00000
	s_addc_u32 s13, s51, 0
	v_mul_f32_e32 v14, s28, v223
	v_mul_f32_e32 v15, s29, v223
	v_mul_f32_e32 v16, s31, v223
	v_mul_f32_e32 v17, s35, v223
	v_exp_f32_e32 v14, v14
	v_exp_f32_e32 v15, v15
	v_exp_f32_e32 v16, v16
	v_exp_f32_e32 v17, v17
	global_store_dwordx4 v35, v[14:17], s[12:13] offset:16
	s_nop 1
	v_mul_f32_e32 v14, s37, v223
	v_mul_f32_e32 v15, s55, v223
	v_mul_f32_e32 v16, s56, v223
	v_mul_f32_e32 v17, s57, v223
	v_exp_f32_e32 v14, v14
	v_exp_f32_e32 v15, v15
	v_exp_f32_e32 v16, v16
	v_exp_f32_e32 v17, v17
	global_store_dwordx4 v35, v[14:17], s[12:13] offset:32
	s_nop 1
	v_mul_f32_e32 v14, s59, v223
	v_mul_f32_e32 v15, s60, v223
	v_mul_f32_e32 v16, s61, v223
	v_mul_f32_e32 v17, s62, v223
	v_exp_f32_e32 v14, v14
	v_exp_f32_e32 v15, v15
	v_exp_f32_e32 v16, v16
	v_exp_f32_e32 v17, v17
	global_store_dwordx4 v35, v[14:17], s[12:13] offset:48
	s_nop 1
	v_mul_f32_e32 v14, s63, v223
	v_mul_f32_e32 v15, s64, v223
	v_mul_f32_e32 v16, s65, v223
	v_mul_f32_e32 v17, s66, v223
	v_exp_f32_e32 v14, v14
	v_exp_f32_e32 v15, v15
	v_exp_f32_e32 v16, v16
	v_exp_f32_e32 v17, v17
	global_store_dwordx4 v35, v[14:17], s[12:13] offset:64
	s_nop 1
	v_mul_f32_e32 v14, s67, v223
	v_mul_f32_e32 v15, s68, v223
	v_mul_f32_e32 v16, s69, v223
	v_mul_f32_e32 v17, s72, v223
	v_exp_f32_e32 v14, v14
	v_exp_f32_e32 v15, v15
	v_exp_f32_e32 v16, v16
	v_exp_f32_e32 v17, v17
	global_store_dwordx4 v35, v[14:17], s[12:13] offset:80

;     __device__ __forceinline__ const float* in(int i) const { return (const float*)(const __attribute__((address_space(1))) float*)ld(i); }
;     __device__ __forceinline__ unsigned char* ws() const { return (unsigned char*)(__attribute__((address_space(1))) unsigned char*)ld(23); }
; __device__ __forceinline__ void gla_prefetch(v4u& pz0, v4u& pz1, v4u& pw0, v4u& pw1, const KPD& kp, int l, int pair, int lane, int wave) {
;     const int half = wave >> 2, w4 = wave & 3, item = 2 * pair + half, h = item & 3, sc = item >> 2; int b, n, rowbase; chunk_coords(sc, b, n, rowbase);
;     const int dir = w4 >> 1, d0 = 24 * (w4 & 1);
;     const bf16* prow = (const bf16*)(kp.ws() + WS_P) + (size_t)(rowbase + lane) * INP;
;     pz0 = *(const v4u*)(prow + (dir ? C_ZB : C_ZF)); pz1 = *(const v4u*)(prow + (dir ? C_ZB : C_ZF) + 8);
;     const float* W = kp.in(I_GWDEC) + (size_t)((l * 2 + dir) * 16) * 192 + h * 48 + d0;
;     const float* bias = kp.in(I_GBDEC) + (l * 2 + dir) * 192 + h * 48 + d0;
;     unsigned w[6];
; #pragma unroll
;     for (int i = 0; i < 6; ++i) { const int e = lane + 64 * i; w[i] = __float_as_uint(W[(e / 24) * 192 + (e % 24)]); }
;     pw0 = (v4u){w[0], w[1], w[2], w[3]}; pw1 = (v4u){w[4], w[5], __float_as_uint(bias[lane < 24 ? lane : 0]), 0u};
.LBB0_271:
	s_lshl_b32 s10, s13, 6
	s_add_i32 s10, s17, s10
	v_or_b32_e32 v4, s10, v120
	s_mov_b32 s17, s79
	s_waitcnt lgkmcnt(0)
	v_readlane_b32 s11, v255, 63
	v_readlane_b32 s13, v255, 62
	s_nop 0
	v_mov_b32_e32 v3, s11
	v_mov_b32_e32 v2, s13
	v_mad_i64_i32 v[2:3], s[10:11], v4, s33, v[2:3]
	v_lshl_add_u64 v[2:3], v[2:3], 0, s[16:17]
	s_mov_b64 s[10:11], 0x7800000
	v_lshl_add_u64 v[4:5], v[2:3], 0, s[10:11]
	s_mov_b32 s10, 0x7800000
	v_add_co_u32_e32 v2, vcc, s10, v2
	s_and_b32 s10, s12, 3
	s_nop 0
	v_addc_co_u32_e32 v3, vcc, 0, v3, vcc
	global_load_dwordx4 v[18:21], v[2:3], off
	global_load_dwordx4 v[22:25], v[4:5], off offset:16
	ds_read_b64 v[2:3], v207
	s_mul_i32 s13, s10, 0xc0
	s_waitcnt lgkmcnt(0)
	v_readfirstlane_b32 s12, v2
	v_readfirstlane_b32 s11, v3
	s_add_u32 s12, s12, s18
	s_addc_u32 s11, s11, s19
	ds_read_b64 v[2:3], v252
	s_add_u32 s10, s12, s13
	s_addc_u32 s11, s11, 0
	s_add_u32 s10, s10, s42
	s_addc_u32 s11, s11, 0
	global_load_dword v26, v142, s[10:11]
	global_load_dword v27, v143, s[10:11] offset:256
	global_load_dword v28, v144, s[10:11] offset:512
	global_load_dword v29, v145, s[10:11] offset:768
	global_load_dword v30, v146, s[10:11] offset:1024
	global_load_dword v31, v147, s[10:11] offset:1280
	s_waitcnt lgkmcnt(0)
	v_readfirstlane_b32 s11, v2
	v_readfirstlane_b32 s10, v3
	s_add_u32 s11, s11, s20
	s_addc_u32 s10, s10, s21
	s_add_u32 s11, s11, s13
	s_addc_u32 s12, s10, 0
	s_add_u32 s10, s11, s42
	s_addc_u32 s11, s12, 0
	global_load_dword v32, v148, s[10:11]

;     __device__ __forceinline__ unsigned char* ws() const { return (unsigned char*)(__attribute__((address_space(1))) unsigned char*)ld(23); }
; __device__ __forceinline__ void prep_pool_item(const KPD& kp, int l, int sc, unsigned char* lds, int tid, int lane, int wave) {
;     ...
;           *(v4u*)(prow_ + (hd < 6 ? C_AQ + hd * 64 : C_AK + (hd - 6) * 64)) = o; } }
;     if (isctx && l != 0) return;
;     bf16* AP = (bf16*)lds;
;     const bf16* WT = (const bf16*)(kp.ws() + WS_PWT) + (size_t)l * 4 * 64 * 64;
;     { const int t = tid >> 3, cgp = tid & 7, g = cgp >> 1, w2 = 1 << g  ; const int s = s0 + t;
;       const int lo = max(s - w2, 0), hi = min(s + w2, T);
;       const int cb = C_PU + g * 64 + (cgp & 1) * 32;
;       float acc[32];
; #pragma unroll
;       for (int i = 0; i < 32; ++i) acc[i] = 0.f;
;       for (int j = lo; j < hi; ++j) { const bf16* up = P + (size_t)(rowbase + j - s0) * INP + cb;
.LBB0_295:
	s_and_b64 s[10:11], s[14:15], s[28:29]
	s_and_b64 vcc, exec, s[10:11]
	v_cvt_pk_bf16_f32 v2, v2, v3
	v_cvt_pk_bf16_f32 v3, v4, v5
	v_cvt_pk_bf16_f32 v4, v6, v7
	v_cvt_pk_bf16_f32 v5, v8, v9
	global_store_dwordx4 v[106:107], v[2:5], off offset:3264
	s_cbranch_vccnz .LBB0_256
	s_add_i32 s12, s30, 0xffffe000
	s_and_b64 s[10:11], exec, s[28:29]
	s_cselect_b32 s28, s12, s30
	s_cselect_b32 s10, 0x100, s96
	s_waitcnt lgkmcnt(0)
	v_readlane_b32 s13, v255, 62
	v_add_u32_e32 v2, s28, v126
	v_readlane_b32 s12, v255, 63
	v_sub_u32_e32 v3, v2, v136
	v_add_u32_e32 v2, v2, v136
	v_max_i32_e32 v34, 0, v3
	v_min_i32_e32 v60, s10, v2
	v_mov_b32_e32 v57, 0
	v_cmp_gt_i32_e32 vcc, v60, v34
	v_mov_b32_e32 v56, v57
	v_mov_b32_e32 v55, v57
	v_mov_b32_e32 v54, v57
	v_mov_b32_e32 v53, v57
	v_mov_b32_e32 v52, v57
	v_mov_b32_e32 v51, v57
	v_mov_b32_e32 v50, v57
	v_mov_b32_e32 v49, v57
	v_mov_b32_e32 v48, v57
	v_mov_b32_e32 v47, v57
	v_mov_b32_e32 v46, v57
	v_mov_b32_e32 v45, v57
	v_mov_b32_e32 v44, v57
	v_mov_b32_e32 v43, v57
	v_mov_b32_e32 v42, v57
	v_mov_b32_e32 v17, v57
	v_mov_b32_e32 v16, v57
	v_mov_b32_e32 v15, v57
	v_mov_b32_e32 v14, v57
	v_mov_b32_e32 v13, v57
	v_mov_b32_e32 v12, v57
	v_mov_b32_e32 v11, v57
	v_mov_b32_e32 v10, v57
	v_mov_b32_e32 v9, v57
	v_mov_b32_e32 v8, v57
	v_mov_b32_e32 v7, v57
	v_mov_b32_e32 v6, v57
	v_mov_b32_e32 v5, v57
	v_mov_b32_e32 v4, v57
	v_mov_b32_e32 v3, v57
	v_mov_b32_e32 v2, v57
	s_and_saveexec_b64 s[10:11], vcc
	s_cbranch_execz .LBB0_255
	v_lshl_add_u64 v[2:3], s[2:3], 0, v[76:77]
	s_mov_b64 s[2:3], 0x7800030
	v_add_u32_e32 v4, s17, v34
	v_lshl_add_u64 v[2:3], v[2:3], 0, s[2:3]
	v_subrev_u32_e32 v4, s28, v4
	v_mad_i64_i32 v[58:59], s[2:3], v4, s33, v[2:3]
	v_mov_b32_e32 v2, 0
	s_mov_b64 s[2:3], 0
	v_mov_b32_e32 v61, v34
	v_mov_b32_e32 v3, v2
	v_mov_b32_e32 v4, v2
	v_mov_b32_e32 v5, v2
	v_mov_b32_e32 v6, v2
	v_mov_b32_e32 v7, v2
	v_mov_b32_e32 v8, v2
	v_mov_b32_e32 v9, v2
	v_mov_b32_e32 v10, v2
	v_mov_b32_e32 v11, v2
	v_mov_b32_e32 v12, v2
	v_mov_b32_e32 v13, v2
	v_mov_b32_e32 v14, v2
	v_mov_b32_e32 v15, v2
	v_mov_b32_e32 v16, v2
	v_mov_b32_e32 v17, v2
	v_mov_b32_e32 v42, v2
	v_mov_b32_e32 v43, v2
	v_mov_b32_e32 v44, v2
	v_mov_b32_e32 v45, v2
	v_mov_b32_e32 v46, v2
	v_mov_b32_e32 v47, v2
	v_mov_b32_e32 v48, v2
	v_mov_b32_e32 v49, v2
	v_mov_b32_e32 v50, v2
	v_mov_b32_e32 v51, v2
	v_mov_b32_e32 v52, v2
	v_mov_b32_e32 v53, v2
	v_mov_b32_e32 v54, v2
	v_mov_b32_e32 v55, v2
	v_mov_b32_e32 v56, v2
	v_mov_b32_e32 v57, v2

;     __device__ __forceinline__ unsigned char* ws() const { return (unsigned char*)(__attribute__((address_space(1))) unsigned char*)ld(23); }
; __device__ __forceinline__ void gla_scan(const KPD& kp, int tid) {
;     if (tid >= 288) return;
;     const int gid = blockIdx.x * 288 + tid;
;     if (gid >= 2 * 4 * 9216) return;
;     const int e2 = gid % 9216, db = gid / 9216, dir = db >> 2, elem = 2 * e2, h = elem / 4608, d = (elem % 4608) / 96;
;     const bf16* ST = (const bf16*)(kp.ws() + WS_ST) + (size_t)db * NCH * 18432 + elem;
;     bf16* SI = (bf16*)(kp.ws() + WS_SI) + (size_t)db * NCH * 18432 + elem;
;     const float* DEC = (const float*)(kp.ws() + WS_DEC) + (size_t)db * NCH * 192 + h * 48 + d;
;     f32x2 s = {0.f, 0.f};
.LBB0_352:
	s_or_b64 exec, exec, s[0:1]
	v_mov_b32_e32 v13, v225
	s_movk_i32 s0, 0x120
	s_waitcnt lgkmcnt(0)
	s_barrier
	s_nop 0
	v_readfirstlane_b32 s2, v13
	v_cmp_gt_i32_e32 vcc, s0, v13
	s_and_saveexec_b64 s[0:1], vcc
	s_cbranch_execz .LBB0_356
	s_mul_i32 s3, s73, 0x120
	v_add_u32_e32 v2, s3, v13
	s_mov_b32 s3, 0x12000
	v_cmp_gt_i32_e32 vcc, s3, v2
	s_and_b64 exec, exec, vcc
	s_cbranch_execz .LBB0_356
	s_mov_b32 s3, 0x38e38e39
	v_mul_hi_i32 v3, v2, s3
	v_lshrrev_b32_e32 v4, 31, v3
	v_ashrrev_i32_e32 v3, 11, v3
	v_add_u32_e32 v10, v3, v4
	v_mul_i32_i24_e32 v3, 0x2400, v10
	v_sub_u32_e32 v3, v2, v3
	v_lshlrev_b32_e32 v2, 1, v3
	v_mul_i32_i24_e32 v3, 0xe39, v3
	v_lshrrev_b32_e32 v4, 31, v3
	v_ashrrev_i32_e32 v3, 23, v3
	v_add_u16_e32 v8, v3, v4
	v_mul_i32_i24_e32 v3, 0xe39, v2
	v_lshrrev_b32_e32 v4, 31, v3
	v_add_u16_sdwa v3, v3, v4 dst_sel:DWORD dst_unused:UNUSED_PAD src0_sel:BYTE_3 src1_sel:DWORD
	v_mul_lo_u16_e32 v3, 0x1200, v3
	v_sub_u16_e32 v3, v2, v3
	s_movk_i32 s3, 0x2aab
	v_mul_i32_i24_sdwa v3, sext(v3), s3 dst_sel:DWORD dst_unused:UNUSED_PAD src0_sel:WORD_0 src1_sel:DWORD
	v_lshrrev_b32_e32 v4, 31, v3
	v_ashrrev_i32_e32 v3, 20, v3
	v_add_u16_e32 v11, v3, v4
	v_mul_i32_i24_e32 v9, 0x84, v10
	s_mov_b32 s6, 0x9000
	v_ashrrev_i32_e32 v3, 31, v2
	v_lshlrev_b64 v[6:7], 1, v[2:3]
	s_waitcnt lgkmcnt(0)
	v_readlane_b32 s3, v255, 63
	v_readlane_b32 s4, v255, 62
	v_mul_lo_u16_e32 v8, 48, v8
	v_mov_b32_e32 v5, s3
	v_mov_b32_e32 v4, s4
	v_mad_i64_i32 v[4:5], s[4:5], v9, s6, v[4:5]
	v_lshl_add_u64 v[2:3], v[4:5], 0, v[6:7]
	s_mov_b64 s[4:5], 0x15000000
	v_lshl_add_u64 v[2:3], v[2:3], 0, s[4:5]
	v_bfe_i32 v8, v8, 0, 16
	v_cmp_gt_u32_e32 vcc, 4, v10
	s_waitcnt lgkmcnt(0)
	v_readlane_b32 s3, v255, 63
	v_readlane_b32 s4, v255, 62
	s_nop 0
	v_mov_b32_e32 v5, s3
	v_mov_b32_e32 v4, s4
	v_mad_i64_i32 v[4:5], s[4:5], v9, s6, v[4:5]
	v_lshl_add_u64 v[4:5], v[4:5], 0, v[6:7]
	s_mov_b64 s[4:5], 0x1a000000
	v_lshl_add_u64 v[4:5], v[4:5], 0, s[4:5]
	s_waitcnt lgkmcnt(0)
	v_readlane_b32 s3, v255, 63
	v_readlane_b32 s4, v255, 62
	s_nop 0
	v_mov_b32_e32 v7, s3
	s_movk_i32 s3, 0x300
	v_mov_b32_e32 v6, s4
	v_mad_i64_i32 v[6:7], s[4:5], v9, s3, v[6:7]
	v_ashrrev_i32_e32 v9, 31, v8
	v_lshl_add_u64 v[6:7], v[8:9], 2, v[6:7]
	v_bfe_i32 v8, v11, 0, 16
	v_ashrrev_i32_e32 v9, 31, v8
	v_lshl_add_u64 v[6:7], v[8:9], 2, v[6:7]
	s_mov_b64 s[4:5], 0x19b00000
	v_mov_b32_e32 v8, 0
	v_lshl_add_u64 v[6:7], v[6:7], 0, s[4:5]
	s_mov_b32 s4, 0
	s_movk_i32 s3, 0x6e
	v_mov_b32_e32 v9, v8

; __device__ __forceinline__ float xor16_32_sum(float v) { float a = v, b = v; swap16(a, b); v = a + b; a = v; b = v; swap32(a, b); return a + b; }
;     __device__ __forceinline__ unsigned char* ws() const { return (unsigned char*)(__attribute__((address_space(1))) unsigned char*)ld(23); }
; __device__ __forceinline__ unsigned cvtpk(float lo, float hi) { unsigned r; asm("v_cvt_pk_bf16_f32 %0, %1, %2" : "=v"(r) : "v"(lo), "v"(hi)); return r; }
; __device__ __forceinline__ void swa_item(const KPD& kp, int l, int item, unsigned char* lds, int tid, int lane, int wave) {
;     ...
;     bf16* MIX = (bf16*)(kp.ws() + WS_MIX);
; #pragma unroll
;     for (int hh = 0; hh < 3; ++hh) { float lt = lrow[hh];
;         lt = pg8::xor16_32_sum(lt);
;         const float inv = 1.0f / lt;
;         bf16* o = MIX + (size_t)(qrow0 + 16 * wave + fr) * D + 384 + (kvh * 3 + hh) * 64 + 4 * fq;
; #pragma unroll
;         for (int dt = 0; dt < 4; ++dt) *(v2u*)(o + 16 * dt) = (v2u){cvtpk(O[hh][dt][0] * inv, O[hh][dt][1] * inv), cvtpk(O[hh][dt][2] * inv, O[hh][dt][3] * inv)}; }
.LBB0_358:
	v_lshlrev_b32_e32 v4, 1, v36
	v_mov_b32_e32 v5, v35
	s_add_i32 s14, s14, s84
	s_cmpk_gt_i32 s14, 0x1ff
	s_waitcnt lgkmcnt(0)
	v_readlane_b32 s5, v255, 63
	v_readlane_b32 s4, v255, 62
	v_lshlrev_b64 v[2:3], 11, v[168:169]
	s_nop 0
	v_lshl_add_u64 v[2:3], s[4:5], 0, v[2:3]
	v_lshl_add_u64 v[2:3], v[2:3], 0, v[4:5]
	v_mov_b32_e32 v4, v167
	v_nop
	v_nop
	v_permlane16_swap_b32 v167, v4
	v_lshl_add_u64 v[2:3], v[2:3], 0, s[78:79]
	v_add_f32_e32 v4, v167, v4
	v_mov_b32_e32 v5, v4
	v_nop
	v_nop
	v_permlane32_swap_b32 v4, v5
	s_nop 0
	v_add_f32_e32 v4, v4, v5
	v_div_scale_f32 v5, s[4:5], v4, v4, 1.0
	v_rcp_f32_e32 v6, v5
	s_mov_b64 s[4:5], 0x10e00300
	v_fma_f32 v7, -v5, v6, 1.0
	v_fmac_f32_e32 v6, v7, v6
	v_div_scale_f32 v7, vcc, 1.0, v4, 1.0
	v_mul_f32_e32 v8, v7, v6
	v_fma_f32 v9, -v5, v8, v7
	v_fmac_f32_e32 v8, v9, v6
	v_fma_f32 v5, -v5, v8, v7
	v_div_fmas_f32 v5, v5, v6, v8
	v_div_fixup_f32 v8, v5, v4, 1.0
	v_lshl_add_u64 v[4:5], v[2:3], 0, s[4:5]
	v_mul_f32_e32 v6, v106, v8
	v_mul_f32_e32 v7, v107, v8
	v_add_co_u32_e32 v2, vcc, s55, v2
	v_cvt_pk_bf16_f32 v6, v6, v7
	v_mul_f32_e32 v7, v108, v8
	s_nop 0
	v_addc_co_u32_e32 v3, vcc, 0, v3, vcc
	v_mul_f32_e32 v9, v109, v8
	v_cvt_pk_bf16_f32 v7, v7, v9
	global_store_dwordx2 v[2:3], v[6:7], off offset:768
	v_mul_f32_e32 v2, v110, v8
	v_mul_f32_e32 v3, v111, v8
	v_cvt_pk_bf16_f32 v2, v2, v3
	v_mul_f32_e32 v3, v112, v8
	v_mul_f32_e32 v6, v113, v8
	v_cvt_pk_bf16_f32 v3, v3, v6
	global_store_dwordx2 v[4:5], v[2:3], off offset:32
	v_mul_f32_e32 v2, v102, v8
	v_mul_f32_e32 v3, v103, v8
	v_cvt_pk_bf16_f32 v2, v2, v3
	v_mul_f32_e32 v3, v104, v8
	v_mul_f32_e32 v6, v105, v8
	v_cvt_pk_bf16_f32 v3, v3, v6
	global_store_dwordx2 v[4:5], v[2:3], off offset:64
	v_mul_f32_e32 v2, v98, v8
	v_mul_f32_e32 v3, v99, v8
	v_cvt_pk_bf16_f32 v2, v2, v3
	v_mul_f32_e32 v3, v100, v8
	v_mul_f32_e32 v6, v101, v8
	v_cvt_pk_bf16_f32 v3, v3, v6
	global_store_dwordx2 v[4:5], v[2:3], off offset:96
	v_mov_b32_e32 v2, v165
	v_nop
	v_nop
	v_permlane16_swap_b32 v165, v2
	s_nop 0
	v_add_f32_e32 v2, v165, v2
	v_mov_b32_e32 v3, v2
	v_nop
	v_nop
	v_permlane32_swap_b32 v2, v3
	s_nop 0
	v_add_f32_e32 v2, v2, v3
	v_div_scale_f32 v3, s[4:5], v2, v2, 1.0
	v_rcp_f32_e32 v6, v3
	s_nop 0
	v_fma_f32 v7, -v3, v6, 1.0
	v_fmac_f32_e32 v6, v7, v6
	v_div_scale_f32 v7, vcc, 1.0, v2, 1.0
	v_mul_f32_e32 v8, v7, v6
	v_fma_f32 v9, -v3, v8, v7
	v_fmac_f32_e32 v8, v9, v6
	v_fma_f32 v3, -v3, v8, v7
	v_div_fmas_f32 v3, v3, v6, v8
	v_div_fixup_f32 v6, v3, v2, 1.0
	v_mul_f32_e32 v2, v90, v6
	v_mul_f32_e32 v3, v91, v6
	v_cvt_pk_bf16_f32 v2, v2, v3
	v_mul_f32_e32 v3, v92, v6
	v_mul_f32_e32 v7, v93, v6
	v_cvt_pk_bf16_f32 v3, v3, v7
	global_store_dwordx2 v[4:5], v[2:3], off offset:128
	v_mul_f32_e32 v2, v94, v6
	v_mul_f32_e32 v3, v95, v6
	v_cvt_pk_bf16_f32 v2, v2, v3
	v_mul_f32_e32 v3, v96, v6
	v_mul_f32_e32 v7, v97, v6
	v_cvt_pk_bf16_f32 v3, v3, v7
	global_store_dwordx2 v[4:5], v[2:3], off offset:160
	v_mul_f32_e32 v2, v86, v6
	v_mul_f32_e32 v3, v87, v6
	v_cvt_pk_bf16_f32 v2, v2, v3
	v_mul_f32_e32 v3, v88, v6
	v_mul_f32_e32 v7, v89, v6
	v_cvt_pk_bf16_f32 v3, v3, v7
	global_store_dwordx2 v[4:5], v[2:3], off offset:192
	v_mul_f32_e32 v2, v82, v6
	v_mul_f32_e32 v3, v83, v6
	v_cvt_pk_bf16_f32 v2, v2, v3
	v_mul_f32_e32 v3, v84, v6
	v_mul_f32_e32 v6, v85, v6
	v_cvt_pk_bf16_f32 v3, v3, v6
	global_store_dwordx2 v[4:5], v[2:3], off offset:224
	v_mov_b32_e32 v2, v163
	v_nop
	v_nop
	v_permlane16_swap_b32 v163, v2
	s_nop 0
	v_add_f32_e32 v2, v163, v2
	v_mov_b32_e32 v3, v2
	v_nop
	v_nop
	v_permlane32_swap_b32 v2, v3
	s_nop 0
	v_add_f32_e32 v2, v2, v3
	v_div_scale_f32 v3, s[4:5], v2, v2, 1.0
	v_rcp_f32_e32 v6, v3
	s_nop 0
	v_fma_f32 v7, -v3, v6, 1.0
	v_fmac_f32_e32 v6, v7, v6
	v_div_scale_f32 v7, vcc, 1.0, v2, 1.0
	v_mul_f32_e32 v8, v7, v6
	v_fma_f32 v9, -v3, v8, v7
	v_fmac_f32_e32 v8, v9, v6
	v_fma_f32 v3, -v3, v8, v7
	v_div_fmas_f32 v3, v3, v6, v8
	v_div_fixup_f32 v6, v3, v2, 1.0
	v_mul_f32_e32 v2, v74, v6
	v_mul_f32_e32 v3, v75, v6
	v_cvt_pk_bf16_f32 v2, v2, v3
	v_mul_f32_e32 v3, v76, v6
	v_mul_f32_e32 v7, v77, v6
	v_cvt_pk_bf16_f32 v3, v3, v7
	global_store_dwordx2 v[4:5], v[2:3], off offset:256
	v_mul_f32_e32 v2, v78, v6
	v_mul_f32_e32 v3, v79, v6
	v_cvt_pk_bf16_f32 v2, v2, v3
	v_mul_f32_e32 v3, v80, v6
	v_mul_f32_e32 v7, v81, v6
	v_cvt_pk_bf16_f32 v3, v3, v7
	global_store_dwordx2 v[4:5], v[2:3], off offset:288
	v_mul_f32_e32 v2, v66, v6
	v_mul_f32_e32 v3, v67, v6
	v_cvt_pk_bf16_f32 v2, v2, v3
	v_mul_f32_e32 v3, v68, v6
	v_mul_f32_e32 v7, v69, v6
	v_cvt_pk_bf16_f32 v3, v3, v7
	global_store_dwordx2 v[4:5], v[2:3], off offset:320
	v_mul_f32_e32 v2, v70, v6
	v_mul_f32_e32 v3, v71, v6
	v_cvt_pk_bf16_f32 v2, v2, v3
	v_mul_f32_e32 v3, v72, v6
	v_mul_f32_e32 v6, v73, v6
	v_cvt_pk_bf16_f32 v3, v3, v6
	global_store_dwordx2 v[4:5], v[2:3], off offset:352
	s_barrier
	s_cbranch_scc1 .LBB0_393

;     __device__ __forceinline__ const float* in(int i) const { return (const float*)(const __attribute__((address_space(1))) float*)ld(i); }
; __device__ __forceinline__ void swa_item(const KPD& kp, int l, int item, unsigned char* lds, int tid, int lane, int wave) {
;     ...
;     if (!isctx) { kvh = item & 1; qblk = (item >> 1) & 63; b = item >> 7; qrow0 = b * SEQ + qblk * 128; }
;     else { const int j = item - 512; kvh = j & 1; qblk = (j >> 1) & 1; b = j >> 2; qrow0 = MLAT + b * CTXL + qblk * 128; }
;     const bf16* P = (const bf16*)(kp.ws() + WS_P);
;     bf16* Kt = (bf16*)lds;
;     bf16* Vs = (bf16*)(lds + 18432);
;     const int fr = lane & 15, fq = lane >> 4;
;     bf16x8 qf[3][2];
; #pragma unroll
;     for (int hh = 0; hh < 3; ++hh)
; #pragma unroll
;         for (int ks = 0; ks < 2; ++ks) qf[hh][ks] = *(const bf16x8*)(P + (size_t)(qrow0 + 16 * wave + fr) * INP + C_AQ + (kvh * 3 + hh) * 64 + 32 * ks + 8 * fq);
;     float mrow[3], lrow[3]; f32x4 O[3][4];
; #pragma unroll
;     for (int hh = 0; hh < 3; ++hh) { mrow[hh] = kp.in(I_SINK)[l * 6 + kvh * 3 + hh] * 1.4426950408889634f; lrow[hh] = (fq == 0) ? 1.f : 0.f;
; #pragma unroll
;         for (int dt = 0; dt < 4; ++dt) O[hh][dt] = (f32x4){0.f, 0.f, 0.f, 0.f}; }
;     int nt = 0; int krow[5]; int kmode[5];
; #pragma unroll
;     for (int kt = 0; kt < 5; ++kt) { krow[kt] = 0; kmode[kt] = 0; }
;     int t0 = 0;
;     if (!isctx) {
;         if (qblk > 0) { krow[0] = b * SEQ + (qblk - 1) * 128; kmode[0] = 1; t0 = 1; }
;     }
;     const bool hasprev = !isctx && qblk > 0, hascur = !isctx, hasnext = !isctx && qblk < 63;
;     const int s_prev = 0, s_next = hasprev ? 1 : 0, s_cur = s_next + (hasnext ? 1 : 0), s_c0 = s_cur + (hascur ? 1 : 0), s_c1 = s_c0 + 1;
;     nt = s_c1 + 1;
;     (void)t0; (void)s_prev;
;     auto tile_row = [&](int i) -> int {
;         if (hasprev && i == 0) return b * SEQ + (qblk - 1) * 128;
;         if (hasnext && i == s_next) return b * SEQ + (qblk + 1) * 128;
;         if (hascur && i == s_cur) return b * SEQ + qblk * 128;
;         if (i == s_c0) return MLAT + b * CTXL;
;         return MLAT + b * CTXL + 128; };
;     auto tile_mode = [&](int i) -> int { if (hasprev && i == 0) return 1; if (hasnext && i == s_next) return 2; return 0; };
;     v4u kpre[4], vpre2[4];
;     const int nstage = (nt + 1) >> 1;
.LBB0_363:
	s_and_b32 s21, s8, 1
	v_add_u32_e32 v168, s9, v174
	v_readlane_b32 s10, v254, 27
	v_readlane_b32 s11, v254, 28
	s_waitcnt lgkmcnt(0)
	v_readlane_b32 s4, v255, 62
	v_readlane_b32 s5, v255, 63
	s_add_u32 s4, s4, 0x7800000
	s_addc_u32 s5, s5, 0
	v_mov_b64_e32 v[2:3], s[4:5]
	v_mad_i64_i32 v[2:3], s[8:9], v168, s33, v[2:3]
	s_mul_i32 s8, s21, 0xc0
	v_lshl_add_u64 v[2:3], v[2:3], 0, v[34:35]
	s_lshl_b32 s78, s8, 1
	s_waitcnt vmcnt(7)
	v_lshl_add_u64 v[22:23], v[2:3], 0, s[78:79]
	global_load_dwordx4 v[2:5], v[22:23], off offset:2368
	global_load_dwordx4 v[6:9], v[22:23], off offset:2432
	global_load_dwordx4 v[10:13], v[22:23], off offset:2496
	global_load_dwordx4 v[14:17], v[22:23], off offset:2560
	global_load_dwordx4 v[18:21], v[22:23], off offset:2624
	s_nop 0
	global_load_dwordx4 v[22:25], v[22:23], off offset:2688
	s_waitcnt vmcnt(11)
	ds_read_b64 v[26:27], v215
	s_mul_i32 s8, s21, 3
	s_mul_i32 s9, s10, 6
	s_add_i32 s8, s8, s9
	s_mov_b32 s9, s79
	s_waitcnt lgkmcnt(0)
	v_readfirstlane_b32 s10, v26
	s_lshl_b64 s[8:9], s[8:9], 2
	v_readfirstlane_b32 s11, v27
	s_add_u32 s10, s10, s8
	s_addc_u32 s11, s11, s9
	v_mov_b32_e32 v167, v35
	s_nop 1
	global_load_dword v68, v35, s[10:11]
	ds_read_b64 v[26:27], v215
	s_waitcnt lgkmcnt(0)
	v_readfirstlane_b32 s10, v26
	v_readfirstlane_b32 s11, v27
	s_add_u32 s10, s10, s8
	s_addc_u32 s11, s11, s9
	s_nop 2
	global_load_dword v67, v35, s[10:11] offset:4
	ds_read_b64 v[26:27], v215
	s_waitcnt lgkmcnt(0)
	v_readfirstlane_b32 s11, v26
	v_readfirstlane_b32 s10, v27
	s_add_u32 s8, s11, s8
	s_addc_u32 s9, s10, s9
	s_cmp_lg_u32 s12, 0
	global_load_dword v66, v35, s[8:9] offset:8
	s_cselect_b64 s[8:9], -1, 0
	s_and_b64 s[8:9], s[6:7], s[8:9]
	s_cmp_lg_u32 s12, 63
	s_cselect_b64 s[10:11], -1, 0
	v_cndmask_b32_e64 v26, 0, 1, s[8:9]
	s_and_b64 s[10:11], s[6:7], s[10:11]
	v_readfirstlane_b32 s17, v26
	v_cndmask_b32_e64 v26, 0, 1, s[10:11]
	s_lshl_b32 s21, s21, 7
	v_readfirstlane_b32 s18, v26
	v_cndmask_b32_e64 v26, 0, 1, s[6:7]
	s_add_i32 s18, s17, s18
	v_readfirstlane_b32 s19, v26
	s_add_i32 s19, s18, s19
	s_add_u32 s4, s4, s21
	s_addc_u32 s5, s5, 0
	v_lshl_add_u64 v[170:171], s[4:5], 0, v[166:167]
	s_add_i32 s4, s20, s13
	s_add_i32 s13, s4, 0x80
	s_add_i32 s20, s4, 0xffffff80
	s_and_b64 s[4:5], s[8:9], exec
	s_cselect_b32 s20, s20, s13
	s_cmp_eq_u32 s19, 0
	s_cselect_b32 s4, 0x8000, s68
	s_add_i32 s21, s4, s15
	s_and_b64 s[4:5], s[6:7], exec
	s_cselect_b32 s20, s20, s21
	v_add_u32_e32 v26, s20, v176
	v_add_u32_e32 v38, s20, v177
	s_waitcnt vmcnt(10)
	v_mad_i64_i32 v[30:31], s[4:5], v26, s33, v[170:171]
	v_mad_i64_i32 v[46:47], s[4:5], v38, s33, v[170:171]
	global_load_dwordx4 v[26:29], v[30:31], off offset:3136
	s_nop 0
	global_load_dwordx4 v[30:33], v[30:31], off offset:3392
	s_nop 0
	global_load_dwordx4 v[42:45], v[46:47], off offset:3136
	s_nop 0
	global_load_dwordx4 v[46:49], v[46:47], off offset:3392
	s_andn2_b64 vcc, exec, s[6:7]
	s_mov_b64 s[4:5], -1
	s_cbranch_vccnz .LBB0_366
	s_cmp_gt_i32 s12, 62
	s_cbranch_scc1 .LBB0_366
	s_cmp_eq_u32 s12, 0
	s_cselect_b64 s[4:5], -1, 0

;     __device__ __forceinline__ const float* in(int i) const { return (const float*)(const __attribute__((address_space(1))) float*)ld(i); }
;     __device__ __forceinline__ unsigned char* ws() const { return (unsigned char*)(__attribute__((address_space(1))) unsigned char*)ld(23); }
; __device__ __forceinline__ void gla_prefetch(v4u& pz0, v4u& pz1, v4u& pw0, v4u& pw1, const KPD& kp, int l, int pair, int lane, int wave) {
;     const int half = wave >> 2, w4 = wave & 3, item = 2 * pair + half, h = item & 3, sc = item >> 2; int b, n, rowbase; chunk_coords(sc, b, n, rowbase);
;     const int dir = w4 >> 1, d0 = 24 * (w4 & 1);
;     const bf16* prow = (const bf16*)(kp.ws() + WS_P) + (size_t)(rowbase + lane) * INP;
;     pz0 = *(const v4u*)(prow + (dir ? C_ZB : C_ZF)); pz1 = *(const v4u*)(prow + (dir ? C_ZB : C_ZF) + 8);
;     const float* W = kp.in(I_GWDEC) + (size_t)((l * 2 + dir) * 16) * 192 + h * 48 + d0;
;     const float* bias = kp.in(I_GBDEC) + (l * 2 + dir) * 192 + h * 48 + d0;
;     unsigned w[6];
; #pragma unroll
;     for (int i = 0; i < 6; ++i) { const int e = lane + 64 * i; w[i] = __float_as_uint(W[(e / 24) * 192 + (e % 24)]); }
;     pw0 = (v4u){w[0], w[1], w[2], w[3]}; pw1 = (v4u){w[4], w[5], __float_as_uint(bias[lane < 24 ? lane : 0]), 0u};
; __global__ void __launch_bounds__(512, 2) fwd_kernel(KP kparg) {
;     ...
;           v4u gz0 = {0u, 0u, 0u, 0u}, gz1 = gz0, gw0 = gz0, gw1 = gz0; { const int i0 = (G == 256) ? XITEM(c) : c; if (i0 < ngl) gla_prefetch(gz0, gz1, gw0, gw1, kp, l, i0, lane, wave); }
.LBB0_450:
	s_lshl_b32 s0, s4, 6
	s_and_b32 s1, s3, 3
	s_add_i32 s3, s5, s0
	s_lshr_b32 s0, s13, 1
	ds_read_b64 v[4:5], v207
	s_and_b32 s4, s0, 1
	s_and_b32 s6, 64, s2
	s_cmp_eq_u32 s4, 0
	s_movk_i32 s0, 0x920
	v_readlane_b32 s10, v254, 27
	s_cselect_b32 s0, 0x900, s0
	s_lshl_b32 s5, s10, 1
	s_or_b32 s9, s4, s5
	s_mul_i32 s78, s9, 0xc00
	s_waitcnt lgkmcnt(0)
	v_readfirstlane_b32 s8, v4
	s_lshl_b64 s[4:5], s[78:79], 2
	v_readfirstlane_b32 s7, v5
	s_add_u32 s4, s8, s4
	s_addc_u32 s5, s7, s5
	s_mul_i32 s7, s1, 0xc0
	s_add_u32 s8, s4, s7
	v_readlane_b32 s1, v255, 63
	v_readlane_b32 s4, v255, 62
	v_or_b32_e32 v4, s3, v80
	v_mov_b32_e32 v3, s1
	v_mov_b32_e32 v2, s4
	s_addc_u32 s10, s5, 0
	v_mad_i64_i32 v[2:3], s[4:5], v4, s33, v[2:3]
	s_mov_b32 s1, s79
	v_lshl_add_u64 v[2:3], v[2:3], 0, s[0:1]
	s_mov_b64 s[0:1], 0x7800000
	v_lshl_add_u64 v[4:5], v[2:3], 0, s[0:1]
	s_mov_b32 s0, 0x7800000
	v_add_co_u32_e32 v2, vcc, s0, v2
	s_cmp_lg_u32 s6, 0
	s_nop 0
	v_addc_co_u32_e32 v3, vcc, 0, v3, vcc
	global_load_dwordx4 v[42:45], v[2:3], off
	global_load_dwordx4 v[46:49], v[4:5], off offset:16
	ds_read_b64 v[2:3], v252
	v_mul_lo_u16_e32 v4, 43, v80
	v_or_b32_e32 v5, 64, v80
	v_or_b32_e32 v6, 0x80, v80
	v_or_b32_e32 v7, 0xc0, v80
	s_cselect_b32 s3, 0x60, 0
	v_lshrrev_b16_e32 v4, 10, v4
	v_mul_lo_u16_e32 v5, 43, v5
	v_mul_lo_u16_e32 v6, 0xab, v6
	v_mul_lo_u16_e32 v7, 0xab, v7
	v_or_b32_e32 v8, 0x100, v80
	v_or_b32_e32 v9, 0x140, v80
	s_add_u32 s0, s8, s3
	v_mul_u32_u24_e32 v4, 0xa8, v4
	v_lshrrev_b16_e32 v5, 10, v5
	v_lshrrev_b16_e32 v6, 12, v6
	v_lshrrev_b16_e32 v7, 12, v7
	v_mul_u32_u24_e32 v8, 0xaab, v8
	s_movk_i32 s4, 0xa8
	v_mul_u32_u24_e32 v9, 0xaab, v9
	s_addc_u32 s1, s10, 0
	v_add_lshl_u32 v4, v4, v80, 2
	v_mul_u32_u24_e32 v5, 0xa8, v5
	v_mul_u32_u24_e32 v6, 0xa8, v6
	v_mul_u32_u24_e32 v7, 0xa8, v7
	v_mul_lo_u16_sdwa v8, v8, s4 dst_sel:DWORD dst_unused:UNUSED_PAD src0_sel:WORD_1 src1_sel:DWORD
	v_mul_lo_u16_sdwa v9, v9, s4 dst_sel:DWORD dst_unused:UNUSED_PAD src0_sel:WORD_1 src1_sel:DWORD
	s_mul_i32 s78, s9, 0xc0
	v_add_lshl_u32 v5, v5, v80, 2
	v_add_lshl_u32 v6, v6, v80, 2
	v_add_lshl_u32 v7, v7, v80, 2
	v_add_lshl_u32 v8, v80, v8, 2
	v_add_lshl_u32 v9, v80, v9, 2
	global_load_dword v84, v4, s[0:1]
	global_load_dword v85, v5, s[0:1] offset:256
	global_load_dword v86, v6, s[0:1] offset:512
	global_load_dword v83, v7, s[0:1] offset:768
	global_load_dword v87, v8, s[0:1] offset:1024
	global_load_dword v88, v9, s[0:1] offset:1280
	s_waitcnt lgkmcnt(0)
	v_readfirstlane_b32 s5, v2
	s_lshl_b64 s[0:1], s[78:79], 2
	v_readfirstlane_b32 s4, v3
	s_add_u32 s0, s5, s0
	s_addc_u32 s1, s4, s1
	s_add_u32 s0, s0, s7
	s_addc_u32 s1, s1, 0
	v_cmp_gt_u32_e32 vcc, 24, v80
	s_add_u32 s0, s0, s3
	s_addc_u32 s1, s1, 0
	v_cndmask_b32_e32 v2, 0, v80, vcc
	v_lshlrev_b32_e32 v2, 2, v2
	global_load_dword v91, v2, s[0:1]
	v_readlane_b32 s11, v254, 28
	s_add_i32 s88, s87, 0xff
	s_cmp_ge_i32 s73, s88
	s_cbranch_scc0 .LBB0_452
	s_branch .LBB0_467

;     __device__ __forceinline__ unsigned char* ws() const { return (unsigned char*)(__attribute__((address_space(1))) unsigned char*)ld(23); }
; __device__ __forceinline__ float lo16(unsigned w) { return __uint_as_float(w << 16); }
; __device__ __forceinline__ float hi16(unsigned w) { return __uint_as_float(w & 0xffff0000u); }
; template <bool PHC>
; __device__ __forceinline__ void gla_pair(const KPD& kp, int l, int pair, unsigned char* lds, int tid, int lane, int wave, v4u& pz0, v4u& pz1, v4u& pw0, v4u& pw1, int next_pair) {
;     const int half = wave >> 2, w4 = wave & 3, t4 = tid & 255;
;     const int item = 2 * pair + half;
;     const int h = item & 3, sc = item >> 2; int b, n, rowbase; chunk_coords(sc, b, n, rowbase);
;     unsigned char* L = lds + half * 69632;
;     const bf16* P = (const bf16*)(kp.ws() + WS_P);
;     float* ST = (float*)(kp.ws() + WS_ST); float* DEC = (float*)(kp.ws() + WS_DEC);
;     const int dir = w4 >> 1, d0 = 24 * (w4 & 1);
;     const bf16* prow = P + (size_t)(rowbase + lane) * INP;
;     v4u vpre[3];
; #pragma unroll
;     for (int i = 0; i < 3; ++i) { const int idx = t4 + 256 * i; vpre[i] = *(const v4u*)(P + (size_t)(rowbase + idx / 12) * INP + C_GV + h * 96 + 8 * (idx % 12)); }
;     v2u spre[9];
;     if constexpr (PHC) { const bf16* SI = (const bf16*)(kp.ws() + WS_SI);
; #pragma unroll
;         for (int i = 0; i < 9; ++i) { const int idx = t4 + 256 * i; const int dd = idx / 1152, e = (idx % 1152) * 4;
;             spre[i] = *(const v2u*)(SI + ((size_t)((dd * 4 + b) * NCH + n) * 4 + h) * 4608 + e); }
;     }
;     float z[16];
;     { const v4u z0 = pz0, z1 = pz1;
;       z[0] = lo16(z0.x); z[1] = hi16(z0.x); z[2] = lo16(z0.y); z[3] = hi16(z0.y); z[4] = lo16(z0.z); z[5] = hi16(z0.z); z[6] = lo16(z0.w); z[7] = hi16(z0.w);
;       z[8] = lo16(z1.x); z[9] = hi16(z1.x); z[10] = lo16(z1.y); z[11] = hi16(z1.y); z[12] = lo16(z1.z); z[13] = hi16(z1.z); z[14] = lo16(z1.w); z[15] = hi16(z1.w); }
;     v4u qraw[3], kraw[3];
; #pragma unroll
;     for (int i = 0; i < 3; ++i) { qraw[i] = *((const v4u*)(prow + C_GQ + h * 48 + d0) + i); kraw[i] = *((const v4u*)(prow + C_GK + h * 48 + d0) + i); }
;     const int wvv[6] = {(int)pw0.x, (int)pw0.y, (int)pw0.z, (int)pw0.w, (int)pw1.x, (int)pw1.y};
;     const int bvv = (int)pw1.z;
.LBB0_459:
	v_readfirstlane_b32 vcc_lo, v225
	s_lshl_b32 vcc_hi, s2, 2
	s_lshr_b32 vcc_lo, vcc_lo, 6
	s_and_b32 vcc_lo, vcc_lo, 3
	s_add_i32 vcc_lo, vcc_lo, vcc_hi
	s_mul_i32 vcc_lo, vcc_lo, 0x1800
	s_waitcnt lgkmcnt(0)
	v_readlane_b32 s100, v255, 62
	v_readlane_b32 s101, v255, 63
	v_mbcnt_lo_u32_b32 v250, -1, 0
	v_mbcnt_hi_u32_b32 v250, -1, v250
	s_add_u32 s100, s100, 0x3400000
	s_addc_u32 s101, s101, 0
	s_add_u32 s100, s100, vcc_lo
	s_addc_u32 s101, s101, 0
	v_lshlrev_b32_e32 v250, 2, v250
	v_add_u32_e32 v251, 0x1000, v250
	global_load_dword v226, v250, s[100:101]
	global_load_dword v227, v250, s[100:101] offset:256
	global_load_dword v228, v250, s[100:101] offset:512
	global_load_dword v229, v250, s[100:101] offset:768
	global_load_dword v230, v250, s[100:101] offset:1024
	global_load_dword v231, v250, s[100:101] offset:1280
	global_load_dword v232, v250, s[100:101] offset:1536
	global_load_dword v233, v250, s[100:101] offset:1792
	global_load_dword v234, v250, s[100:101] offset:2048
	global_load_dword v235, v250, s[100:101] offset:2304
	global_load_dword v236, v250, s[100:101] offset:2560
	global_load_dword v237, v250, s[100:101] offset:2816
	global_load_dword v238, v250, s[100:101] offset:3072
	global_load_dword v239, v250, s[100:101] offset:3328
	global_load_dword v240, v250, s[100:101] offset:3584
	global_load_dword v241, v250, s[100:101] offset:3840
	global_load_dword v242, v251, s[100:101]
	global_load_dword v243, v251, s[100:101] offset:256
	global_load_dword v244, v251, s[100:101] offset:512
	global_load_dword v245, v251, s[100:101] offset:768
	global_load_dword v246, v251, s[100:101] offset:1024
	global_load_dword v247, v251, s[100:101] offset:1280
	global_load_dword v248, v251, s[100:101] offset:1536
	global_load_dword v249, v251, s[100:101] offset:1792
	v_readlane_b32 s0, v253, 17
	s_add_i32 s3, s0, s3
	v_readlane_b32 s0, v254, 32
	s_add_i32 s59, s59, s0
	v_readlane_b32 s0, v254, 48
	v_readlane_b32 s1, v254, 49
	s_and_b64 s[0:1], s[0:1], exec
	s_cselect_b32 s0, s3, s59
	s_cmp_lt_i32 s0, s87
	s_cselect_b32 s77, s0, -1
	s_lshl_b32 s0, s9, 6
	s_and_b32 s10, s2, 3
	s_add_i32 s80, s8, s0
	s_waitcnt lgkmcnt(0)
	v_readlane_b32 s0, v255, 62
	v_readlane_b32 s1, v255, 63
	s_add_u32 s0, s0, 0x7800000
	s_addc_u32 s1, s1, 0
	ds_read_b64 v[2:3], v204
	s_waitcnt lgkmcnt(0)
	ds_read_b64 v[2:3], v204
	s_mul_i32 s78, s10, 0x60
	s_waitcnt lgkmcnt(0)
	v_add_u32_e32 v2, s80, v37
	v_mov_b64_e32 v[60:61], s[0:1]
	v_add_u32_e32 v4, s80, v82
	v_add_u32_e32 v10, s80, v95
	v_mad_i64_i32 v[2:3], s[0:1], v2, s33, v[60:61]
	s_lshl_b32 s8, s78, 1
	s_mov_b32 s9, s79
	v_mad_i64_i32 v[4:5], s[0:1], v4, s33, v[60:61]
	v_mad_i64_i32 v[10:11], s[0:1], v10, s33, v[60:61]
	v_lshl_add_u64 v[2:3], v[2:3], 0, s[8:9]
	v_lshl_add_u64 v[4:5], v[4:5], 0, s[8:9]
	v_mov_b32_e32 v55, v35
	v_lshl_add_u64 v[10:11], v[10:11], 0, s[8:9]
	v_mov_b32_e32 v57, v35
	v_lshl_add_u64 v[2:3], v[2:3], 0, v[34:35]
	v_lshl_add_u64 v[6:7], v[4:5], 0, v[54:55]
	v_lshl_add_u64 v[10:11], v[10:11], 0, v[56:57]
	global_load_dwordx4 v[2:5], v[2:3], off offset:768
	global_load_dwordx4 v[6:9], v[6:7], off offset:768
	s_mul_i32 s2, s81, 0x84
	global_load_dwordx4 v[10:13], v[10:11], off offset:768
	v_lshlrev_b32_e32 v16, 16, v49
	v_and_b32_e32 v17, 0xffff0000, v49
	v_lshlrev_b32_e32 v18, 16, v42
	v_and_b32_e32 v19, 0xffff0000, v42
	s_waitcnt lgkmcnt(0)
	v_readlane_b32 s0, v255, 62
	v_readlane_b32 s1, v255, 63
	s_add_u32 s0, s0, 0x1a000000
	s_addc_u32 s1, s1, 0
	s_add_i32 s2, s2, s97
	s_ashr_i32 s3, s2, 31
	s_lshl_b64 s[2:3], s[2:3], 2
	s_or_b32 s72, s2, s10
	s_mul_i32 s2, s3, 0x2400
	s_mul_hi_u32 s11, s72, 0x2400
	s_add_i32 s11, s11, s2
	v_lshlrev_b32_e32 v20, 16, v43
	v_and_b32_e32 v21, 0xffff0000, v43
	v_lshlrev_b32_e32 v22, 16, v44
	v_and_b32_e32 v23, 0xffff0000, v44
	v_lshlrev_b32_e32 v24, 16, v45
	v_and_b32_e32 v25, 0xffff0000, v45
	v_lshlrev_b32_e32 v26, 16, v46
	v_and_b32_e32 v27, 0xffff0000, v46
	v_lshlrev_b32_e32 v28, 16, v47
	v_and_b32_e32 v29, 0xffff0000, v47
	v_lshlrev_b32_e32 v30, 16, v48
	v_and_b32_e32 v31, 0xffff0000, v48
	s_mov_b32 s12, 0xbfb8aa3b
	s_mov_b32 s13, 0x800000
	s_mulk_i32 s72, 0x2400
	v_mov_b32_e32 v59, v35
	s_add_u32 s2, s0, s72
	s_addc_u32 s3, s1, s11
	v_mov_b64_e32 v[14:15], s[0:1]
	global_load_dwordx2 v[62:63], v108, s[2:3]
	global_load_dwordx2 v[64:65], v109, s[2:3]
	global_load_dwordx2 v[66:67], v110, s[2:3]
	global_load_dwordx2 v[68:69], v111, s[2:3]
	s_add_u32 s2, s2, 0x1290000
	s_addc_u32 s3, s3, 0
	global_load_dwordx2 v[70:71], v115, s[2:3]
	s_cmp_lt_i32 s77, 0
	v_readlane_b32 s11, v91, 23
	v_readlane_b32 s72, v88, 39
	v_readlane_b32 s73, v88, 63
	v_mov_b32_e32 v38, s11
	v_readlane_b32 s11, v84, 23
	v_pk_mul_f32 v[16:17], v[16:17], s[72:73]
	s_nop 0
	v_fmac_f32_e32 v38, s11, v18
	v_readlane_b32 s11, v84, 47
	s_nop 1
	v_fmac_f32_e32 v38, s11, v19
	v_readlane_b32 s11, v85, 7
	s_nop 1
	v_fmac_f32_e32 v38, s11, v20
	v_readlane_b32 s11, v85, 31
	s_nop 1
	v_fmac_f32_e32 v38, s11, v21
	v_readlane_b32 s11, v85, 55
	s_nop 1
	v_fmac_f32_e32 v38, s11, v22
	v_readlane_b32 s11, v86, 15
	s_nop 1
	v_fmac_f32_e32 v38, s11, v23
	v_readlane_b32 s11, v86, 39
	s_nop 1
	v_fmac_f32_e32 v38, s11, v24
	v_readlane_b32 s11, v86, 63
	s_nop 1
	v_fmac_f32_e32 v38, s11, v25
	v_readlane_b32 s11, v83, 23
	s_nop 1
	v_fmac_f32_e32 v38, s11, v26
	v_readlane_b32 s11, v83, 47
	s_nop 1
	v_fmac_f32_e32 v38, s11, v27
	v_readlane_b32 s11, v87, 7
	s_nop 1
	v_fmac_f32_e32 v38, s11, v28
	v_readlane_b32 s11, v87, 31
	s_nop 1
	v_fmac_f32_e32 v38, s11, v29
	v_readlane_b32 s11, v87, 55
	v_add_u32_e32 v18, s80, v80
	s_nop 0
	v_fmac_f32_e32 v38, s11, v30
	v_readlane_b32 s11, v88, 15
	s_nop 1
	v_fmac_f32_e32 v38, s11, v31
	v_add_f32_e32 v16, v38, v16
	v_add_f32_e32 v38, v16, v17
	v_mul_f32_e64 v16, |v38|, s12
	v_exp_f32_e32 v16, v16
	s_nop 0
	v_add_f32_e32 v16, 1.0, v16
	v_cmp_gt_f32_e32 vcc, s13, v16
	v_add_u32_e32 v16, s81, v89
	s_movk_i32 s0, 0x84
	v_mul_lo_u32 v16, v16, s0
	v_add_u32_e32 v16, s97, v16
	v_ashrrev_i32_e32 v17, 31, v16
	v_lshlrev_b64 v[16:17], 2, v[16:17]
	v_or_b32_e32 v16, s10, v16
	s_movk_i32 s10, 0x2400
	v_mad_u64_u32 v[14:15], s[0:1], v16, s10, v[14:15]
	v_mad_i32_i24 v15, v17, s10, v15
	v_lshl_add_u64 v[14:15], v[14:15], 0, v[58:59]
	global_load_dwordx2 v[72:73], v112, s[2:3]
	global_load_dwordx2 v[74:75], v113, s[2:3]
	global_load_dwordx2 v[76:77], v114, s[2:3]
	global_load_dwordx2 v[78:79], v[14:15], off
	v_mad_i64_i32 v[14:15], s[0:1], v18, s33, v[60:61]
	v_lshl_add_u64 v[14:15], v[14:15], 0, s[78:79]
	s_waitcnt vmcnt(12)
; __device__ __forceinline__ unsigned pk2(float lo, float hi) { return cvtpk(lo, hi); }
; template <bool PHC>
; __device__ __forceinline__ void gla_pair(const KPD& kp, int l, int pair, unsigned char* lds, int tid, int lane, int wave, v4u& pz0, v4u& pz1, v4u& pw0, v4u& pw1, int next_pair) {
;     ...
;         const float qs = 0.14433756729740643f;
;         { unsigned qw[12], kw[12];
; #pragma unroll
;           for (int i = 0; i < 12; ++i) { qw[i] = pk2(qv[2 * i] * qs * __expf(bc[2 * i]), qv[2 * i + 1] * qs * __expf(bc[2 * i + 1])); kw[i] = pk2(kv[2 * i] * __expf(-bc[2 * i]), kv[2 * i + 1] * __expf(-bc[2 * i + 1])); }
	v_mov_b32_e32 v55, v226
	v_mov_b32_e32 v57, v227
	s_mov_b32 s97, s79
	v_lshl_add_u64 v[30:31], v[14:15], 0, s[96:97]
	global_load_dwordx4 v[26:29], v[30:31], off offset:16
	global_load_dwordx4 v[50:53], v[30:31], off
	global_load_dwordx4 v[14:17], v[30:31], off offset:416
	global_load_dwordx4 v[22:25], v[30:31], off offset:400
	global_load_dwordx4 v[18:21], v[30:31], off offset:32
	global_load_dwordx4 v[30:33], v[30:31], off offset:384
	v_mov_b32_e32 v59, v228
	v_mov_b32_e32 v128, v229
	v_mov_b32_e32 v129, v230
	v_mov_b32_e32 v130, v231
	v_mov_b32_e32 v131, v232
	s_waitcnt vmcnt(0)
	v_lshlrev_b32_e32 v149, 16, v30
	v_and_b32_e32 v30, 0xffff0000, v30
	v_lshlrev_b32_e32 v150, 16, v31
	v_and_b32_e32 v31, 0xffff0000, v31
	v_mov_b32_e32 v132, v233
	v_lshlrev_b32_e32 v152, 16, v33
	v_and_b32_e32 v33, 0xffff0000, v33
	v_lshlrev_b32_e32 v153, 16, v26
	v_and_b32_e32 v26, 0xffff0000, v26
	v_mov_b32_e32 v133, v234
	v_lshlrev_b32_e32 v151, 16, v32
	v_and_b32_e32 v32, 0xffff0000, v32
	v_lshlrev_b32_e32 v155, 16, v28
	v_and_b32_e32 v28, 0xffff0000, v28
	v_mul_f32_e32 v28, 0x3e13cd3a, v28
	v_lshlrev_b32_e32 v156, 16, v29
	v_and_b32_e32 v29, 0xffff0000, v29
	v_mul_f32_e32 v29, 0x3e13cd3a, v29
	v_mov_b32_e32 v134, v235
	v_and_b32_e32 v158, 0xffff0000, v22
	v_lshlrev_b32_e32 v159, 16, v23
	v_lshlrev_b32_e32 v154, 16, v27
	v_and_b32_e32 v27, 0xffff0000, v27
	v_mov_b32_e32 v135, v236
	v_lshlrev_b32_e32 v157, 16, v22
	v_mul_f32_e32 v22, 0x3fb8aa3b, v132
	v_lshlrev_b32_e32 v161, 16, v24
	v_and_b32_e32 v162, 0xffff0000, v24
	v_exp_f32_e32 v22, v22
	v_mul_f32_e32 v24, 0xbfb8aa3b, v132
	v_exp_f32_e32 v24, v24
	v_mov_b32_e32 v136, v237
	v_lshlrev_b32_e32 v165, 16, v18
	v_and_b32_e32 v160, 0xffff0000, v23
	v_mul_f32_e32 v23, 0xbfb8aa3b, v131
	v_exp_f32_e32 v23, v23
	v_and_b32_e32 v164, 0xffff0000, v25
	v_mov_b32_e32 v137, v238
	v_lshlrev_b32_e32 v167, 16, v19
	v_and_b32_e32 v168, 0xffff0000, v19
	v_mul_f32_e32 v19, 0xbfb8aa3b, v59
	v_exp_f32_e32 v19, v19
	v_lshlrev_b32_e32 v163, 16, v25
	v_mul_f32_e32 v25, 0x3fb8aa3b, v135
	v_exp_f32_e32 v25, v25
	v_mov_b32_e32 v138, v239
	v_and_b32_e32 v166, 0xffff0000, v18
	v_and_b32_e32 v170, 0xffff0000, v20
	v_lshlrev_b32_e32 v171, 16, v21
	v_mov_b32_e32 v139, v240
	v_lshlrev_b32_e32 v173, 16, v14
	v_and_b32_e32 v174, 0xffff0000, v14
	v_mul_f32_e32 v14, 0x3fb8aa3b, v55
	v_exp_f32_e32 v14, v14
	v_lshlrev_b32_e32 v169, 16, v20
	v_mul_f32_e32 v20, 0xbfb8aa3b, v128
	v_exp_f32_e32 v20, v20
	v_mov_b32_e32 v140, v241
	v_and_b32_e32 v176, 0xffff0000, v15
	v_lshlrev_b32_e32 v177, 16, v16
	v_and_b32_e32 v172, 0xffff0000, v21
	v_mul_f32_e32 v21, 0x3fb8aa3b, v131
	v_exp_f32_e32 v21, v21
	v_mov_b32_e32 v141, v242
	v_lshlrev_b32_e32 v175, 16, v15
	v_mul_f32_e32 v15, 0x3fb8aa3b, v57
	v_exp_f32_e32 v15, v15
	v_lshlrev_b32_e32 v179, 16, v17
	v_and_b32_e32 v180, 0xffff0000, v17
	v_mul_f32_e32 v17, 0x3fb8aa3b, v59
	v_exp_f32_e32 v17, v17
	v_mov_b32_e32 v142, v243
	v_and_b32_e32 v178, 0xffff0000, v16
	v_mov_b32_e32 v143, v244
	v_mov_b32_e32 v144, v245
	v_mov_b32_e32 v145, v246
	v_mov_b32_e32 v146, v247
	v_lshlrev_b32_e32 v148, 16, v53
	v_and_b32_e32 v53, 0xffff0000, v53
	v_mov_b32_e32 v39, v248
	v_lshlrev_b32_e32 v147, 16, v52
	v_and_b32_e32 v52, 0xffff0000, v52
	v_mov_b32_e32 v38, v249
	v_lshlrev_b32_e32 v40, 16, v50
	v_and_b32_e32 v41, 0xffff0000, v50
	v_mul_f32_e32 v16, 0x3e13cd3a, v40
	v_mul_f32_e32 v14, v16, v14
	v_mul_f32_e32 v16, 0x3e13cd3a, v41
	v_mul_f32_e32 v15, v16, v15
	v_cvt_pk_bf16_f32 v14, v14, v15
	v_mul_f32_e32 v15, 0xbfb8aa3b, v57
	v_mul_f32_e32 v16, 0xbfb8aa3b, v55
	v_exp_f32_e32 v15, v15
	v_exp_f32_e32 v16, v16
	v_lshlrev_b32_e32 v50, 16, v51
	v_and_b32_e32 v51, 0xffff0000, v51
	v_mul_f32_e32 v15, v15, v30
	v_mul_f32_e32 v16, v16, v149
	v_cvt_pk_bf16_f32 v18, v16, v15
	v_mul_f32_e32 v15, 0x3e13cd3a, v50
	v_mul_f32_e32 v15, v15, v17
	v_mul_f32_e32 v17, 0x3fb8aa3b, v128
	v_exp_f32_e32 v17, v17
	v_mul_f32_e32 v16, 0x3e13cd3a, v51
	v_mul_f32_e32 v30, 0xbfb8aa3b, v136
	v_exp_f32_e32 v30, v30
	v_mul_f32_e32 v16, v16, v17
	v_cvt_pk_bf16_f32 v15, v15, v16
	v_mul_f32_e32 v16, v19, v150
	v_mul_f32_e32 v17, v20, v31
	v_cvt_pk_bf16_f32 v19, v16, v17
	v_mul_f32_e32 v16, 0x3fb8aa3b, v129
	v_exp_f32_e32 v16, v16
	v_mul_f32_e32 v17, 0x3fb8aa3b, v130
	v_exp_f32_e32 v17, v17
	v_mul_f32_e32 v20, 0x3e13cd3a, v147
	v_mul_f32_e32 v16, v20, v16
	v_mul_f32_e32 v20, 0x3e13cd3a, v52
	v_mul_f32_e32 v17, v20, v17
	v_mul_f32_e32 v20, 0xbfb8aa3b, v129
	v_cvt_pk_bf16_f32 v16, v16, v17
	v_mul_f32_e32 v17, 0xbfb8aa3b, v130
	v_exp_f32_e32 v20, v20
	v_exp_f32_e32 v17, v17
	v_mul_f32_e32 v31, 0xbfb8aa3b, v139
	v_exp_f32_e32 v31, v31
	v_mul_f32_e32 v20, v20, v151
	v_mul_f32_e32 v17, v17, v32
	v_cvt_pk_bf16_f32 v20, v20, v17
	v_mul_f32_e32 v17, 0x3e13cd3a, v148
	v_mul_f32_e32 v17, v17, v21
	v_mul_f32_e32 v21, 0x3e13cd3a, v53
	v_mul_f32_e32 v21, v21, v22
	v_cvt_pk_bf16_f32 v17, v17, v21
	v_mul_f32_e32 v21, v23, v152
	v_mul_f32_e32 v22, v24, v33
	v_cvt_pk_bf16_f32 v21, v21, v22
	v_mul_f32_e32 v22, 0x3fb8aa3b, v133
	v_exp_f32_e32 v22, v22
	v_mul_f32_e32 v23, 0x3fb8aa3b, v134
	v_exp_f32_e32 v23, v23
	v_mul_f32_e32 v24, 0x3e13cd3a, v153
	v_mul_f32_e32 v22, v24, v22
	v_mul_f32_e32 v24, 0x3e13cd3a, v26
	v_mul_f32_e32 v23, v24, v23
	v_cvt_pk_bf16_f32 v22, v22, v23
	v_mul_f32_e32 v23, 0xbfb8aa3b, v134
	v_mul_f32_e32 v24, 0xbfb8aa3b, v133
	v_exp_f32_e32 v23, v23
	v_exp_f32_e32 v24, v24
	v_mul_f32_e32 v32, 0xbfb8aa3b, v140
	v_exp_f32_e32 v32, v32
	v_mul_f32_e32 v23, v23, v158
	v_mul_f32_e32 v24, v24, v157
	v_cvt_pk_bf16_f32 v26, v24, v23
	v_mul_f32_e32 v23, 0x3e13cd3a, v154
	v_mul_f32_e32 v23, v23, v25
	v_mul_f32_e32 v25, 0x3fb8aa3b, v136
	v_mul_f32_e32 v24, 0x3e13cd3a, v27
; __device__ __forceinline__ unsigned pk2(float lo, float hi) { return cvtpk(lo, hi); }
; template <bool PHC>
; __device__ __forceinline__ void gla_pair(const KPD& kp, int l, int pair, unsigned char* lds, int tid, int lane, int wave, v4u& pz0, v4u& pz1, v4u& pw0, v4u& pw1, int next_pair) {
;     ...
;         { unsigned qw[12], kw[12];
; #pragma unroll
;           for (int i = 0; i < 12; ++i) { qw[i] = pk2(qv[2 * i] * qs * __expf(bc[2 * i]), qv[2 * i + 1] * qs * __expf(bc[2 * i + 1])); kw[i] = pk2(kv[2 * i] * __expf(-bc[2 * i]), kv[2 * i + 1] * __expf(-bc[2 * i + 1])); }
;           v4u* qo = (v4u*)(AC + lane * 168 + 64 + dir * 48 + d0); v4u* ko = (v4u*)(KI + (dir * 64 + lane) * 56 + d0);
; #pragma unroll
;           for (int i = 0; i < 3; ++i) { qo[i] = (v4u){qw[4 * i], qw[4 * i + 1], qw[4 * i + 2], qw[4 * i + 3]}; ko[i] = (v4u){kw[4 * i], kw[4 * i + 1], kw[4 * i + 2], kw[4 * i + 3]}; } }
; #pragma unroll
;         for (int i = 0; i < 3; ++i) { const int idx = t4 + 256 * i; const int t = idx / 12, ch = idx % 12; *(v4u*)(Vr + t * 104 + 8 * ch) = vpre[i]; }
; #pragma unroll
;         for (int i = 0; i < 9; ++i) { const int idx = t4 + 256 * i; const int dd = idx / 1152, e = (idx % 1152) * 4, d = e / 96, v = e % 96;
;             *(v2u*)(SB + (dd * 48 + d) * 104 + v) = spre[i]; }
;         __syncthreads();
	v_exp_f32_e32 v25, v25
	v_mul_f32_e32 v27, 0xbfb8aa3b, v135
	v_exp_f32_e32 v27, v27
	v_mul_f32_e32 v33, 0x3fb8aa3b, v143
	v_mul_f32_e32 v24, v24, v25
	v_cvt_pk_bf16_f32 v23, v23, v24
	v_mul_f32_e32 v24, v27, v159
	v_mul_f32_e32 v25, v30, v160
	v_cvt_pk_bf16_f32 v27, v24, v25
	v_mul_f32_e32 v24, 0x3fb8aa3b, v137
	v_mul_f32_e32 v25, 0x3fb8aa3b, v138
	v_exp_f32_e32 v24, v24
	v_exp_f32_e32 v25, v25
	v_mul_f32_e32 v30, 0x3e13cd3a, v155
	v_exp_f32_e32 v33, v33
	v_mul_f32_e32 v24, v30, v24
	v_mul_f32_e32 v25, v28, v25
	v_mul_f32_e32 v28, 0xbfb8aa3b, v137
	v_cvt_pk_bf16_f32 v24, v24, v25
	v_mul_f32_e32 v25, 0xbfb8aa3b, v138
	v_exp_f32_e32 v28, v28
	v_exp_f32_e32 v25, v25
	v_mul_f32_e32 v30, 0x3fb8aa3b, v139
	v_exp_f32_e32 v30, v30
	v_mul_f32_e32 v28, v28, v161
	v_mul_f32_e32 v25, v25, v162
	v_cvt_pk_bf16_f32 v28, v28, v25
	v_mul_f32_e32 v25, 0x3e13cd3a, v156
	v_mul_f32_e32 v25, v25, v30
	v_mul_f32_e32 v30, 0x3fb8aa3b, v140
	v_exp_f32_e32 v30, v30
	v_mul_f32_e32 v40, 0xbfb8aa3b, v143
	v_exp_f32_e32 v40, v40
	v_mul_f32_e32 v41, 0xbfb8aa3b, v144
	v_mul_f32_e32 v29, v29, v30
	v_cvt_pk_bf16_f32 v25, v25, v29
	v_mul_f32_e32 v29, v31, v163
	v_mul_f32_e32 v30, v32, v164
	v_cvt_pk_bf16_f32 v29, v29, v30
	v_mul_f32_e32 v30, 0x3fb8aa3b, v141
	v_exp_f32_e32 v30, v30
	v_mul_f32_e32 v31, 0x3fb8aa3b, v142
	v_exp_f32_e32 v31, v31
	v_mul_f32_e32 v32, 0x3e13cd3a, v165
	v_mul_f32_e32 v30, v32, v30
	v_mul_f32_e32 v32, 0x3e13cd3a, v166
	v_mul_f32_e32 v31, v32, v31
	v_cvt_pk_bf16_f32 v30, v30, v31
	v_mul_f32_e32 v31, 0xbfb8aa3b, v142
	v_mul_f32_e32 v32, 0xbfb8aa3b, v141
	v_exp_f32_e32 v31, v31
	v_exp_f32_e32 v32, v32
	v_exp_f32_e32 v41, v41
	v_readlane_b32 s0, v255, 9
	v_mul_f32_e32 v31, v31, v174
	v_mul_f32_e32 v32, v32, v173
	v_cvt_pk_bf16_f32 v50, v32, v31
	v_mul_f32_e32 v31, 0x3e13cd3a, v167
	v_mul_f32_e32 v31, v31, v33
	v_mul_f32_e32 v33, 0x3fb8aa3b, v144
	v_exp_f32_e32 v33, v33
	v_mul_f32_e32 v32, 0x3e13cd3a, v168
	v_readlane_b32 s1, v255, 10
	v_mul_f32_e32 v32, v32, v33
	v_cvt_pk_bf16_f32 v31, v31, v32
	v_mul_f32_e32 v32, v40, v175
	v_mul_f32_e32 v33, v41, v176
	v_cvt_pk_bf16_f32 v51, v32, v33
	v_mul_f32_e32 v32, 0x3fb8aa3b, v145
	v_exp_f32_e32 v32, v32
	v_mul_f32_e32 v33, 0x3fb8aa3b, v146
	v_exp_f32_e32 v33, v33
	v_mul_f32_e32 v40, 0x3e13cd3a, v169
	v_mul_f32_e32 v32, v40, v32
	v_mul_f32_e32 v40, 0x3e13cd3a, v170
	v_mul_f32_e32 v33, v40, v33
	v_cvt_pk_bf16_f32 v32, v32, v33
	v_mul_f32_e32 v33, 0xbfb8aa3b, v146
	v_mul_f32_e32 v40, 0xbfb8aa3b, v145
	v_exp_f32_e32 v33, v33
	v_exp_f32_e32 v40, v40
	v_mul_f32_e32 v41, 0x3fb8aa3b, v39
	v_exp_f32_e32 v41, v41
	v_mul_f32_e32 v33, v33, v178
	v_mul_f32_e32 v40, v40, v177
	v_cvt_pk_bf16_f32 v52, v40, v33
	v_mul_f32_e32 v33, 0x3e13cd3a, v171
	v_mul_f32_e32 v33, v33, v41
	v_mul_f32_e32 v41, 0x3fb8aa3b, v38
	v_mul_f32_e32 v39, 0xbfb8aa3b, v39
	v_mul_f32_e32 v38, 0xbfb8aa3b, v38
	v_exp_f32_e32 v39, v39
	v_exp_f32_e32 v38, v38
	v_exp_f32_e32 v41, v41
	v_mul_f32_e32 v40, 0x3e13cd3a, v172
	v_mul_f32_e32 v39, v39, v179
	v_mul_f32_e32 v38, v38, v180
	v_cvt_pk_bf16_f32 v53, v39, v38
	v_mul_f32_e32 v40, v40, v41
	v_cvt_pk_bf16_f32 v33, v33, v40
	ds_write_b128 v90, v[14:17] offset:128
	ds_write_b128 v92, v[18:21] offset:54784
	ds_write_b128 v90, v[22:25] offset:144
	ds_write_b128 v92, v[26:29] offset:54800
	ds_write_b128 v90, v[30:33] offset:160
	ds_write_b128 v92, v[50:53] offset:54816
	ds_write_b128 v116, v[2:5] offset:21504
	ds_write_b128 v117, v[6:9] offset:21504
	ds_write_b128 v118, v[10:13] offset:21504
	ds_write_b64 v93, v[62:63] offset:34816
	ds_write_b64 v94, v[64:65] offset:34816
	ds_write_b64 v96, v[66:67] offset:34816
	ds_write_b64 v97, v[68:69] offset:34816
	ds_write_b64 v98, v[78:79] offset:34816
	ds_write_b64 v99, v[72:73] offset:44800
	ds_write_b64 v100, v[74:75] offset:44800
	ds_write_b64 v101, v[76:77] offset:44800
	ds_write_b64 v102, v[70:71] offset:44800
	s_waitcnt lgkmcnt(0)
	s_barrier
; __device__ __forceinline__ unsigned cvtpk(float lo, float hi) { unsigned r; asm("v_cvt_pk_bf16_f32 %0, %1, %2" : "=v"(r) : "v"(lo), "v"(hi)); return r; }
; template <bool PHC>
; __device__ __forceinline__ void gla_pair(const KPD& kp, int l, int pair, unsigned char* lds, int tid, int lane, int wave, v4u& pz0, v4u& pz1, v4u& pw0, v4u& pw1, int next_pair) {
;     ...
;         { const int rt = w4 >> 1, ct = w4 & 1, r32 = lane & 31, hi = lane >> 5;
;           f32x16 af, ab;
; #pragma unroll
;           for (int r = 0; r < 16; ++r) { af[r] = 0.f; ab[r] = 0.f; }
; #pragma unroll
;           for (int ks = 0; ks < 3; ++ks) {
;               const bf16x8 a0 = *(const bf16x8*)(AC + (32 * rt + r32) * 168 + 64 + 16 * ks + 8 * hi);
;               const bf16x8 b0 = *(const bf16x8*)(KI + (32 * ct + r32) * 56 + 16 * ks + 8 * hi);
;               af = __builtin_amdgcn_mfma_f32_32x32x16_bf16(a0, b0, af, 0, 0, 0);
;               const bf16x8 a1 = *(const bf16x8*)(AC + (32 * rt + r32) * 168 + 112 + 16 * ks + 8 * hi);
;               const bf16x8 b1 = *(const bf16x8*)(KI + (64 + 32 * ct + r32) * 56 + 16 * ks + 8 * hi);
;               ab = __builtin_amdgcn_mfma_f32_32x32x16_bf16(a1, b1, ab, 0, 0, 0); }
;           const int j = 32 * ct + r32;
; #pragma unroll
;           for (int r = 0; r < 16; ++r) { const int i = 32 * rt + (r & 3) + 8 * (r >> 2) + 4 * hi;
;               const float val = ((j <= i) ? af[r] : 0.f) + ((j >= i) ? ab[r] : 0.f);
;               AC[i * 168 + j] = (bf16)(cvtpk(val, val) & 0xffffu); } }
;         const int fr = lane & 15, fq = lane >> 4;
;         unsigned short gpre[4][6];
; #pragma unroll
;         for (int r = 0; r < 4; ++r)
; #pragma unroll
;             for (int ct = 0; ct < 6; ++ct) gpre[r][ct] = P[(size_t)(rowbase + 16 * w4 + 4 * fq + r) * INP + C_GG + h * 96 + 16 * ct + fr];
;         __syncthreads();
	ds_read_b128 v[2:5], v103 offset:128
	ds_read_b128 v[6:9], v104 offset:54784
	ds_read_b128 v[50:53], v103 offset:160
	ds_read_b128 v[62:65], v104 offset:54816
	s_waitcnt lgkmcnt(2)
	v_mfma_f32_32x32x16_bf16 v[2:17], v[2:5], v[6:9], 0
	ds_read_b128 v[18:21], v103 offset:224
	ds_read_b128 v[22:25], v104 offset:61952
	ds_read_b128 v[66:69], v103 offset:192
	ds_read_b128 v[70:73], v104 offset:54848
	s_waitcnt lgkmcnt(2)
	v_mfma_f32_32x32x16_bf16 v[18:33], v[18:21], v[22:25], 0
	v_mfma_f32_32x32x16_bf16 v[2:17], v[50:53], v[62:65], v[2:17]
	ds_read_b128 v[50:53], v103 offset:256
	ds_read_b128 v[62:65], v104 offset:61984
	ds_read_b128 v[74:77], v103 offset:288
	ds_read_b128 v[128:131], v104 offset:62016
	s_waitcnt lgkmcnt(2)
	v_mfma_f32_32x32x16_bf16 v[18:33], v[50:53], v[62:65], v[18:33]
	v_add_u32_e32 v64, s80, v105
	v_add_u32_e32 v62, 1, v64
	v_mfma_f32_32x32x16_bf16 v[2:17], v[66:69], v[70:73], v[2:17]
	v_lshlrev_b32_e32 v66, 1, v36
	v_mov_b32_e32 v67, v35
	s_waitcnt lgkmcnt(0)
	v_mfma_f32_32x32x16_bf16 v[18:33], v[74:77], v[128:131], v[18:33]
	s_nop 7
	v_cndmask_b32_e64 v2, v2, 0, s[6:7]
	s_nop 2
	v_cndmask_b32_e64 v18, v18, 0, s[0:1]
	v_mad_i64_i32 v[50:51], s[0:1], v64, s33, v[60:61]
	v_mad_i64_i32 v[52:53], s[0:1], v62, s33, v[60:61]
	v_add_f32_e32 v2, v2, v18
	v_lshl_add_u64 v[50:51], v[50:51], 0, s[8:9]
	v_lshl_add_u64 v[52:53], v[52:53], 0, s[8:9]
	v_cvt_pk_bf16_f32 v2, v2, v2
	ds_write_b16 v119, v2
	v_lshl_add_u64 v[50:51], v[50:51], 0, v[66:67]
	v_lshl_add_u64 v[68:69], v[52:53], 0, v[66:67]
	v_add_u32_e32 v52, 2, v64
	global_load_ushort v136, v[50:51], off offset:1536
	global_load_ushort v135, v[50:51], off offset:1568
	global_load_ushort v134, v[50:51], off offset:1600
	global_load_ushort v133, v[50:51], off offset:1632
	global_load_ushort v131, v[50:51], off offset:1664
	global_load_ushort v129, v[50:51], off offset:1696
	global_load_ushort v128, v[68:69], off offset:1536
	global_load_ushort v79, v[68:69], off offset:1568
	v_mad_i64_i32 v[50:51], s[0:1], v52, s33, v[60:61]
	v_lshl_add_u64 v[50:51], v[50:51], 0, s[8:9]
	v_lshl_add_u64 v[138:139], v[50:51], 0, v[66:67]
	v_add_u32_e32 v50, 3, v64
	v_mad_i64_i32 v[60:61], s[0:1], v50, s33, v[60:61]
	v_lshl_add_u64 v[60:61], v[60:61], 0, s[8:9]
	global_load_ushort v78, v[68:69], off offset:1600
	global_load_ushort v77, v[68:69], off offset:1632
	global_load_ushort v76, v[68:69], off offset:1664
	global_load_ushort v75, v[68:69], off offset:1696
	global_load_ushort v74, v[138:139], off offset:1536
	global_load_ushort v73, v[138:139], off offset:1568
	global_load_ushort v72, v[138:139], off offset:1600
	global_load_ushort v71, v[138:139], off offset:1632
	v_lshl_add_u64 v[140:141], v[60:61], 0, v[66:67]
	global_load_ushort v70, v[138:139], off offset:1664
	global_load_ushort v69, v[138:139], off offset:1696
	global_load_ushort v68, v[140:141], off offset:1536
	global_load_ushort v61, v[140:141], off offset:1568
	global_load_ushort v60, v[140:141], off offset:1600
	global_load_ushort v59, v[140:141], off offset:1632
	global_load_ushort v57, v[140:141], off offset:1664
	global_load_ushort v55, v[140:141], off offset:1696
	v_readlane_b32 s0, v255, 11
	v_readlane_b32 s1, v255, 12
	s_nop 1
	v_cndmask_b32_e64 v2, v3, 0, s[0:1]
	v_cndmask_b32_e64 v3, 0, v19, s[6:7]
	v_add_f32_e32 v2, v2, v3
	v_readlane_b32 s0, v255, 13
	v_cvt_pk_bf16_f32 v2, v2, v2
	v_readlane_b32 s1, v255, 14
	ds_write_b16 v119, v2 offset:336
	s_nop 0
	v_cndmask_b32_e64 v2, v4, 0, s[0:1]
	v_readlane_b32 s0, v255, 15
	v_readlane_b32 s1, v255, 16
	s_nop 1
	v_cndmask_b32_e64 v3, v20, 0, s[0:1]
	v_add_f32_e32 v2, v2, v3
	v_cvt_pk_bf16_f32 v2, v2, v2
	ds_write_b16 v119, v2 offset:672
	v_cndmask_b32_e64 v2, v5, 0, s[16:17]
	v_cndmask_b32_e64 v3, v21, 0, s[18:19]
	v_add_f32_e32 v2, v2, v3
	v_cvt_pk_bf16_f32 v2, v2, v2
	ds_write_b16 v119, v2 offset:1008
	v_cndmask_b32_e64 v2, v6, 0, s[20:21]
	v_cndmask_b32_e64 v3, v22, 0, s[22:23]
	v_add_f32_e32 v2, v2, v3
	v_cvt_pk_bf16_f32 v2, v2, v2
	ds_write_b16 v119, v2 offset:2688
	v_cndmask_b32_e64 v2, v7, 0, s[24:25]
	v_cndmask_b32_e64 v3, v23, 0, s[26:27]
	v_add_f32_e32 v2, v2, v3
	v_cvt_pk_bf16_f32 v2, v2, v2
	ds_write_b16 v119, v2 offset:3024
	v_cndmask_b32_e64 v2, v8, 0, s[28:29]
	v_cndmask_b32_e64 v3, v24, 0, s[30:31]
	v_add_f32_e32 v2, v2, v3
	v_cvt_pk_bf16_f32 v2, v2, v2
	ds_write_b16 v119, v2 offset:3360
	v_cndmask_b32_e64 v2, v9, 0, s[34:35]
	v_cndmask_b32_e64 v3, v25, 0, s[36:37]
	v_add_f32_e32 v2, v2, v3
	v_cvt_pk_bf16_f32 v2, v2, v2
	ds_write_b16 v119, v2 offset:3696
	v_cndmask_b32_e64 v2, v10, 0, s[38:39]
	v_cndmask_b32_e64 v3, v26, 0, s[40:41]
	v_add_f32_e32 v2, v2, v3
	v_cvt_pk_bf16_f32 v2, v2, v2
	ds_write_b16 v119, v2 offset:5376
	v_cndmask_b32_e64 v2, v11, 0, s[42:43]
	v_cndmask_b32_e64 v3, v27, 0, s[44:45]
	v_add_f32_e32 v2, v2, v3
	v_cvt_pk_bf16_f32 v2, v2, v2
	ds_write_b16 v119, v2 offset:5712
	v_cndmask_b32_e64 v2, v12, 0, s[46:47]
	v_cndmask_b32_e64 v3, v28, 0, s[48:49]
	v_add_f32_e32 v2, v2, v3
	v_cvt_pk_bf16_f32 v2, v2, v2
	ds_write_b16 v119, v2 offset:6048
	v_cndmask_b32_e64 v2, v13, 0, s[50:51]
	v_cndmask_b32_e64 v3, v29, 0, s[52:53]
	v_add_f32_e32 v2, v2, v3
	v_cvt_pk_bf16_f32 v2, v2, v2
	ds_write_b16 v119, v2 offset:6384
	v_cndmask_b32_e64 v2, v14, 0, s[54:55]
	v_cndmask_b32_e64 v3, v30, 0, s[56:57]
	v_add_f32_e32 v2, v2, v3
	v_cvt_pk_bf16_f32 v2, v2, v2
	ds_write_b16 v119, v2 offset:8064
	v_cndmask_b32_e64 v2, v15, 0, s[84:85]
	v_cndmask_b32_e64 v3, v31, 0, s[60:61]
	v_add_f32_e32 v2, v2, v3
	v_cvt_pk_bf16_f32 v2, v2, v2
	ds_write_b16 v119, v2 offset:8400
	v_cndmask_b32_e64 v2, v16, 0, s[62:63]
	v_cndmask_b32_e64 v3, v32, 0, s[64:65]
	v_add_f32_e32 v2, v2, v3
	v_cvt_pk_bf16_f32 v2, v2, v2
	ds_write_b16 v119, v2 offset:8736
	v_cndmask_b32_e64 v2, v17, 0, s[66:67]
	v_cndmask_b32_e64 v3, v33, 0, s[68:69]
	v_add_f32_e32 v2, v2, v3
	v_cvt_pk_bf16_f32 v2, v2, v2
	ds_write_b16 v119, v2 offset:9072
	s_waitcnt lgkmcnt(0)
	s_barrier
	s_cbranch_scc1 .LBB0_465
	s_lshl_b32 s2, s77, 1
	s_add_i32 s2, s2, s89
	s_ashr_i32 s9, s2, 2
	s_cmpk_gt_i32 s9, 0x1ff
	s_mov_b64 s[0:1], -1
	s_cbranch_scc0 .LBB0_462
	s_lshl_b32 s0, s9, 6
	s_bfe_u32 s3, s2, 0x20002
	s_and_b32 s8, s0, 0xffffff00
	s_mov_b64 s[0:1], 0

;     __device__ __forceinline__ const float* in(int i) const { return (const float*)(const __attribute__((address_space(1))) float*)ld(i); }
; __device__ __forceinline__ void gla_prefetch(v4u& pz0, v4u& pz1, v4u& pw0, v4u& pw1, const KPD& kp, int l, int pair, int lane, int wave) {
;     const int half = wave >> 2, w4 = wave & 3, item = 2 * pair + half, h = item & 3, sc = item >> 2; int b, n, rowbase; chunk_coords(sc, b, n, rowbase);
;     const int dir = w4 >> 1, d0 = 24 * (w4 & 1);
;     const bf16* prow = (const bf16*)(kp.ws() + WS_P) + (size_t)(rowbase + lane) * INP;
;     pz0 = *(const v4u*)(prow + (dir ? C_ZB : C_ZF)); pz1 = *(const v4u*)(prow + (dir ? C_ZB : C_ZF) + 8);
;     const float* W = kp.in(I_GWDEC) + (size_t)((l * 2 + dir) * 16) * 192 + h * 48 + d0;
;     const float* bias = kp.in(I_GBDEC) + (l * 2 + dir) * 192 + h * 48 + d0;
;     unsigned w[6];
; #pragma unroll
;     for (int i = 0; i < 6; ++i) { const int e = lane + 64 * i; w[i] = __float_as_uint(W[(e / 24) * 192 + (e % 24)]); }
;     pw0 = (v4u){w[0], w[1], w[2], w[3]}; pw1 = (v4u){w[4], w[5], __float_as_uint(bias[lane < 24 ? lane : 0]), 0u};
; template <bool PHC>
; __device__ __forceinline__ void gla_pair(const KPD& kp, int l, int pair, unsigned char* lds, int tid, int lane, int wave, v4u& pz0, v4u& pz1, v4u& pw0, v4u& pw1, int next_pair) {
;     ...
;         f32x4 o6[6];
; #pragma unroll
;         for (int ct = 0; ct < 6; ++ct) o6[ct] = (f32x4){0.f, 0.f, 0.f, 0.f};
;         { const int q4 = fr >> 2, p4 = lane & 3;
; #pragma unroll
;           for (int ks = 0; ks < 2; ++ks) {
;               const bf16x8 a = *(const bf16x8*)(AC + (16 * w4 + fr) * 168 + 32 * ks + 8 * fq);
; #pragma unroll
;               for (int ct = 0; ct < 6; ++ct) { const bf16x8 bb = tr8(Vr + (32 * ks + 8 * fq + q4) * 104 + 16 * ct + 4 * p4, 4 * 104);
;                   o6[ct] = __builtin_amdgcn_mfma_f32_16x16x32_bf16(a, bb, o6[ct], 0, 0, 0); } }
; #pragma unroll
;           for (int ks = 2; ks < 5; ++ks) {
;               const bf16x8 a = *(const bf16x8*)(AC + (16 * w4 + fr) * 168 + 32 * ks + 8 * fq);
; #pragma unroll
;               for (int ct = 0; ct < 6; ++ct) { const bf16x8 bb = tr8(SB + (32 * (ks - 2) + 8 * fq + q4) * 104 + 16 * ct + 4 * p4, 4 * 104);
;                   o6[ct] = __builtin_amdgcn_mfma_f32_16x16x32_bf16(a, bb, o6[ct], 0, 0, 0); } } }
.LBB0_464:
	s_lshl_b32 s0, s3, 6
	s_add_i32 s0, s8, s0
	v_or_b32_e32 v4, s0, v80
	s_mov_b32 s77, s79
	s_waitcnt lgkmcnt(0)
	v_readlane_b32 s1, v255, 63
	v_readlane_b32 s3, v255, 62
	s_nop 0
	v_mov_b32_e32 v3, s1
	v_mov_b32_e32 v2, s3
	v_mad_i64_i32 v[2:3], s[0:1], v4, s33, v[2:3]
	v_lshl_add_u64 v[2:3], v[2:3], 0, s[76:77]
	s_mov_b64 s[0:1], 0x7800000
	v_lshl_add_u64 v[4:5], v[2:3], 0, s[0:1]
	s_mov_b32 s0, 0x7800000
	v_add_co_u32_e32 v2, vcc, s0, v2
	s_and_b32 s0, s2, 3
	s_nop 0
	v_addc_co_u32_e32 v3, vcc, 0, v3, vcc
	global_load_dwordx4 v[42:45], v[2:3], off
	global_load_dwordx4 v[46:49], v[4:5], off offset:16
	ds_read_b64 v[2:3], v207
	s_mul_i32 s3, s0, 0xc0
	s_waitcnt lgkmcnt(0)
	v_readfirstlane_b32 s2, v2
	v_readfirstlane_b32 s1, v3
	s_add_u32 s2, s2, s94
	s_addc_u32 s1, s1, s95
	ds_read_b64 v[2:3], v252
	s_add_u32 s0, s2, s3
	s_addc_u32 s1, s1, 0
	s_add_u32 s0, s0, s86
	s_addc_u32 s1, s1, 0
	global_load_dword v84, v120, s[0:1]
	global_load_dword v85, v121, s[0:1] offset:256
	global_load_dword v86, v122, s[0:1] offset:512
	global_load_dword v83, v123, s[0:1] offset:768
	global_load_dword v87, v124, s[0:1] offset:1024
	global_load_dword v88, v125, s[0:1] offset:1280
	s_waitcnt lgkmcnt(0)
	v_readfirstlane_b32 s1, v2
	v_readfirstlane_b32 s0, v3
	s_add_u32 s1, s1, s90
	s_addc_u32 s0, s0, s91
	s_add_u32 s1, s1, s3
	s_addc_u32 s2, s0, 0
	s_add_u32 s0, s1, s86
	s_addc_u32 s1, s2, 0
	global_load_dword v91, v126, s[0:1]
.LBB0_465:
	ds_read_b128 v[2:5], v106
	ds_read_b64_tr_b16 v[8:9], v107 offset:22336
	ds_read_b64_tr_b16 v[6:7], v107 offset:21504
	ds_read_b64_tr_b16 v[10:11], v107 offset:21536
	ds_read_b64_tr_b16 v[12:13], v107 offset:22368
	ds_read_b64_tr_b16 v[14:15], v107 offset:21568
	ds_read_b64_tr_b16 v[16:17], v107 offset:22400
	ds_read_b64_tr_b16 v[18:19], v107 offset:21600
	ds_read_b64_tr_b16 v[20:21], v107 offset:22432
	ds_read_b64_tr_b16 v[22:23], v107 offset:21632
	ds_read_b64_tr_b16 v[24:25], v107 offset:22464
	ds_read_b64_tr_b16 v[26:27], v107 offset:21664
	ds_read_b64_tr_b16 v[28:29], v107 offset:22496
	s_waitcnt lgkmcnt(10)
	v_mfma_f32_16x16x32_bf16 v[6:9], v[2:5], v[6:9], 0
	v_mov_b32_e32 v67, v35
	v_ashrrev_i32_e32 v65, 31, v64
	v_ashrrev_i32_e32 v63, 31, v62
	s_waitcnt lgkmcnt(8)
	v_mfma_f32_16x16x32_bf16 v[10:13], v[2:5], v[10:13], 0
	v_ashrrev_i32_e32 v53, 31, v52
	v_ashrrev_i32_e32 v51, 31, v50
	s_waitcnt lgkmcnt(6)
	v_mfma_f32_16x16x32_bf16 v[14:17], v[2:5], v[14:17], 0
	s_waitcnt lgkmcnt(4)
	v_mfma_f32_16x16x32_bf16 v[18:21], v[2:5], v[18:21], 0
	s_waitcnt lgkmcnt(2)
	v_mfma_f32_16x16x32_bf16 v[22:25], v[2:5], v[22:25], 0
	s_waitcnt lgkmcnt(0)
	v_mfma_f32_16x16x32_bf16 v[2:5], v[2:5], v[26:29], 0
	ds_read_b128 v[26:29], v106 offset:64
	ds_read_b64_tr_b16 v[30:31], v107 offset:28160
	ds_read_b64_tr_b16 v[32:33], v107 offset:28992
	s_waitcnt lgkmcnt(0)
	v_mfma_f32_16x16x32_bf16 v[6:9], v[26:29], v[30:33], v[6:9]
	ds_read_b64_tr_b16 v[30:31], v107 offset:28192
	ds_read_b64_tr_b16 v[32:33], v107 offset:29024
	s_waitcnt lgkmcnt(0)
	v_mfma_f32_16x16x32_bf16 v[10:13], v[26:29], v[30:33], v[10:13]
	ds_read_b64_tr_b16 v[30:31], v107 offset:28224
	ds_read_b64_tr_b16 v[32:33], v107 offset:29056
	s_waitcnt lgkmcnt(0)
	v_mfma_f32_16x16x32_bf16 v[14:17], v[26:29], v[30:33], v[14:17]
	ds_read_b64_tr_b16 v[30:31], v107 offset:28256
	ds_read_b64_tr_b16 v[32:33], v107 offset:29088
	s_waitcnt lgkmcnt(0)
	v_mfma_f32_16x16x32_bf16 v[18:21], v[26:29], v[30:33], v[18:21]
	ds_read_b64_tr_b16 v[30:31], v107 offset:28288
	ds_read_b64_tr_b16 v[32:33], v107 offset:29120
	s_waitcnt lgkmcnt(0)
	v_mfma_f32_16x16x32_bf16 v[22:25], v[26:29], v[30:33], v[22:25]
	ds_read_b64_tr_b16 v[30:31], v107 offset:28320
	ds_read_b64_tr_b16 v[32:33], v107 offset:29152
	s_waitcnt lgkmcnt(0)
	v_mfma_f32_16x16x32_bf16 v[2:5], v[26:29], v[30:33], v[2:5]
	ds_read_b128 v[26:29], v106 offset:128
	ds_read_b64_tr_b16 v[30:31], v107 offset:34816
	ds_read_b64_tr_b16 v[32:33], v107 offset:35648
	s_waitcnt lgkmcnt(0)
	v_mfma_f32_16x16x32_bf16 v[6:9], v[26:29], v[30:33], v[6:9]
	ds_read_b64_tr_b16 v[30:31], v107 offset:34848
	ds_read_b64_tr_b16 v[32:33], v107 offset:35680
	s_waitcnt lgkmcnt(0)
	v_mfma_f32_16x16x32_bf16 v[10:13], v[26:29], v[30:33], v[10:13]
	ds_read_b64_tr_b16 v[30:31], v107 offset:34880
	ds_read_b64_tr_b16 v[32:33], v107 offset:35712
	s_waitcnt lgkmcnt(0)
	v_mfma_f32_16x16x32_bf16 v[14:17], v[26:29], v[30:33], v[14:17]
	ds_read_b64_tr_b16 v[30:31], v107 offset:34912
	ds_read_b64_tr_b16 v[32:33], v107 offset:35744
	s_waitcnt lgkmcnt(0)
	v_mfma_f32_16x16x32_bf16 v[18:21], v[26:29], v[30:33], v[18:21]
	ds_read_b64_tr_b16 v[30:31], v107 offset:34944
	ds_read_b64_tr_b16 v[32:33], v107 offset:35776
	s_waitcnt lgkmcnt(0)
	v_mfma_f32_16x16x32_bf16 v[22:25], v[26:29], v[30:33], v[22:25]
	ds_read_b64_tr_b16 v[30:31], v107 offset:34976
	ds_read_b64_tr_b16 v[32:33], v107 offset:35808
	s_waitcnt lgkmcnt(0)
	v_mfma_f32_16x16x32_bf16 v[2:5], v[26:29], v[30:33], v[2:5]
	ds_read_b128 v[26:29], v106 offset:192
	ds_read_b64_tr_b16 v[30:31], v107 offset:41472
	ds_read_b64_tr_b16 v[32:33], v107 offset:42304
	s_waitcnt lgkmcnt(0)
	v_mfma_f32_16x16x32_bf16 v[6:9], v[26:29], v[30:33], v[6:9]
	ds_read_b64_tr_b16 v[30:31], v107 offset:41504
	ds_read_b64_tr_b16 v[32:33], v107 offset:42336
	s_waitcnt lgkmcnt(0)
	v_mfma_f32_16x16x32_bf16 v[10:13], v[26:29], v[30:33], v[10:13]
	ds_read_b64_tr_b16 v[30:31], v107 offset:41536
	ds_read_b64_tr_b16 v[32:33], v107 offset:42368
	s_waitcnt lgkmcnt(0)
	v_mfma_f32_16x16x32_bf16 v[30:33], v[26:29], v[30:33], v[14:17]
	s_nop 2
	ds_read_b64_tr_b16 v[14:15], v107 offset:41568
	ds_read_b64_tr_b16 v[16:17], v107 offset:42400
	s_waitcnt lgkmcnt(0)
;     __device__ __forceinline__ const float* in(int i) const { return (const float*)(const __attribute__((address_space(1))) float*)ld(i); }
;     __device__ __forceinline__ unsigned char* ws() const { return (unsigned char*)(__attribute__((address_space(1))) unsigned char*)ld(23); }
; __device__ __forceinline__ float bf2f(unsigned h) { return __uint_as_float(h << 16); }
; __device__ __forceinline__ unsigned f2bf(float f) { unsigned u = __float_as_uint(f); return (u + 0x7fffu + ((u >> 16) & 1u)) >> 16; }
; __device__ __forceinline__ float silu_f(float x) { return x * __builtin_amdgcn_rcpf(1.f + __expf(-x)); }
; __device__ __forceinline__ float row16_sum(float v) { v += dppf<0xB1>(v); v += dppf<0x4E>(v); v += dppf<0x141>(v); v += dppf<0x128>(v); return v; }
; template <bool PHC>
; __device__ __forceinline__ void gla_pair(const KPD& kp, int l, int pair, unsigned char* lds, int tid, int lane, int wave, v4u& pz0, v4u& pz1, v4u& pw0, v4u& pw1, int next_pair) {
;     ...
;         bf16* MIX = (bf16*)(kp.ws() + WS_MIX);
;         const float* gng = kp.in(I_GNG) + l * 96;
;         float gn6[6];
; #pragma unroll
;         for (int ct = 0; ct < 6; ++ct) gn6[ct] = gng[16 * ct + fr];
; #pragma unroll
;         for (int r = 0; r < 4; ++r) { float ssq = 0.f;
; #pragma unroll
;             for (int ct = 0; ct < 6; ++ct) ssq += o6[ct][r] * o6[ct][r];
;             ssq = row16_sum(ssq);
;             const float rstd = 1.0f / sqrtf(ssq * (1.f / 96.f) + EPS);
;             const int i = 16 * w4 + 4 * fq + r;
; #pragma unroll
;             for (int ct = 0; ct < 6; ++ct) MIX[(size_t)(rowbase + i) * D + h * 96 + 16 * ct + fr] = (bf16)f2bf(o6[ct][r] * rstd * gn6[ct] * silu_f(bf2f(gpre[r][ct]))); }
	v_mfma_f32_16x16x32_bf16 v[138:141], v[26:29], v[14:17], v[18:21]
	ds_read_b64_tr_b16 v[14:15], v107 offset:41600
	ds_read_b64_tr_b16 v[16:17], v107 offset:42432
	s_waitcnt lgkmcnt(0)
	v_mfma_f32_16x16x32_bf16 v[142:145], v[26:29], v[14:17], v[22:25]
	ds_read_b64_tr_b16 v[14:15], v107 offset:41632
	ds_read_b64_tr_b16 v[16:17], v107 offset:42464
	s_waitcnt lgkmcnt(0)
	v_mfma_f32_16x16x32_bf16 v[22:25], v[26:29], v[14:17], v[2:5]
	ds_read_b128 v[26:29], v106 offset:256
	s_nop 1
	ds_read_b64_tr_b16 v[2:3], v107 offset:48128
	ds_read_b64_tr_b16 v[4:5], v107 offset:48960
	s_waitcnt lgkmcnt(0)
	v_mfma_f32_16x16x32_bf16 v[18:21], v[26:29], v[2:5], v[6:9]
	ds_read_b64_tr_b16 v[2:3], v107 offset:48160
	ds_read_b64_tr_b16 v[4:5], v107 offset:48992
	s_waitcnt lgkmcnt(0)
	v_mfma_f32_16x16x32_bf16 v[14:17], v[26:29], v[2:5], v[10:13]
	ds_read_b64_tr_b16 v[2:3], v107 offset:48192
	ds_read_b64_tr_b16 v[4:5], v107 offset:49024
	s_waitcnt lgkmcnt(0)
	v_mfma_f32_16x16x32_bf16 v[10:13], v[26:29], v[2:5], v[30:33]
	ds_read_b64_tr_b16 v[2:3], v107 offset:48224
	ds_read_b64_tr_b16 v[4:5], v107 offset:49056
	s_waitcnt lgkmcnt(0)
	v_mfma_f32_16x16x32_bf16 v[6:9], v[26:29], v[2:5], v[138:141]
	ds_read_b64_tr_b16 v[2:3], v107 offset:48256
	ds_read_b64_tr_b16 v[4:5], v107 offset:49088
	ds_read_b64_tr_b16 v[30:31], v107 offset:48288
	ds_read_b64_tr_b16 v[32:33], v107 offset:49120
	s_waitcnt lgkmcnt(2)
	v_mfma_f32_16x16x32_bf16 v[2:5], v[26:29], v[2:5], v[142:145]
	s_waitcnt lgkmcnt(0)
	v_mfma_f32_16x16x32_bf16 v[22:25], v[26:29], v[30:33], v[22:25]
	v_mul_f32_e32 v28, v14, v14
	v_fmac_f32_e32 v28, v18, v18
	v_fmac_f32_e32 v28, v10, v10
	v_fmac_f32_e32 v28, v6, v6
	s_waitcnt lgkmcnt(0)
	v_readlane_b32 s3, v255, 62
	v_mov_b32_e32 v26, 0x26450
	v_readlane_b32 s2, v255, 63
	ds_read_b64 v[26:27], v26
	v_fmac_f32_e32 v28, v2, v2
	v_fmac_f32_e32 v28, v22, v22
	s_waitcnt lgkmcnt(0)
	v_readfirstlane_b32 s0, v26
	v_readfirstlane_b32 s1, v27
	s_add_u32 s0, s0, s92
	s_addc_u32 s1, s1, s93
	v_lshlrev_b32_e32 v26, 2, v36
	s_nop 1
	global_load_dword v132, v26, s[0:1]
	global_load_dword v130, v26, s[0:1] offset:64
	global_load_dword v33, v26, s[0:1] offset:128
	global_load_dword v32, v127, s[0:1]
	global_load_dword v31, v26, s[0:1] offset:256
	global_load_dword v30, v26, s[0:1] offset:320
	v_add_f32_dpp v28, v28, v28 quad_perm:[1,0,3,2] row_mask:0xf bank_mask:0xf bound_ctrl:1
	s_lshl_b32 s0, s78, 1
	s_add_u32 s0, s3, s0
	v_add_f32_dpp v28, v28, v28 quad_perm:[2,3,0,1] row_mask:0xf bank_mask:0xf bound_ctrl:1
	s_addc_u32 s1, s2, 0
	s_mov_b32 s2, 0xf800000
	v_add_f32_dpp v28, v28, v28 row_half_mirror row_mask:0xf bank_mask:0xf bound_ctrl:1
	v_lshl_add_u64 v[26:27], s[0:1], 0, v[66:67]
	s_mov_b64 s[0:1], 0x10e00000
	v_add_f32_dpp v28, v28, v28 row_ror:8 row_mask:0xf bank_mask:0xf bound_ctrl:1
	v_fmamk_f32 v28, v28, 0x3c2aaaab, v205
	v_cmp_gt_f32_e32 vcc, s2, v28
	v_mul_f32_e32 v29, 0x4f800000, v28
	v_lshl_add_u64 v[26:27], v[26:27], 0, s[0:1]
	v_cndmask_b32_e32 v28, v28, v29, vcc
	v_sqrt_f32_e32 v29, v28
	s_movk_i32 s3, 0x7fff
	s_cmp_ge_i32 s59, s88
	v_add_u32_e32 v38, -1, v29
	v_fma_f32 v39, -v38, v29, v28
	v_cmp_ge_f32_e64 s[0:1], 0, v39
	v_add_u32_e32 v39, 1, v29
	s_nop 0
	v_cndmask_b32_e64 v38, v29, v38, s[0:1]
	v_fma_f32 v29, -v39, v29, v28
	v_cmp_lt_f32_e64 s[0:1], 0, v29
	s_nop 1
	v_cndmask_b32_e64 v29, v38, v39, s[0:1]
	v_mul_f32_e32 v38, 0x37800000, v29
	v_cndmask_b32_e32 v29, v29, v38, vcc
	v_cmp_class_f32_e32 vcc, v28, v206
	s_nop 1
	v_cndmask_b32_e32 v28, v29, v28, vcc
	v_div_scale_f32 v29, s[0:1], v28, v28, 1.0
	v_rcp_f32_e32 v38, v29
	s_nop 0
	v_fma_f32 v39, -v29, v38, 1.0
	v_fmac_f32_e32 v38, v39, v38
	v_div_scale_f32 v39, vcc, 1.0, v28, 1.0
	v_mul_f32_e32 v40, v39, v38
	v_fma_f32 v41, -v29, v40, v39
	v_fmac_f32_e32 v40, v41, v38
	v_fma_f32 v29, -v29, v40, v39
	s_waitcnt vmcnt(29)
	v_lshlrev_b32_e32 v39, 16, v136
	v_div_fmas_f32 v29, v29, v38, v40
	v_mul_f32_e32 v40, 0xbfb8aa3b, v39
	v_exp_f32_e32 v40, v40
	v_div_fixup_f32 v38, v29, v28, 1.0
	v_mul_f32_e32 v18, v18, v38
	v_lshlrev_b64 v[28:29], 11, v[64:65]
	v_add_f32_e32 v40, 1.0, v40
	v_rcp_f32_e32 v40, v40
	v_lshl_add_u64 v[28:29], v[26:27], 0, v[28:29]
	v_mul_f32_e32 v14, v14, v38
	v_mul_f32_e32 v10, v10, v38
	v_mul_f32_e32 v39, v40, v39
	v_mul_f32_e32 v6, v6, v38
	v_mul_f32_e32 v2, v2, v38
	s_waitcnt vmcnt(5)
	v_mul_f32_e32 v18, v132, v18
	v_mul_f32_e32 v18, v39, v18
	v_bfe_u32 v39, v18, 16, 1
	v_add3_u32 v18, v18, v39, s3
	global_store_short_d16_hi v[28:29], v18, off
	v_lshlrev_b32_e32 v18, 16, v135
	v_mul_f32_e32 v39, 0xbfb8aa3b, v18
	v_exp_f32_e32 v39, v39
	s_waitcnt vmcnt(5)
	v_mul_f32_e32 v14, v130, v14
	s_waitcnt vmcnt(4)
	v_mul_f32_e32 v10, v33, v10
	s_waitcnt vmcnt(3)
	v_mul_f32_e32 v6, v32, v6
	v_add_f32_e32 v39, 1.0, v39
	v_rcp_f32_e32 v39, v39
	s_waitcnt vmcnt(2)
	v_mul_f32_e32 v2, v31, v2
	v_mul_f32_e32 v18, v39, v18
	v_mul_f32_e32 v14, v18, v14
	v_bfe_u32 v18, v14, 16, 1
	v_add3_u32 v14, v14, v18, s3
	global_store_short_d16_hi v[28:29], v14, off offset:32
	v_lshlrev_b32_e32 v14, 16, v134
	v_mul_f32_e32 v18, 0xbfb8aa3b, v14
	v_exp_f32_e32 v18, v18
	s_nop 0
	v_add_f32_e32 v18, 1.0, v18
	v_rcp_f32_e32 v18, v18
	s_nop 0
	v_mul_f32_e32 v14, v18, v14
	v_mul_f32_e32 v10, v14, v10
	v_bfe_u32 v14, v10, 16, 1
	v_add3_u32 v10, v10, v14, s3
	global_store_short_d16_hi v[28:29], v10, off offset:64
	v_lshlrev_b32_e32 v10, 16, v133
	v_mul_f32_e32 v14, 0xbfb8aa3b, v10
	v_exp_f32_e32 v14, v14
	s_nop 0
	v_add_f32_e32 v14, 1.0, v14
	v_rcp_f32_e32 v14, v14
	s_nop 0
	v_mul_f32_e32 v10, v14, v10
	v_mul_f32_e32 v6, v10, v6
	v_bfe_u32 v10, v6, 16, 1
	v_add3_u32 v6, v6, v10, s3
	global_store_short_d16_hi v[28:29], v6, off offset:96
	v_lshlrev_b32_e32 v6, 16, v131
	v_mul_f32_e32 v10, 0xbfb8aa3b, v6
	v_exp_f32_e32 v10, v10
	s_nop 0
	v_add_f32_e32 v10, 1.0, v10
	v_rcp_f32_e32 v10, v10
	s_nop 0
	v_mul_f32_e32 v6, v10, v6
	v_mul_f32_e32 v2, v6, v2
	v_bfe_u32 v6, v2, 16, 1
	v_add3_u32 v2, v2, v6, s3
	v_lshlrev_b32_e32 v6, 16, v129
	v_mul_f32_e32 v10, 0xbfb8aa3b, v6
	v_exp_f32_e32 v10, v10
	global_store_short_d16_hi v[28:29], v2, off offset:128
	v_mul_f32_e32 v2, v22, v38
	s_waitcnt vmcnt(5)
; __device__ __forceinline__ float bf2f(unsigned h) { return __uint_as_float(h << 16); }
; __device__ __forceinline__ unsigned f2bf(float f) { unsigned u = __float_as_uint(f); return (u + 0x7fffu + ((u >> 16) & 1u)) >> 16; }
; __device__ __forceinline__ float silu_f(float x) { return x * __builtin_amdgcn_rcpf(1.f + __expf(-x)); }
; __device__ __forceinline__ float row16_sum(float v) { v += dppf<0xB1>(v); v += dppf<0x4E>(v); v += dppf<0x141>(v); v += dppf<0x128>(v); return v; }
; template <bool PHC>
; __device__ __forceinline__ void gla_pair(const KPD& kp, int l, int pair, unsigned char* lds, int tid, int lane, int wave, v4u& pz0, v4u& pz1, v4u& pw0, v4u& pw1, int next_pair) {
;     ...
;         for (int r = 0; r < 4; ++r) { float ssq = 0.f;
; #pragma unroll
;             for (int ct = 0; ct < 6; ++ct) ssq += o6[ct][r] * o6[ct][r];
;             ssq = row16_sum(ssq);
;             const float rstd = 1.0f / sqrtf(ssq * (1.f / 96.f) + EPS);
;             const int i = 16 * w4 + 4 * fq + r;
; #pragma unroll
;             for (int ct = 0; ct < 6; ++ct) MIX[(size_t)(rowbase + i) * D + h * 96 + 16 * ct + fr] = (bf16)f2bf(o6[ct][r] * rstd * gn6[ct] * silu_f(bf2f(gpre[r][ct]))); }
	v_mul_f32_e32 v2, v30, v2
	v_add_f32_e32 v10, 1.0, v10
	v_rcp_f32_e32 v10, v10
	s_nop 0
	v_mul_f32_e32 v6, v10, v6
	v_mul_f32_e32 v2, v6, v2
	v_bfe_u32 v6, v2, 16, 1
	v_add3_u32 v2, v2, v6, s3
	global_store_short_d16_hi v[28:29], v2, off offset:160
	v_mul_f32_e32 v2, v15, v15
	v_fmac_f32_e32 v2, v19, v19
	v_fmac_f32_e32 v2, v11, v11
	v_fmac_f32_e32 v2, v7, v7
	v_fmac_f32_e32 v2, v3, v3
	v_fmac_f32_e32 v2, v23, v23
	v_lshlrev_b64 v[28:29], 11, v[62:63]
	v_lshl_add_u64 v[28:29], v[26:27], 0, v[28:29]
	v_add_f32_dpp v2, v2, v2 quad_perm:[1,0,3,2] row_mask:0xf bank_mask:0xf bound_ctrl:1
	s_nop 1
	v_add_f32_dpp v2, v2, v2 quad_perm:[2,3,0,1] row_mask:0xf bank_mask:0xf bound_ctrl:1
	s_nop 1
	v_add_f32_dpp v2, v2, v2 row_half_mirror row_mask:0xf bank_mask:0xf bound_ctrl:1
	s_nop 1
	v_add_f32_dpp v2, v2, v2 row_ror:8 row_mask:0xf bank_mask:0xf bound_ctrl:1
	v_fmamk_f32 v2, v2, 0x3c2aaaab, v205
	v_cmp_gt_f32_e32 vcc, s2, v2
	v_mul_f32_e32 v6, 0x4f800000, v2
	s_nop 0
	v_cndmask_b32_e32 v2, v2, v6, vcc
	v_sqrt_f32_e32 v6, v2
	s_nop 0
	v_add_u32_e32 v10, -1, v6
	v_fma_f32 v14, -v10, v6, v2
	v_cmp_ge_f32_e64 s[0:1], 0, v14
	v_add_u32_e32 v14, 1, v6
	s_nop 0
	v_cndmask_b32_e64 v10, v6, v10, s[0:1]
	v_fma_f32 v6, -v14, v6, v2
	v_cmp_lt_f32_e64 s[0:1], 0, v6
	s_nop 1
	v_cndmask_b32_e64 v6, v10, v14, s[0:1]
	v_mul_f32_e32 v10, 0x37800000, v6
	v_cndmask_b32_e32 v6, v6, v10, vcc
	v_cmp_class_f32_e32 vcc, v2, v206
	s_nop 1
	v_cndmask_b32_e32 v2, v6, v2, vcc
	v_div_scale_f32 v6, s[0:1], v2, v2, 1.0
	v_rcp_f32_e32 v10, v6
	s_nop 0
	v_fma_f32 v14, -v6, v10, 1.0
	v_fmac_f32_e32 v10, v14, v10
	v_div_scale_f32 v14, vcc, 1.0, v2, 1.0
	v_mul_f32_e32 v18, v14, v10
	v_fma_f32 v22, -v6, v18, v14
	v_fmac_f32_e32 v18, v22, v10
	v_fma_f32 v6, -v6, v18, v14
	v_div_fmas_f32 v6, v6, v10, v18
	v_lshlrev_b32_e32 v10, 16, v128
	v_mul_f32_e32 v14, 0xbfb8aa3b, v10
	v_exp_f32_e32 v14, v14
	v_div_fixup_f32 v2, v6, v2, 1.0
	v_mul_f32_e32 v6, v19, v2
	v_mul_f32_e32 v6, v132, v6
	v_add_f32_e32 v14, 1.0, v14
	v_rcp_f32_e32 v14, v14
	v_mul_f32_e32 v3, v3, v2
	v_mul_f32_e32 v3, v31, v3
	v_mul_f32_e32 v10, v14, v10
	v_mul_f32_e32 v6, v10, v6
	v_bfe_u32 v10, v6, 16, 1
	v_add3_u32 v6, v6, v10, s3
	v_lshlrev_b32_e32 v10, 16, v79
	v_mul_f32_e32 v14, 0xbfb8aa3b, v10
	v_exp_f32_e32 v14, v14
	global_store_short_d16_hi v[28:29], v6, off
	v_mul_f32_e32 v6, v15, v2
	v_mul_f32_e32 v6, v130, v6
	v_add_f32_e32 v14, 1.0, v14
	v_rcp_f32_e32 v14, v14
	s_nop 0
	v_mul_f32_e32 v10, v14, v10
	v_mul_f32_e32 v6, v10, v6
	v_bfe_u32 v10, v6, 16, 1
	v_add3_u32 v6, v6, v10, s3
	v_lshlrev_b32_e32 v10, 16, v78
	global_store_short_d16_hi v[28:29], v6, off offset:32
	v_mul_f32_e32 v6, v11, v2
	v_mul_f32_e32 v11, 0xbfb8aa3b, v10
	v_exp_f32_e32 v11, v11
	v_mul_f32_e32 v6, v33, v6
	v_add_f32_e32 v11, 1.0, v11
	v_rcp_f32_e32 v11, v11
	s_nop 0
	v_mul_f32_e32 v10, v11, v10
	v_mul_f32_e32 v6, v10, v6
	v_bfe_u32 v10, v6, 16, 1
	v_add3_u32 v6, v6, v10, s3
	global_store_short_d16_hi v[28:29], v6, off offset:64
	v_mul_f32_e32 v6, v7, v2
	v_lshlrev_b32_e32 v7, 16, v77
	v_mul_f32_e32 v10, 0xbfb8aa3b, v7
	v_exp_f32_e32 v10, v10
	v_mul_f32_e32 v6, v32, v6
	v_mul_f32_e32 v2, v23, v2
	v_mul_f32_e32 v2, v30, v2
	v_add_f32_e32 v10, 1.0, v10
	v_rcp_f32_e32 v10, v10
	s_nop 0
	v_mul_f32_e32 v7, v10, v7
	v_mul_f32_e32 v6, v7, v6
	v_bfe_u32 v7, v6, 16, 1
	v_add3_u32 v6, v6, v7, s3
	global_store_short_d16_hi v[28:29], v6, off offset:96
	v_lshlrev_b32_e32 v6, 16, v76
	v_mul_f32_e32 v7, 0xbfb8aa3b, v6
	v_exp_f32_e32 v7, v7
	s_nop 0
	v_add_f32_e32 v7, 1.0, v7
	v_rcp_f32_e32 v7, v7
	s_nop 0
	v_mul_f32_e32 v6, v7, v6
	v_mul_f32_e32 v3, v6, v3
	v_bfe_u32 v6, v3, 16, 1
	v_add3_u32 v3, v3, v6, s3
	global_store_short_d16_hi v[28:29], v3, off offset:128
	v_lshlrev_b32_e32 v3, 16, v75
	v_mul_f32_e32 v6, 0xbfb8aa3b, v3
	v_exp_f32_e32 v6, v6
	s_nop 0
	v_add_f32_e32 v6, 1.0, v6
	v_rcp_f32_e32 v6, v6
	s_nop 0
	v_mul_f32_e32 v3, v6, v3
	v_mul_f32_e32 v2, v3, v2
	v_bfe_u32 v3, v2, 16, 1
	v_add3_u32 v2, v2, v3, s3
	global_store_short_d16_hi v[28:29], v2, off offset:160
	v_mul_f32_e32 v2, v16, v16
	v_fmac_f32_e32 v2, v20, v20
	v_fmac_f32_e32 v2, v12, v12
	v_fmac_f32_e32 v2, v8, v8
	v_fmac_f32_e32 v2, v4, v4
	v_fmac_f32_e32 v2, v24, v24
	s_nop 1
	v_add_f32_dpp v2, v2, v2 quad_perm:[1,0,3,2] row_mask:0xf bank_mask:0xf bound_ctrl:1
	s_nop 1
	v_add_f32_dpp v2, v2, v2 quad_perm:[2,3,0,1] row_mask:0xf bank_mask:0xf bound_ctrl:1
	s_nop 1
	v_add_f32_dpp v2, v2, v2 row_half_mirror row_mask:0xf bank_mask:0xf bound_ctrl:1
	s_nop 1
	v_add_f32_dpp v2, v2, v2 row_ror:8 row_mask:0xf bank_mask:0xf bound_ctrl:1
	v_fmamk_f32 v2, v2, 0x3c2aaaab, v205
	v_cmp_gt_f32_e32 vcc, s2, v2
	v_mul_f32_e32 v3, 0x4f800000, v2
	s_nop 0
	v_cndmask_b32_e32 v2, v2, v3, vcc
	v_sqrt_f32_e32 v3, v2
	s_nop 0
	v_add_u32_e32 v6, -1, v3
	v_fma_f32 v7, -v6, v3, v2
	v_cmp_ge_f32_e64 s[0:1], 0, v7
	v_add_u32_e32 v7, 1, v3
	s_nop 0
	v_cndmask_b32_e64 v6, v3, v6, s[0:1]
	v_fma_f32 v3, -v7, v3, v2
	v_cmp_lt_f32_e64 s[0:1], 0, v3
	s_nop 1
	v_cndmask_b32_e64 v3, v6, v7, s[0:1]
	v_mul_f32_e32 v6, 0x37800000, v3
	v_cndmask_b32_e32 v3, v3, v6, vcc
	v_cmp_class_f32_e32 vcc, v2, v206
	s_nop 1
	v_cndmask_b32_e32 v2, v3, v2, vcc
	v_div_scale_f32 v3, s[0:1], v2, v2, 1.0
	v_rcp_f32_e32 v6, v3
	s_nop 0
	v_fma_f32 v7, -v3, v6, 1.0
	v_fmac_f32_e32 v6, v7, v6
	v_div_scale_f32 v7, vcc, 1.0, v2, 1.0
	v_mul_f32_e32 v10, v7, v6
	v_fma_f32 v11, -v3, v10, v7
	v_fmac_f32_e32 v10, v11, v6
	v_fma_f32 v3, -v3, v10, v7
	v_div_fmas_f32 v3, v3, v6, v10
	v_lshlrev_b32_e32 v10, 16, v74
	v_mul_f32_e32 v11, 0xbfb8aa3b, v10
	v_exp_f32_e32 v11, v11
	v_div_fixup_f32 v6, v3, v2, 1.0
	v_mul_f32_e32 v7, v20, v6
	v_mul_f32_e32 v7, v132, v7
; __device__ __forceinline__ float bf2f(unsigned h) { return __uint_as_float(h << 16); }
; __device__ __forceinline__ unsigned f2bf(float f) { unsigned u = __float_as_uint(f); return (u + 0x7fffu + ((u >> 16) & 1u)) >> 16; }
; __device__ __forceinline__ float silu_f(float x) { return x * __builtin_amdgcn_rcpf(1.f + __expf(-x)); }
; __device__ __forceinline__ float row16_sum(float v) { v += dppf<0xB1>(v); v += dppf<0x4E>(v); v += dppf<0x141>(v); v += dppf<0x128>(v); return v; }
; template <bool PHC>
; __device__ __forceinline__ void gla_pair(const KPD& kp, int l, int pair, unsigned char* lds, int tid, int lane, int wave, v4u& pz0, v4u& pz1, v4u& pw0, v4u& pw1, int next_pair) {
;     ...
;         for (int r = 0; r < 4; ++r) { float ssq = 0.f;
; #pragma unroll
;             for (int ct = 0; ct < 6; ++ct) ssq += o6[ct][r] * o6[ct][r];
;             ssq = row16_sum(ssq);
;             const float rstd = 1.0f / sqrtf(ssq * (1.f / 96.f) + EPS);
;             const int i = 16 * w4 + 4 * fq + r;
; #pragma unroll
;             for (int ct = 0; ct < 6; ++ct) MIX[(size_t)(rowbase + i) * D + h * 96 + 16 * ct + fr] = (bf16)f2bf(o6[ct][r] * rstd * gn6[ct] * silu_f(bf2f(gpre[r][ct]))); }
; __global__ void __launch_bounds__(512, 2) fwd_kernel(KP kparg) {
;     ...
;               const int nx = (G == 256) ? XITEM(it + G) : it + G; gla_pair<true>(kp, l, item, lds, tid, lane, wave, gz0, gz1, gw0, gw1, nx < ngl ? nx : -1); __syncthreads(); }
	v_add_f32_e32 v11, 1.0, v11
	v_rcp_f32_e32 v11, v11
	v_lshlrev_b64 v[2:3], 11, v[52:53]
	v_lshl_add_u64 v[2:3], v[26:27], 0, v[2:3]
	v_mul_f32_e32 v4, v4, v6
	v_mul_f32_e32 v10, v11, v10
	v_mul_f32_e32 v7, v10, v7
	v_bfe_u32 v10, v7, 16, 1
	v_add3_u32 v7, v7, v10, s3
	v_lshlrev_b32_e32 v10, 16, v73
	v_mul_f32_e32 v11, 0xbfb8aa3b, v10
	v_exp_f32_e32 v11, v11
	global_store_short_d16_hi v[2:3], v7, off
	v_mul_f32_e32 v7, v16, v6
	v_mul_f32_e32 v7, v130, v7
	v_add_f32_e32 v11, 1.0, v11
	v_rcp_f32_e32 v11, v11
	v_mul_f32_e32 v4, v31, v4
	v_mul_f32_e32 v10, v11, v10
	v_mul_f32_e32 v7, v10, v7
	v_bfe_u32 v10, v7, 16, 1
	v_add3_u32 v7, v7, v10, s3
	v_lshlrev_b32_e32 v10, 16, v72
	v_mul_f32_e32 v11, 0xbfb8aa3b, v10
	v_exp_f32_e32 v11, v11
	global_store_short_d16_hi v[2:3], v7, off offset:32
	v_mul_f32_e32 v7, v12, v6
	v_mul_f32_e32 v7, v33, v7
	v_add_f32_e32 v11, 1.0, v11
	v_rcp_f32_e32 v11, v11
	s_nop 0
	v_mul_f32_e32 v10, v11, v10
	v_mul_f32_e32 v7, v10, v7
	v_bfe_u32 v10, v7, 16, 1
	v_add3_u32 v7, v7, v10, s3
	global_store_short_d16_hi v[2:3], v7, off offset:64
	v_mul_f32_e32 v7, v8, v6
	v_lshlrev_b32_e32 v8, 16, v71
	v_mul_f32_e32 v10, 0xbfb8aa3b, v8
	v_exp_f32_e32 v10, v10
	v_mul_f32_e32 v7, v32, v7
	v_add_f32_e32 v10, 1.0, v10
	v_rcp_f32_e32 v10, v10
	s_nop 0
	v_mul_f32_e32 v8, v10, v8
	v_mul_f32_e32 v7, v8, v7
	v_bfe_u32 v8, v7, 16, 1
	v_add3_u32 v7, v7, v8, s3
	global_store_short_d16_hi v[2:3], v7, off offset:96
	v_lshlrev_b32_e32 v7, 16, v70
	v_mul_f32_e32 v8, 0xbfb8aa3b, v7
	v_exp_f32_e32 v8, v8
	s_nop 0
	v_add_f32_e32 v8, 1.0, v8
	v_rcp_f32_e32 v8, v8
	s_nop 0
	v_mul_f32_e32 v7, v8, v7
	v_mul_f32_e32 v4, v7, v4
	v_bfe_u32 v7, v4, 16, 1
	v_add3_u32 v4, v4, v7, s3
	global_store_short_d16_hi v[2:3], v4, off offset:128
	v_mul_f32_e32 v4, v24, v6
	v_lshlrev_b32_e32 v6, 16, v69
	v_mul_f32_e32 v7, 0xbfb8aa3b, v6
	v_exp_f32_e32 v7, v7
	v_mul_f32_e32 v4, v30, v4
	v_add_f32_e32 v7, 1.0, v7
	v_rcp_f32_e32 v7, v7
	s_nop 0
	v_mul_f32_e32 v6, v7, v6
	v_mul_f32_e32 v4, v6, v4
	v_bfe_u32 v6, v4, 16, 1
	v_add3_u32 v4, v4, v6, s3
	global_store_short_d16_hi v[2:3], v4, off offset:160
	v_mul_f32_e32 v2, v17, v17
	v_fmac_f32_e32 v2, v21, v21
	v_fmac_f32_e32 v2, v13, v13
	v_fmac_f32_e32 v2, v9, v9
	v_fmac_f32_e32 v2, v5, v5
	v_fmac_f32_e32 v2, v25, v25
	s_nop 1
	v_add_f32_dpp v2, v2, v2 quad_perm:[1,0,3,2] row_mask:0xf bank_mask:0xf bound_ctrl:1
	s_nop 1
	v_add_f32_dpp v2, v2, v2 quad_perm:[2,3,0,1] row_mask:0xf bank_mask:0xf bound_ctrl:1
	s_nop 1
	v_add_f32_dpp v2, v2, v2 row_half_mirror row_mask:0xf bank_mask:0xf bound_ctrl:1
	s_nop 1
	v_add_f32_dpp v2, v2, v2 row_ror:8 row_mask:0xf bank_mask:0xf bound_ctrl:1
	v_fmamk_f32 v2, v2, 0x3c2aaaab, v205
	v_cmp_gt_f32_e32 vcc, s2, v2
	v_mul_f32_e32 v3, 0x4f800000, v2
	s_nop 0
	v_cndmask_b32_e32 v2, v2, v3, vcc
	v_sqrt_f32_e32 v3, v2
	s_nop 0
	v_add_u32_e32 v4, -1, v3
	v_fma_f32 v6, -v4, v3, v2
	v_cmp_ge_f32_e64 s[0:1], 0, v6
	v_add_u32_e32 v6, 1, v3
	s_nop 0
	v_cndmask_b32_e64 v4, v3, v4, s[0:1]
	v_fma_f32 v3, -v6, v3, v2
	v_cmp_lt_f32_e64 s[0:1], 0, v3
	s_nop 1
	v_cndmask_b32_e64 v3, v4, v6, s[0:1]
	v_mul_f32_e32 v4, 0x37800000, v3
	v_cndmask_b32_e32 v3, v3, v4, vcc
	v_cmp_class_f32_e32 vcc, v2, v206
	s_nop 1
	v_cndmask_b32_e32 v2, v3, v2, vcc
	v_div_scale_f32 v3, s[0:1], v2, v2, 1.0
	v_rcp_f32_e32 v4, v3
	s_cselect_b64 s[0:1], -1, 0
	v_fma_f32 v6, -v3, v4, 1.0
	v_fmac_f32_e32 v4, v6, v4
	v_div_scale_f32 v6, vcc, 1.0, v2, 1.0
	v_mul_f32_e32 v7, v6, v4
	v_fma_f32 v8, -v3, v7, v6
	v_fmac_f32_e32 v7, v8, v4
	v_fma_f32 v3, -v3, v7, v6
	v_div_fmas_f32 v3, v3, v4, v7
	v_lshlrev_b32_e32 v7, 16, v68
	v_mul_f32_e32 v8, 0xbfb8aa3b, v7
	v_exp_f32_e32 v8, v8
	v_div_fixup_f32 v4, v3, v2, 1.0
	v_mul_f32_e32 v6, v21, v4
	v_mul_f32_e32 v6, v132, v6
	v_add_f32_e32 v8, 1.0, v8
	v_rcp_f32_e32 v8, v8
	v_lshlrev_b64 v[2:3], 11, v[50:51]
	v_lshl_add_u64 v[2:3], v[26:27], 0, v[2:3]
	v_mul_f32_e32 v5, v5, v4
	v_mul_f32_e32 v7, v8, v7
	v_mul_f32_e32 v6, v7, v6
	v_bfe_u32 v7, v6, 16, 1
	v_add3_u32 v6, v6, v7, s3
	v_lshlrev_b32_e32 v7, 16, v61
	v_mul_f32_e32 v8, 0xbfb8aa3b, v7
	v_exp_f32_e32 v8, v8
	global_store_short_d16_hi v[2:3], v6, off
	v_mul_f32_e32 v6, v17, v4
	v_mul_f32_e32 v6, v130, v6
	v_add_f32_e32 v8, 1.0, v8
	v_rcp_f32_e32 v8, v8
	v_mul_f32_e32 v5, v31, v5
	v_mul_f32_e32 v7, v8, v7
	v_mul_f32_e32 v6, v7, v6
	v_bfe_u32 v7, v6, 16, 1
	v_add3_u32 v6, v6, v7, s3
	v_lshlrev_b32_e32 v7, 16, v60
	v_mul_f32_e32 v8, 0xbfb8aa3b, v7
	v_exp_f32_e32 v8, v8
	global_store_short_d16_hi v[2:3], v6, off offset:32
	v_mul_f32_e32 v6, v13, v4
	v_mul_f32_e32 v6, v33, v6
	v_add_f32_e32 v8, 1.0, v8
	v_rcp_f32_e32 v8, v8
	s_nop 0
	v_mul_f32_e32 v7, v8, v7
	v_mul_f32_e32 v6, v7, v6
	v_bfe_u32 v7, v6, 16, 1
	v_add3_u32 v6, v6, v7, s3
	v_lshlrev_b32_e32 v7, 16, v59
	v_mul_f32_e32 v8, 0xbfb8aa3b, v7
	v_exp_f32_e32 v8, v8
	global_store_short_d16_hi v[2:3], v6, off offset:64
	v_mul_f32_e32 v6, v9, v4
	v_mul_f32_e32 v6, v32, v6
	v_add_f32_e32 v8, 1.0, v8
	v_rcp_f32_e32 v8, v8
	v_mul_f32_e32 v4, v25, v4
	v_mul_f32_e32 v4, v30, v4
	v_mul_f32_e32 v7, v8, v7
	v_mul_f32_e32 v6, v7, v6
	v_bfe_u32 v7, v6, 16, 1
	v_add3_u32 v6, v6, v7, s3
	global_store_short_d16_hi v[2:3], v6, off offset:96
	v_lshlrev_b32_e32 v6, 16, v57
	v_mul_f32_e32 v7, 0xbfb8aa3b, v6
	v_exp_f32_e32 v7, v7
	s_nop 0
	v_add_f32_e32 v7, 1.0, v7
	v_rcp_f32_e32 v7, v7
	s_nop 0
	v_mul_f32_e32 v6, v7, v6
	v_mul_f32_e32 v5, v6, v5
	v_bfe_u32 v6, v5, 16, 1
	v_add3_u32 v5, v5, v6, s3
	global_store_short_d16_hi v[2:3], v5, off offset:128
	v_lshlrev_b32_e32 v5, 16, v55
	v_mul_f32_e32 v6, 0xbfb8aa3b, v5
	v_exp_f32_e32 v6, v6
	s_nop 0
	v_add_f32_e32 v6, 1.0, v6
	v_rcp_f32_e32 v6, v6
	s_nop 0
	v_mul_f32_e32 v5, v6, v5
	v_mul_f32_e32 v4, v5, v4
	v_bfe_u32 v5, v4, 16, 1
	v_add3_u32 v4, v4, v5, s3
	global_store_short_d16_hi v[2:3], v4, off offset:160
	s_barrier
	s_and_b64 vcc, exec, s[0:1]
	s_cbranch_vccz .LBB0_454

; __device__ __forceinline__ void swa_item(const KPD& kp, int l, int item, unsigned char* lds, int tid, int lane, int wave) {
;     ...
;     if (!isctx) { kvh = item & 1; qblk = (item >> 1) & 63; b = item >> 7; qrow0 = b * SEQ + qblk * 128; }
;     else { const int j = item - 512; kvh = j & 1; qblk = (j >> 1) & 1; b = j >> 2; qrow0 = MLAT + b * CTXL + qblk * 128; }
;     const bf16* P = (const bf16*)(kp.ws() + WS_P);
;     bf16* Kt = (bf16*)lds;
;     bf16* Vs = (bf16*)(lds + 18432);
;     const int fr = lane & 15, fq = lane >> 4;
;     bf16x8 qf[3][2];
; #pragma unroll
;     for (int hh = 0; hh < 3; ++hh)
; #pragma unroll
;         for (int ks = 0; ks < 2; ++ks) qf[hh][ks] = *(const bf16x8*)(P + (size_t)(qrow0 + 16 * wave + fr) * INP + C_AQ + (kvh * 3 + hh) * 64 + 32 * ks + 8 * fq);
;     float mrow[3], lrow[3]; f32x4 O[3][4];
; #pragma unroll
;     for (int hh = 0; hh < 3; ++hh) { mrow[hh] = kp.in(I_SINK)[l * 6 + kvh * 3 + hh] * 1.4426950408889634f; lrow[hh] = (fq == 0) ? 1.f : 0.f;
; #pragma unroll
;         for (int dt = 0; dt < 4; ++dt) O[hh][dt] = (f32x4){0.f, 0.f, 0.f, 0.f}; }
;     int nt = 0; int krow[5]; int kmode[5];
; #pragma unroll
;     for (int kt = 0; kt < 5; ++kt) { krow[kt] = 0; kmode[kt] = 0; }
;     int t0 = 0;
;     if (!isctx) {
;         if (qblk > 0) { krow[0] = b * SEQ + (qblk - 1) * 128; kmode[0] = 1; t0 = 1; }
;     }
;     const bool hasprev = !isctx && qblk > 0, hascur = !isctx, hasnext = !isctx && qblk < 63;
;     const int s_prev = 0, s_next = hasprev ? 1 : 0, s_cur = s_next + (hasnext ? 1 : 0), s_c0 = s_cur + (hascur ? 1 : 0), s_c1 = s_c0 + 1;
;     nt = s_c1 + 1;
;     (void)t0; (void)s_prev;
;     auto tile_row = [&](int i) -> int {
;         if (hasprev && i == 0) return b * SEQ + (qblk - 1) * 128;
;         if (hasnext && i == s_next) return b * SEQ + (qblk + 1) * 128;
;         if (hascur && i == s_cur) return b * SEQ + qblk * 128;
;         if (i == s_c0) return MLAT + b * CTXL;
;         return MLAT + b * CTXL + 128; };
;     auto tile_mode = [&](int i) -> int { if (hasprev && i == 0) return 1; if (hasnext && i == s_next) return 2; return 0; };
;     v4u kpre[4], vpre2[4];
;     const int nstage = (nt + 1) >> 1;
;     ...
;     SWA_LOAD_STAGE(0);
;     const int q4 = (lane & 15) >> 2, p4 = lane & 3;
; #pragma unroll 1
;     for (int st = 0; st < nstage; ++st) {
;         const int ta = 2 * st, ntl = (nt - ta) < 2 ? (nt - ta) : 2;
.LBB0_467:
	v_readlane_b32 s0, v253, 20
	v_readlane_b32 s1, v253, 21
	s_and_b64 s[0:1], s[46:47], s[0:1]
	s_andn2_b64 vcc, exec, s[0:1]
	s_movk_i32 s87, 0x3000
	s_mov_b32 s88, 0xf800000
	s_cbranch_vccnz .LBB0_477
	v_and_b32_e32 v134, 15, v81
	v_readlane_b32 s2, v253, 22
	v_and_b32_e32 v34, 48, v80
	v_readlane_b32 s4, v254, 22
	s_waitcnt lgkmcnt(0)
	v_readlane_b32 s0, v255, 62
	v_readlane_b32 s1, v255, 63
	s_add_u32 s0, s0, 0x7800000
	s_addc_u32 s1, s1, 0
	v_or_b32_e32 v2, s2, v134
	v_lshl_add_u32 v130, s13, 4, v2
	v_mov_b64_e32 v[2:3], s[0:1]
	v_mad_i64_i32 v[2:3], s[2:3], v130, s33, v[2:3]
	v_readlane_b32 s2, v254, 15
	v_lshl_add_u64 v[2:3], v[2:3], 0, v[34:35]
	s_lshl_b32 s78, s2, 1
	s_waitcnt vmcnt(7)
	v_lshl_add_u64 v[22:23], v[2:3], 0, s[78:79]
	global_load_dwordx4 v[2:5], v[22:23], off offset:2368
	global_load_dwordx4 v[6:9], v[22:23], off offset:2432
	global_load_dwordx4 v[10:13], v[22:23], off offset:2496
	global_load_dwordx4 v[14:17], v[22:23], off offset:2560
	global_load_dwordx4 v[18:21], v[22:23], off offset:2624
	s_nop 0
	global_load_dwordx4 v[22:25], v[22:23], off offset:2688
	s_waitcnt vmcnt(11)
	ds_read_b64 v[26:27], v215
	s_waitcnt vmcnt(8)
	v_mov_b32_e32 v30, s4
	v_add_u32_e32 v39, 0x200, v81
	v_ashrrev_i32_e32 v38, 3, v81
	v_ashrrev_i32_e32 v39, 3, v39
	s_waitcnt lgkmcnt(0)
	v_readfirstlane_b32 s3, v27
	v_readfirstlane_b32 s2, v26
	v_cmp_gt_u32_e32 vcc, 16, v80
	v_ashrrev_i32_e32 v131, 31, v130
	s_nop 0
	v_cndmask_b32_e64 v135, 0, 1.0, vcc
	s_nop 0
	global_load_dword v26, v30, s[2:3]
	s_waitcnt vmcnt(0)
	v_mul_f32_e32 v136, 0x3fb8aa3b, v26
	ds_read_b64 v[26:27], v215
	s_waitcnt lgkmcnt(0)
	v_readfirstlane_b32 s3, v27
	v_readfirstlane_b32 s2, v26
	s_nop 4
	global_load_dword v26, v30, s[2:3] offset:4
	ds_read_b64 v[28:29], v215
	s_waitcnt lgkmcnt(0)
	v_readfirstlane_b32 s3, v29
	v_readfirstlane_b32 s2, v28
	s_nop 4
	global_load_dword v27, v30, s[2:3] offset:8
	s_mov_b32 s2, 0x3fb8aa3b
	s_waitcnt vmcnt(0)
	v_pk_mul_f32 v[132:133], v[26:27], s[2:3] op_sel_hi:[1,0]
	v_readlane_b32 s2, v254, 23
	s_add_u32 s0, s0, s2
	v_lshlrev_b32_e32 v26, 4, v81
	s_addc_u32 s1, s1, 0
	v_and_b32_e32 v34, 0x70, v26
	v_readlane_b32 s2, v253, 23
	v_lshl_add_u64 v[36:37], s[0:1], 0, v[34:35]
	v_add_u32_e32 v34, 0, v34
	v_add_u32_e32 v26, s2, v38
	v_add_u32_e32 v40, s2, v39
	v_readlane_b32 s2, v253, 24
	v_mad_i64_i32 v[46:47], s[0:1], v40, s33, v[36:37]
	s_nop 0
	v_add_u32_e32 v40, s2, v39
	v_mad_i64_i32 v[54:55], s[0:1], v40, s33, v[36:37]
	v_add_u32_e32 v40, s2, v38
	v_mad_i64_i32 v[30:31], s[0:1], v26, s33, v[36:37]
	v_mad_i64_i32 v[36:37], s[0:1], v40, s33, v[36:37]
	global_load_dwordx4 v[26:29], v[30:31], off offset:3136
	s_nop 0
	global_load_dwordx4 v[30:33], v[30:31], off offset:3392
	s_nop 0
	global_load_dwordx4 v[42:45], v[46:47], off offset:3136
	s_nop 0
	global_load_dwordx4 v[46:49], v[46:47], off offset:3392
	s_nop 0
	global_load_dwordx4 v[50:53], v[54:55], off offset:3392
	s_nop 0
	global_load_dwordx4 v[54:57], v[54:55], off offset:3136
	s_nop 0
	global_load_dwordx4 v[58:61], v[36:37], off offset:3392
	global_load_dwordx4 v[62:65], v[36:37], off offset:3136
	v_and_b32_e32 v37, 48, v81
	v_add_u32_e32 v138, 0, v37
	v_lshrrev_b32_e32 v37, 2, v80
	v_bfe_u32 v36, v81, 2, 2
	v_and_b32_e32 v137, 12, v37
	v_or_b32_e32 v139, v36, v137
	v_lshlrev_b32_e32 v36, 3, v80
	v_and_b32_e32 v36, 24, v36
	s_movk_i32 s2, 0x90
	v_add_u32_e32 v140, 0, v36
	v_mad_u64_u32 v[36:37], s[0:1], v38, s2, v[34:35]
	v_mad_u64_u32 v[66:67], s[0:1], v39, s2, v[34:35]
	s_barrier
	v_mov_b32_e32 v34, v35
	v_mov_b32_e32 v37, v35
	s_mov_b32 s0, 0
	s_mov_b32 s1, 0
	s_waitcnt vmcnt(7)
	ds_write_b128 v36, v[26:29]
	s_waitcnt vmcnt(6)
	ds_write_b128 v36, v[30:33] offset:18432
	s_waitcnt vmcnt(5)
	ds_write_b128 v66, v[42:45]
	s_waitcnt vmcnt(4)
	ds_write_b128 v66, v[46:49] offset:18432
	s_waitcnt vmcnt(0)
	ds_write_b128 v36, v[62:65] offset:36864
	ds_write_b128 v36, v[58:61] offset:55296
	ds_write_b128 v66, v[54:57] offset:36864
	ds_write_b128 v66, v[50:53] offset:55296
	v_mov_b32_e32 v36, v35
	v_mov_b64_e32 v[26:27], v[34:35]
	v_mov_b64_e32 v[30:31], v[34:35]
	v_mov_b64_e32 v[48:49], v[36:37]
	v_mov_b64_e32 v[44:45], v[36:37]
	v_mov_b64_e32 v[52:53], v[36:37]
	v_mov_b64_e32 v[56:57], v[36:37]
	v_mov_b64_e32 v[64:65], v[36:37]
	v_mov_b64_e32 v[60:61], v[36:37]
	v_mov_b64_e32 v[68:69], v[36:37]
	v_mov_b64_e32 v[72:73], v[36:37]
	v_mov_b64_e32 v[80:81], v[36:37]
	v_mov_b64_e32 v[76:77], v[36:37]
	v_mov_b64_e32 v[28:29], v[36:37]
	v_mov_b64_e32 v[32:33], v[36:37]
	v_mov_b64_e32 v[46:47], v[34:35]
	v_mov_b64_e32 v[42:43], v[34:35]
	v_mov_b64_e32 v[50:51], v[34:35]
	v_mov_b64_e32 v[54:55], v[34:35]
	v_mov_b64_e32 v[62:63], v[34:35]
	v_mov_b64_e32 v[58:59], v[34:35]
	v_mov_b64_e32 v[66:67], v[34:35]
	v_mov_b64_e32 v[70:71], v[34:35]
	v_mov_b64_e32 v[78:79], v[34:35]
	v_mov_b64_e32 v[74:75], v[34:35]
	v_mov_b32_e32 v37, v135
	v_mov_b32_e32 v36, v135
	s_waitcnt lgkmcnt(0)
	s_barrier
	s_branch .LBB0_470

; __device__ __forceinline__ float xor16_32_sum(float v) { float a = v, b = v; swap16(a, b); v = a + b; a = v; b = v; swap32(a, b); return a + b; }
;     __device__ __forceinline__ unsigned char* ws() const { return (unsigned char*)(__attribute__((address_space(1))) unsigned char*)ld(23); }
; __device__ __forceinline__ unsigned cvtpk(float lo, float hi) { unsigned r; asm("v_cvt_pk_bf16_f32 %0, %1, %2" : "=v"(r) : "v"(lo), "v"(hi)); return r; }
; __device__ __forceinline__ void swa_item(const KPD& kp, int l, int item, unsigned char* lds, int tid, int lane, int wave) {
;     ...
;     bf16* MIX = (bf16*)(kp.ws() + WS_MIX);
; #pragma unroll
;     for (int hh = 0; hh < 3; ++hh) { float lt = lrow[hh];
;         lt = pg8::xor16_32_sum(lt);
;         const float inv = 1.0f / lt;
;         bf16* o = MIX + (size_t)(qrow0 + 16 * wave + fr) * D + 384 + (kvh * 3 + hh) * 64 + 4 * fq;
; #pragma unroll
;         for (int dt = 0; dt < 4; ++dt) *(v2u*)(o + 16 * dt) = (v2u){cvtpk(O[hh][dt][0] * inv, O[hh][dt][1] * inv), cvtpk(O[hh][dt][2] * inv, O[hh][dt][3] * inv)}; }
.LBB0_476:
	v_mov_b32_e32 v4, v135
	v_nop
	v_nop
	v_permlane16_swap_b32 v135, v4
	v_lshlrev_b32_e32 v34, 1, v137
	v_add_f32_e32 v4, v135, v4
	v_mov_b32_e32 v5, v4
	v_nop
	v_nop
	v_permlane32_swap_b32 v4, v5
	s_waitcnt lgkmcnt(0)
	v_readlane_b32 s1, v255, 63
	v_readlane_b32 s0, v255, 62
	v_lshlrev_b64 v[2:3], 11, v[130:131]
	v_add_f32_e32 v4, v4, v5
	v_lshl_add_u64 v[2:3], s[0:1], 0, v[2:3]
	v_div_scale_f32 v5, s[0:1], v4, v4, 1.0
	v_rcp_f32_e32 v6, v5
	v_lshl_add_u64 v[2:3], v[2:3], 0, v[34:35]
	v_lshl_add_u64 v[2:3], v[2:3], 0, s[78:79]
	s_mov_b64 s[0:1], 0x10e00300
	v_fma_f32 v7, -v5, v6, 1.0
	v_fmac_f32_e32 v6, v7, v6
	v_div_scale_f32 v7, vcc, 1.0, v4, 1.0
	v_mul_f32_e32 v8, v7, v6
	v_fma_f32 v9, -v5, v8, v7
	v_fmac_f32_e32 v8, v9, v6
	v_fma_f32 v5, -v5, v8, v7
	v_div_fmas_f32 v5, v5, v6, v8
	v_div_fixup_f32 v8, v5, v4, 1.0
	v_lshl_add_u64 v[4:5], v[2:3], 0, s[0:1]
	s_mov_b32 s0, 0x10e00000
	v_mul_f32_e32 v6, v74, v8
	v_mul_f32_e32 v7, v75, v8
	v_add_co_u32_e32 v2, vcc, s0, v2
	v_cvt_pk_bf16_f32 v6, v6, v7
	v_mul_f32_e32 v7, v76, v8
	s_nop 0
	v_addc_co_u32_e32 v3, vcc, 0, v3, vcc
	v_mul_f32_e32 v9, v77, v8
	v_cvt_pk_bf16_f32 v7, v7, v9
	global_store_dwordx2 v[2:3], v[6:7], off offset:768
	v_mul_f32_e32 v2, v78, v8
	v_mul_f32_e32 v3, v79, v8
	v_cvt_pk_bf16_f32 v2, v2, v3
	v_mul_f32_e32 v3, v80, v8
	v_mul_f32_e32 v6, v81, v8
	v_cvt_pk_bf16_f32 v3, v3, v6
	global_store_dwordx2 v[4:5], v[2:3], off offset:32
	v_mul_f32_e32 v2, v70, v8
	v_mul_f32_e32 v3, v71, v8
	v_cvt_pk_bf16_f32 v2, v2, v3
	v_mul_f32_e32 v3, v72, v8
	v_mul_f32_e32 v6, v73, v8
	v_cvt_pk_bf16_f32 v3, v3, v6
	global_store_dwordx2 v[4:5], v[2:3], off offset:64
	v_mul_f32_e32 v2, v66, v8
	v_mul_f32_e32 v3, v67, v8
	v_cvt_pk_bf16_f32 v2, v2, v3
	v_mul_f32_e32 v3, v68, v8
	v_mul_f32_e32 v6, v69, v8
	v_cvt_pk_bf16_f32 v3, v3, v6
	global_store_dwordx2 v[4:5], v[2:3], off offset:96
	v_mov_b32_e32 v2, v37
	v_nop
	v_nop
	v_permlane16_swap_b32 v37, v2
	s_nop 0
	v_add_f32_e32 v2, v37, v2
	v_mov_b32_e32 v3, v2
	v_nop
	v_nop
	v_permlane32_swap_b32 v2, v3
	s_nop 0
	v_add_f32_e32 v2, v2, v3
	v_div_scale_f32 v3, s[0:1], v2, v2, 1.0
	v_rcp_f32_e32 v6, v3
	s_nop 0
	v_fma_f32 v7, -v3, v6, 1.0
	v_fmac_f32_e32 v6, v7, v6
	v_div_scale_f32 v7, vcc, 1.0, v2, 1.0
	v_mul_f32_e32 v8, v7, v6
	v_fma_f32 v9, -v3, v8, v7
	v_fmac_f32_e32 v8, v9, v6
	v_fma_f32 v3, -v3, v8, v7
	v_div_fmas_f32 v3, v3, v6, v8
	v_div_fixup_f32 v6, v3, v2, 1.0
	v_mul_f32_e32 v2, v58, v6
	v_mul_f32_e32 v3, v59, v6
	v_cvt_pk_bf16_f32 v2, v2, v3
	v_mul_f32_e32 v3, v60, v6
	v_mul_f32_e32 v7, v61, v6
	v_cvt_pk_bf16_f32 v3, v3, v7
	global_store_dwordx2 v[4:5], v[2:3], off offset:128
	v_mul_f32_e32 v2, v62, v6
	v_mul_f32_e32 v3, v63, v6
	v_cvt_pk_bf16_f32 v2, v2, v3
	v_mul_f32_e32 v3, v64, v6
	v_mul_f32_e32 v7, v65, v6
	v_cvt_pk_bf16_f32 v3, v3, v7
	global_store_dwordx2 v[4:5], v[2:3], off offset:160
	v_mul_f32_e32 v2, v54, v6
	v_mul_f32_e32 v3, v55, v6
	v_cvt_pk_bf16_f32 v2, v2, v3
	v_mul_f32_e32 v3, v56, v6
	v_mul_f32_e32 v7, v57, v6
	v_cvt_pk_bf16_f32 v3, v3, v7
	global_store_dwordx2 v[4:5], v[2:3], off offset:192
	v_mul_f32_e32 v2, v50, v6
	v_mul_f32_e32 v3, v51, v6
	v_cvt_pk_bf16_f32 v2, v2, v3
	v_mul_f32_e32 v3, v52, v6
	v_mul_f32_e32 v6, v53, v6
	v_cvt_pk_bf16_f32 v3, v3, v6
	global_store_dwordx2 v[4:5], v[2:3], off offset:224
	v_mov_b32_e32 v2, v36
	v_nop
	v_nop
	v_permlane16_swap_b32 v36, v2
	s_nop 0
	v_add_f32_e32 v2, v36, v2
	v_mov_b32_e32 v3, v2
	v_nop
	v_nop
	v_permlane32_swap_b32 v2, v3
	s_nop 0
	v_add_f32_e32 v2, v2, v3
	v_div_scale_f32 v3, s[0:1], v2, v2, 1.0
	v_rcp_f32_e32 v6, v3
	s_nop 0
	v_fma_f32 v7, -v3, v6, 1.0
	v_fmac_f32_e32 v6, v7, v6
	v_div_scale_f32 v7, vcc, 1.0, v2, 1.0
	v_mul_f32_e32 v8, v7, v6
	v_fma_f32 v9, -v3, v8, v7
	v_fmac_f32_e32 v8, v9, v6
	v_fma_f32 v3, -v3, v8, v7
	v_div_fmas_f32 v3, v3, v6, v8
	v_div_fixup_f32 v6, v3, v2, 1.0
	v_mul_f32_e32 v2, v42, v6
	v_mul_f32_e32 v3, v43, v6
	v_cvt_pk_bf16_f32 v2, v2, v3
	v_mul_f32_e32 v3, v44, v6
	v_mul_f32_e32 v7, v45, v6
	v_cvt_pk_bf16_f32 v3, v3, v7
	global_store_dwordx2 v[4:5], v[2:3], off offset:256
	v_mul_f32_e32 v2, v46, v6
	v_mul_f32_e32 v3, v47, v6
	v_cvt_pk_bf16_f32 v2, v2, v3
	v_mul_f32_e32 v3, v48, v6
	v_mul_f32_e32 v7, v49, v6
	v_cvt_pk_bf16_f32 v3, v3, v7
	global_store_dwordx2 v[4:5], v[2:3], off offset:288
	v_mul_f32_e32 v2, v30, v6
	v_mul_f32_e32 v3, v31, v6
	v_cvt_pk_bf16_f32 v2, v2, v3
	v_mul_f32_e32 v3, v32, v6
	v_mul_f32_e32 v7, v33, v6
	v_cvt_pk_bf16_f32 v3, v3, v7
	global_store_dwordx2 v[4:5], v[2:3], off offset:320
	v_mul_f32_e32 v2, v26, v6
	v_mul_f32_e32 v3, v27, v6
	v_cvt_pk_bf16_f32 v2, v2, v3
	v_mul_f32_e32 v3, v28, v6
	v_mul_f32_e32 v6, v29, v6
	v_cvt_pk_bf16_f32 v3, v3, v6
	global_store_dwordx2 v[4:5], v[2:3], off offset:352
	s_barrier
